# rotate fold + lane merge + sign-splat fold combined
# baseline (speedup 1.0000x reference)
.LBB0_499:
	v_mov_b32_e32 v2, v210
	s_mov_b32 s43, s8
	v_and_b32_e32 v3, 0x1ff, v2
	v_lshlrev_b32_e32 v2, 5, v2
	v_and_or_b32 v2, v2, s94, v3
	v_ashrrev_i32_e32 v4, 5, v2
	v_lshlrev_b32_e32 v2, 3, v2
	v_lshlrev_b32_e32 v4, 3, v4
	v_add3_u32 v18, 0, v2, v4
	ds_read_b64 v[128:129], v18
	ds_read_b64 v[134:135], v18 offset:4224
	ds_read_b64 v[136:137], v18 offset:8448
	ds_read_b64 v[138:139], v18 offset:12672
	ds_read_b64 v[140:141], v18 offset:16896
	ds_read_b64 v[142:143], v18 offset:21120
	ds_read_b64 v[132:133], v18 offset:25344
	ds_read_b64 v[130:131], v18 offset:29568
	ds_read_b64 v[144:145], v18 offset:33792
	ds_read_b64 v[148:149], v18 offset:38016
	ds_read_b64 v[150:151], v18 offset:42240
	ds_read_b64 v[152:153], v18 offset:46464
	s_waitcnt lgkmcnt(10)
	v_pk_mul_f32 v[162:163], v[134:135], s[10:11]
	s_mov_b32 s74, s11
	v_pk_fma_f32 v[162:163], v[134:135], s[8:9], v[162:163] op_sel:[0,0,1] op_sel_hi:[1,0,0]
	s_waitcnt lgkmcnt(2)
	v_pk_mul_f32 v[178:179], v[148:149], s[42:43]
	v_pk_add_f32 v[194:195], v[134:135], v[148:149]
	v_pk_add_f32 v[134:135], v[134:135], v[148:149] neg_lo:[0,1] neg_hi:[0,1]
	v_pk_mul_f32 v[164:165], v[136:137], s[18:19]
	s_mov_b32 s41, s16
	v_pk_fma_f32 v[178:179], v[148:149], s[74:75], v[178:179] op_sel:[0,0,1] op_sel_hi:[1,0,0] neg_lo:[1,0,0] neg_hi:[1,0,0]
	v_pk_mul_f32 v[148:149], v[134:135], s[18:19]
	v_pk_fma_f32 v[164:165], v[136:137], s[16:17], v[164:165] op_sel:[0,0,1] op_sel_hi:[1,0,0]
	s_mov_b32 s80, s19
	s_waitcnt lgkmcnt(1)
	v_pk_mul_f32 v[180:181], v[150:151], s[40:41]
	v_pk_fma_f32 v[134:135], v[134:135], s[16:17], v[148:149] op_sel:[0,0,1] op_sel_hi:[1,0,0]
	v_pk_add_f32 v[148:149], v[136:137], v[150:151]
	v_pk_add_f32 v[136:137], v[136:137], v[150:151] neg_lo:[0,1] neg_hi:[0,1]
	v_pk_mul_f32 v[166:167], v[138:139], s[26:27]
	s_mov_b32 s78, s37
	s_mov_b32 s39, s24
	v_pk_fma_f32 v[180:181], v[150:151], s[80:81], v[180:181] op_sel:[0,0,1] op_sel_hi:[1,0,0] neg_lo:[1,0,0] neg_hi:[1,0,0]
	v_pk_mul_f32 v[150:151], v[136:137], s[36:37]
	ds_read_b64 v[154:155], v18 offset:50688
	ds_read_b64 v[156:157], v18 offset:54912
	ds_read_b64 v[158:159], v18 offset:59136
	ds_read_b64 v[160:161], v18 offset:63360
	v_pk_fma_f32 v[166:167], v[138:139], s[24:25], v[166:167] op_sel:[0,0,1] op_sel_hi:[1,0,0]
	s_mov_b32 s0, s27
	s_waitcnt lgkmcnt(4)
	v_pk_mul_f32 v[182:183], v[152:153], s[38:39]
	v_pk_fma_f32 v[136:137], v[136:137], s[78:79], v[150:151] op_sel:[0,0,1] op_sel_hi:[1,0,0]
	v_pk_add_f32 v[150:151], v[138:139], v[152:153]
	v_pk_add_f32 v[138:139], v[138:139], v[152:153] neg_lo:[0,1] neg_hi:[0,1]
	v_pk_mul_f32 v[168:169], v[140:141], s[36:37]
	v_pk_fma_f32 v[182:183], v[152:153], s[0:1], v[182:183] op_sel:[0,0,1] op_sel_hi:[1,0,0] neg_lo:[1,0,0] neg_hi:[1,0,0]
	v_pk_mul_f32 v[152:153], v[138:139], s[40:41]
	v_pk_fma_f32 v[168:169], v[140:141], s[78:79], v[168:169] op_sel:[0,0,1] op_sel_hi:[1,0,0]
	v_pk_mul_f32 v[170:171], v[142:143], s[38:39]
	s_waitcnt lgkmcnt(3)
	v_pk_mul_f32 v[184:185], v[154:155], s[36:37]
	v_pk_fma_f32 v[138:139], v[138:139], s[80:81], v[152:153] op_sel:[0,0,1] op_sel_hi:[1,0,0]
	v_pk_add_f32 v[152:153], v[140:141], v[154:155]
	v_pk_add_f32 v[140:141], v[140:141], v[154:155] neg_lo:[0,1] neg_hi:[0,1]
	v_pk_fma_f32 v[170:171], v[142:143], s[0:1], v[170:171] op_sel:[0,0,1] op_sel_hi:[1,0,0]
	v_pk_fma_f32 v[184:185], v[154:155], s[78:79], v[184:185] op_sel:[0,0,1] op_sel_hi:[1,0,0] neg_lo:[1,0,0] neg_hi:[1,0,0]
	s_waitcnt lgkmcnt(2)
	v_pk_mul_f32 v[186:187], v[156:157], s[26:27]
	v_xor_b32_e32 v155, 0x80000000, v140
	v_mov_b32_e32 v154, v141
	v_pk_add_f32 v[140:141], v[142:143], v[156:157]
	v_pk_add_f32 v[142:143], v[142:143], v[156:157] neg_lo:[0,1] neg_hi:[0,1]
	v_pk_mul_f32 v[172:173], v[132:133], s[40:41]
	v_pk_fma_f32 v[186:187], v[156:157], s[24:25], v[186:187] op_sel:[0,0,1] op_sel_hi:[1,0,0] neg_lo:[1,0,0] neg_hi:[1,0,0]
	v_pk_mul_f32 v[156:157], v[142:143], s[40:41]
	v_pk_fma_f32 v[172:173], v[132:133], s[80:81], v[172:173] op_sel:[0,0,1] op_sel_hi:[1,0,0]
	s_waitcnt lgkmcnt(1)
	v_pk_mul_f32 v[188:189], v[158:159], s[18:19]
	v_pk_fma_f32 v[142:143], v[142:143], s[80:81], v[156:157] op_sel:[0,0,1] op_sel_hi:[1,0,0] neg_lo:[1,0,0] neg_hi:[1,0,0]
	v_pk_add_f32 v[156:157], v[132:133], v[158:159]
	v_pk_add_f32 v[132:133], v[132:133], v[158:159] neg_lo:[0,1] neg_hi:[0,1]
	v_pk_mul_f32 v[174:175], v[130:131], s[42:43]
	v_pk_fma_f32 v[188:189], v[158:159], s[16:17], v[188:189] op_sel:[0,0,1] op_sel_hi:[1,0,0] neg_lo:[1,0,0] neg_hi:[1,0,0]
	v_pk_mul_f32 v[158:159], v[132:133], s[36:37]
	v_pk_fma_f32 v[174:175], v[130:131], s[74:75], v[174:175] op_sel:[0,0,1] op_sel_hi:[1,0,0]
	s_waitcnt lgkmcnt(0)
	v_pk_mul_f32 v[190:191], v[160:161], s[10:11]
	v_pk_fma_f32 v[132:133], v[132:133], s[78:79], v[158:159] op_sel:[0,0,1] op_sel_hi:[1,0,0] neg_lo:[1,0,0] neg_hi:[1,0,0]
	v_pk_add_f32 v[158:159], v[130:131], v[160:161]
	v_pk_add_f32 v[130:131], v[130:131], v[160:161] neg_lo:[0,1] neg_hi:[0,1]
	v_xor_b32_e32 v177, 0x80000000, v144
	v_mov_b32_e32 v176, v145
	v_pk_fma_f32 v[190:191], v[160:161], s[8:9], v[190:191] op_sel:[0,0,1] op_sel_hi:[1,0,0] neg_lo:[1,0,0] neg_hi:[1,0,0]
	v_pk_mul_f32 v[160:161], v[130:131], s[18:19]
	v_pk_add_f32 v[192:193], v[128:129], v[144:145]
	v_pk_add_f32 v[144:145], v[128:129], v[144:145] neg_lo:[0,1] neg_hi:[0,1]
	v_pk_fma_f32 v[130:131], v[130:131], s[16:17], v[160:161] op_sel:[0,0,1] op_sel_hi:[1,0,0] neg_lo:[1,0,0] neg_hi:[1,0,0]
	v_pk_add_f32 v[160:161], v[128:129], v[176:177]
	v_pk_add_f32 v[128:129], v[128:129], v[176:177] neg_lo:[0,1] neg_hi:[0,1]
	v_pk_add_f32 v[176:177], v[162:163], v[178:179]
	v_pk_add_f32 v[162:163], v[162:163], v[178:179] neg_lo:[0,1] neg_hi:[0,1]
	v_cvt_f32_u32_e32 v2, v3
	v_pk_mul_f32 v[178:179], v[162:163], s[18:19]
	s_add_i32 s76, s72, s48
	v_pk_fma_f32 v[162:163], v[162:163], s[16:17], v[178:179] op_sel:[0,0,1] op_sel_hi:[1,0,0]
	v_pk_add_f32 v[178:179], v[164:165], v[180:181]
	v_pk_add_f32 v[164:165], v[164:165], v[180:181] neg_lo:[0,1] neg_hi:[0,1]
	v_mul_f32_e32 v2, 0x38800000, v2
	v_pk_mul_f32 v[180:181], v[164:165], s[36:37]
	v_sin_f32_e32 v34, v2
	v_pk_fma_f32 v[164:165], v[164:165], s[78:79], v[180:181] op_sel:[0,0,1] op_sel_hi:[1,0,0]
	v_pk_add_f32 v[180:181], v[166:167], v[182:183]
	v_pk_add_f32 v[166:167], v[166:167], v[182:183] neg_lo:[0,1] neg_hi:[0,1]
	v_cos_f32_e32 v30, v2
	v_pk_mul_f32 v[182:183], v[166:167], s[40:41]
	v_xor_b32_e32 v31, 0x80000000, v34
	v_pk_fma_f32 v[166:167], v[166:167], s[80:81], v[182:183] op_sel:[0,0,1] op_sel_hi:[1,0,0]
	v_pk_add_f32 v[182:183], v[168:169], v[184:185]
	v_pk_add_f32 v[184:185], v[168:169], v[184:185] neg_lo:[0,1] neg_hi:[0,1]
	v_mov_b32_e32 v35, v31
	v_pk_add_f32 v[168:169], v[170:171], v[186:187]
	v_pk_add_f32 v[170:171], v[170:171], v[186:187] neg_lo:[0,1] neg_hi:[0,1]
	v_pk_mul_f32 v[2:3], v[30:31], v[34:35] op_sel:[1,0] op_sel_hi:[0,1]
	v_pk_mul_f32 v[186:187], v[170:171], s[40:41]
	v_pk_fma_f32 v[44:45], v[30:31], v[30:31], v[2:3] op_sel_hi:[1,0,1]
	v_pk_fma_f32 v[170:171], v[170:171], s[80:81], v[186:187] op_sel:[0,0,1] op_sel_hi:[1,0,0] neg_lo:[1,0,0] neg_hi:[1,0,0]
	v_pk_add_f32 v[186:187], v[172:173], v[188:189]
	v_pk_add_f32 v[172:173], v[172:173], v[188:189] neg_lo:[0,1] neg_hi:[0,1]
	v_pk_mul_f32 v[2:3], v[34:35], v[44:45] op_sel:[0,1] op_sel_hi:[1,0]
	v_pk_mul_f32 v[188:189], v[172:173], s[36:37]
	v_pk_fma_f32 v[172:173], v[172:173], s[78:79], v[188:189] op_sel:[0,0,1] op_sel_hi:[1,0,0] neg_lo:[1,0,0] neg_hi:[1,0,0]
	v_pk_add_f32 v[188:189], v[174:175], v[190:191]
	v_pk_add_f32 v[174:175], v[174:175], v[190:191] neg_lo:[0,1] neg_hi:[0,1]
	v_pk_mul_f32 v[190:191], v[174:175], s[18:19]
	v_pk_fma_f32 v[46:47], v[30:31], v[44:45], v[2:3] op_sel_hi:[0,1,1]
	v_pk_fma_f32 v[174:175], v[174:175], s[16:17], v[190:191] op_sel:[0,0,1] op_sel_hi:[1,0,0] neg_lo:[1,0,0] neg_hi:[1,0,0]
	v_pk_add_f32 v[190:191], v[192:193], v[152:153]
	v_pk_add_f32 v[152:153], v[192:193], v[152:153] neg_lo:[0,1] neg_hi:[0,1]
	v_pk_add_f32 v[192:193], v[194:195], v[140:141]
	v_pk_add_f32 v[140:141], v[194:195], v[140:141] neg_lo:[0,1] neg_hi:[0,1]
	v_pk_mul_f32 v[2:3], v[44:45], v[44:45] op_sel:[1,1] op_sel_hi:[0,1] neg_lo:[0,1]
	v_pk_mul_f32 v[194:195], v[140:141], s[36:37]
	v_pk_fma_f32 v[52:53], v[44:45], v[44:45], v[2:3] op_sel_hi:[1,0,1]
	v_pk_fma_f32 v[140:141], v[140:141], s[78:79], v[194:195] op_sel:[0,0,1] op_sel_hi:[1,0,0]
	v_pk_add_f32 v[194:195], v[148:149], v[156:157]
	v_pk_add_f32 v[156:157], v[148:149], v[156:157] neg_lo:[0,1] neg_hi:[0,1]
	v_pk_add_f32 v[148:149], v[150:151], v[158:159]
	v_pk_add_f32 v[150:151], v[150:151], v[158:159] neg_lo:[0,1] neg_hi:[0,1]
	v_pk_mul_f32 v[158:159], v[150:151], s[36:37]
	v_pk_mul_f32 v[2:3], v[52:53], v[52:53] op_sel:[1,1] op_sel_hi:[0,1] neg_lo:[0,1]
	v_pk_fma_f32 v[150:151], v[150:151], s[78:79], v[158:159] op_sel:[0,0,1] op_sel_hi:[1,0,0] neg_lo:[1,0,0] neg_hi:[1,0,0]
	v_pk_add_f32 v[158:159], v[144:145], v[154:155]
	v_pk_add_f32 v[144:145], v[144:145], v[154:155] neg_lo:[0,1] neg_hi:[0,1]
	v_pk_add_f32 v[154:155], v[134:135], v[142:143]
	v_pk_add_f32 v[134:135], v[134:135], v[142:143] neg_lo:[0,1] neg_hi:[0,1]
	v_pk_fma_f32 v[48:49], v[52:53], v[52:53], v[2:3] op_sel_hi:[1,0,1]
	v_pk_mul_f32 v[142:143], v[134:135], s[36:37]
	v_pk_mul_f32 v[2:3], v[52:53], v[48:49] op_sel:[1,1] op_sel_hi:[1,0] neg_lo:[1,0]
	v_pk_fma_f32 v[134:135], v[134:135], s[78:79], v[142:143] op_sel:[0,0,1] op_sel_hi:[1,0,0]
	v_pk_add_f32 v[142:143], v[136:137], v[132:133]
	v_pk_add_f32 v[136:137], v[136:137], v[132:133] neg_lo:[0,1] neg_hi:[0,1]
	v_pk_fma_f32 v[36:37], v[52:53], v[48:49], v[2:3] op_sel_hi:[0,1,1]
	v_pk_add_f32 v[132:133], v[138:139], v[130:131]
	v_pk_add_f32 v[130:131], v[138:139], v[130:131] neg_lo:[0,1] neg_hi:[0,1]
	v_pk_mul_f32 v[2:3], v[52:53], v[36:37] op_sel:[1,1] op_sel_hi:[1,0] neg_lo:[1,0]
	v_pk_mul_f32 v[138:139], v[130:131], s[36:37]
	v_pk_fma_f32 v[26:27], v[52:53], v[36:37], v[2:3] op_sel_hi:[0,1,1]
	v_pk_fma_f32 v[130:131], v[130:131], s[78:79], v[138:139] op_sel:[0,0,1] op_sel_hi:[1,0,0] neg_lo:[1,0,0] neg_hi:[1,0,0]
	v_pk_add_f32 v[138:139], v[160:161], v[182:183]
	v_pk_add_f32 v[160:161], v[160:161], v[182:183] neg_lo:[0,1] neg_hi:[0,1]
	v_pk_add_f32 v[182:183], v[176:177], v[168:169]
	v_pk_add_f32 v[168:169], v[176:177], v[168:169] neg_lo:[0,1] neg_hi:[0,1]
	v_pk_mul_f32 v[2:3], v[52:53], v[26:27] op_sel:[1,1] op_sel_hi:[1,0] neg_lo:[1,0]
	v_pk_mul_f32 v[176:177], v[168:169], s[36:37]
	v_pk_fma_f32 v[20:21], v[52:53], v[26:27], v[2:3] op_sel_hi:[0,1,1]
	v_pk_fma_f32 v[168:169], v[168:169], s[78:79], v[176:177] op_sel:[0,0,1] op_sel_hi:[1,0,0]
	v_pk_add_f32 v[176:177], v[178:179], v[186:187]
	v_pk_add_f32 v[186:187], v[178:179], v[186:187] neg_lo:[0,1] neg_hi:[0,1]
	v_pk_mul_f32 v[2:3], v[52:53], v[20:21] op_sel:[1,1] op_sel_hi:[1,0] neg_lo:[1,0]
	v_pk_add_f32 v[178:179], v[180:181], v[188:189]
	v_pk_add_f32 v[180:181], v[180:181], v[188:189] neg_lo:[0,1] neg_hi:[0,1]
	v_pk_fma_f32 v[10:11], v[52:53], v[20:21], v[2:3] op_sel_hi:[0,1,1]
	v_pk_mul_f32 v[188:189], v[180:181], s[36:37]
	v_pk_mul_f32 v[2:3], v[52:53], v[10:11] op_sel:[1,1] op_sel_hi:[1,0] neg_lo:[1,0]
	v_pk_fma_f32 v[180:181], v[180:181], s[78:79], v[188:189] op_sel:[0,0,1] op_sel_hi:[1,0,0] neg_lo:[1,0,0] neg_hi:[1,0,0]
	v_pk_add_f32 v[188:189], v[128:129], v[184:185] op_sel:[0,1] op_sel_hi:[1,0] neg_hi:[0,1]
	v_pk_add_f32 v[128:129], v[128:129], v[184:185] op_sel:[0,1] op_sel_hi:[1,0] neg_lo:[0,1]
	v_pk_add_f32 v[184:185], v[162:163], v[170:171]
	v_pk_add_f32 v[162:163], v[162:163], v[170:171] neg_lo:[0,1] neg_hi:[0,1]
	v_pk_fma_f32 v[4:5], v[52:53], v[10:11], v[2:3] op_sel_hi:[0,1,1]
	v_pk_mul_f32 v[170:171], v[162:163], s[36:37]
	v_pk_mul_f32 v[8:9], v[44:45], v[4:5] op_sel:[1,1] op_sel_hi:[1,0] neg_lo:[1,0]
	v_pk_fma_f32 v[162:163], v[162:163], s[78:79], v[170:171] op_sel:[0,0,1] op_sel_hi:[1,0,0]
	v_pk_add_f32 v[170:171], v[164:165], v[172:173]
	v_pk_add_f32 v[172:173], v[164:165], v[172:173] neg_lo:[0,1] neg_hi:[0,1]
	v_pk_mul_f32 v[14:15], v[34:35], v[4:5] op_sel:[0,1] op_sel_hi:[1,0]
	v_pk_add_f32 v[164:165], v[166:167], v[174:175]
	v_pk_add_f32 v[166:167], v[166:167], v[174:175] neg_lo:[0,1] neg_hi:[0,1]
	v_pk_mul_f32 v[32:33], v[44:45], v[10:11] op_sel:[1,1] op_sel_hi:[1,0] neg_lo:[1,0]
	v_pk_mul_f32 v[174:175], v[166:167], s[36:37]
	v_pk_mul_f32 v[40:41], v[34:35], v[10:11] op_sel:[0,1] op_sel_hi:[1,0]
	v_pk_fma_f32 v[166:167], v[166:167], s[78:79], v[174:175] op_sel:[0,0,1] op_sel_hi:[1,0,0] neg_lo:[1,0,0] neg_hi:[1,0,0]
	v_pk_add_f32 v[174:175], v[190:191], v[194:195]
	v_pk_add_f32 v[190:191], v[190:191], v[194:195] neg_lo:[0,1] neg_hi:[0,1]
	v_pk_add_f32 v[194:195], v[192:193], v[148:149]
	v_pk_add_f32 v[192:193], v[192:193], v[148:149] neg_lo:[0,1] neg_hi:[0,1]
	v_pk_mul_f32 v[62:63], v[44:45], v[20:21] op_sel:[1,1] op_sel_hi:[1,0] neg_lo:[1,0]
	v_pk_add_f32 v[148:149], v[152:153], v[156:157] op_sel:[0,1] op_sel_hi:[1,0] neg_hi:[0,1]
	v_pk_add_f32 v[152:153], v[152:153], v[156:157] op_sel:[0,1] op_sel_hi:[1,0] neg_lo:[0,1]
	v_pk_add_f32 v[156:157], v[140:141], v[150:151]
	v_pk_add_f32 v[150:151], v[140:141], v[150:151] neg_lo:[0,1] neg_hi:[0,1]
	v_pk_mul_f32 v[66:67], v[34:35], v[20:21] op_sel:[0,1] op_sel_hi:[1,0]
	v_pk_add_f32 v[140:141], v[158:159], v[142:143]
	v_pk_add_f32 v[142:143], v[158:159], v[142:143] neg_lo:[0,1] neg_hi:[0,1]
	v_pk_add_f32 v[158:159], v[154:155], v[132:133]
	v_pk_add_f32 v[154:155], v[154:155], v[132:133] neg_lo:[0,1] neg_hi:[0,1]
	v_pk_mul_f32 v[78:79], v[44:45], v[26:27] op_sel:[1,1] op_sel_hi:[1,0] neg_lo:[1,0]
	v_pk_add_f32 v[132:133], v[144:145], v[136:137] op_sel:[0,1] op_sel_hi:[1,0] neg_hi:[0,1]
	v_pk_add_f32 v[136:137], v[144:145], v[136:137] op_sel:[0,1] op_sel_hi:[1,0] neg_lo:[0,1]
	v_pk_add_f32 v[144:145], v[134:135], v[130:131]
	v_pk_add_f32 v[134:135], v[134:135], v[130:131] neg_lo:[0,1] neg_hi:[0,1]
	v_pk_mul_f32 v[82:83], v[34:35], v[26:27] op_sel:[0,1] op_sel_hi:[1,0]
	v_pk_add_f32 v[130:131], v[138:139], v[176:177]
	v_pk_add_f32 v[138:139], v[138:139], v[176:177] neg_lo:[0,1] neg_hi:[0,1]
	v_pk_add_f32 v[176:177], v[182:183], v[178:179]
	v_pk_add_f32 v[182:183], v[182:183], v[178:179] neg_lo:[0,1] neg_hi:[0,1]
	v_pk_mul_f32 v[92:93], v[44:45], v[36:37] op_sel:[1,1] op_sel_hi:[1,0] neg_lo:[1,0]
	v_pk_add_f32 v[178:179], v[160:161], v[186:187] op_sel:[0,1] op_sel_hi:[1,0] neg_hi:[0,1]
	v_pk_add_f32 v[160:161], v[160:161], v[186:187] op_sel:[0,1] op_sel_hi:[1,0] neg_lo:[0,1]
	v_pk_add_f32 v[186:187], v[168:169], v[180:181]
	v_pk_add_f32 v[180:181], v[168:169], v[180:181] neg_lo:[0,1] neg_hi:[0,1]
	v_pk_mul_f32 v[96:97], v[34:35], v[36:37] op_sel:[0,1] op_sel_hi:[1,0]
	v_pk_add_f32 v[168:169], v[188:189], v[170:171]
	v_pk_add_f32 v[170:171], v[188:189], v[170:171] neg_lo:[0,1] neg_hi:[0,1]
	v_pk_add_f32 v[188:189], v[184:185], v[164:165]
	v_pk_add_f32 v[184:185], v[184:185], v[164:165] neg_lo:[0,1] neg_hi:[0,1]
	v_pk_mul_f32 v[106:107], v[44:45], v[48:49] op_sel:[1,1] op_sel_hi:[1,0] neg_lo:[1,0]
	v_pk_add_f32 v[164:165], v[128:129], v[172:173] op_sel:[0,1] op_sel_hi:[1,0] neg_hi:[0,1]
	v_pk_add_f32 v[128:129], v[128:129], v[172:173] op_sel:[0,1] op_sel_hi:[1,0] neg_lo:[0,1]
	v_pk_add_f32 v[172:173], v[162:163], v[166:167]
	v_pk_add_f32 v[166:167], v[162:163], v[166:167] neg_lo:[0,1] neg_hi:[0,1]
	v_pk_mul_f32 v[110:111], v[34:35], v[48:49] op_sel:[0,1] op_sel_hi:[1,0]
	v_pk_add_f32 v[162:163], v[174:175], v[194:195]
	v_pk_add_f32 v[174:175], v[174:175], v[194:195] neg_lo:[0,1] neg_hi:[0,1]
	v_pk_add_f32 v[194:195], v[190:191], v[192:193] op_sel:[0,1] op_sel_hi:[1,0] neg_hi:[0,1]
	v_pk_add_f32 v[190:191], v[190:191], v[192:193] op_sel:[0,1] op_sel_hi:[1,0] neg_lo:[0,1]
	v_pk_add_f32 v[192:193], v[148:149], v[156:157]
	v_pk_add_f32 v[148:149], v[148:149], v[156:157] neg_lo:[0,1] neg_hi:[0,1]
	v_pk_add_f32 v[156:157], v[152:153], v[150:151] op_sel:[0,1] op_sel_hi:[1,0] neg_hi:[0,1]
	v_pk_add_f32 v[150:151], v[152:153], v[150:151] op_sel:[0,1] op_sel_hi:[1,0] neg_lo:[0,1]
	v_pk_add_f32 v[152:153], v[140:141], v[158:159]
	v_pk_add_f32 v[140:141], v[140:141], v[158:159] neg_lo:[0,1] neg_hi:[0,1]
	v_pk_add_f32 v[158:159], v[142:143], v[154:155] op_sel:[0,1] op_sel_hi:[1,0] neg_hi:[0,1]
	v_pk_add_f32 v[142:143], v[142:143], v[154:155] op_sel:[0,1] op_sel_hi:[1,0] neg_lo:[0,1]
	v_pk_add_f32 v[154:155], v[132:133], v[144:145]
	v_pk_add_f32 v[132:133], v[132:133], v[144:145] neg_lo:[0,1] neg_hi:[0,1]
	v_pk_add_f32 v[144:145], v[136:137], v[134:135] op_sel:[0,1] op_sel_hi:[1,0] neg_hi:[0,1]
	v_pk_add_f32 v[134:135], v[136:137], v[134:135] op_sel:[0,1] op_sel_hi:[1,0] neg_lo:[0,1]
	v_pk_add_f32 v[136:137], v[130:131], v[176:177]
	v_pk_mul_f32 v[120:121], v[44:45], v[52:53] op_sel:[1,1] op_sel_hi:[1,0] neg_lo:[1,0]
	v_pk_mul_f32 v[124:125], v[34:35], v[52:53] op_sel:[0,1] op_sel_hi:[1,0]
	v_pk_mul_f32 v[34:35], v[34:35], v[136:137] op_sel:[0,1] op_sel_hi:[1,0]
	v_pk_fma_f32 v[8:9], v[44:45], v[4:5], v[8:9] op_sel_hi:[0,1,1]
	v_pk_fma_f32 v[14:15], v[30:31], v[4:5], v[14:15] op_sel_hi:[0,1,1]
	v_xor_b32_e32 v22, 0x80000000, v5
	v_pk_fma_f32 v[32:33], v[44:45], v[10:11], v[32:33] op_sel_hi:[0,1,1]
	v_pk_fma_f32 v[40:41], v[30:31], v[10:11], v[40:41] op_sel_hi:[0,1,1]
	v_pk_fma_f32 v[62:63], v[44:45], v[20:21], v[62:63] op_sel_hi:[0,1,1]
	v_pk_fma_f32 v[66:67], v[30:31], v[20:21], v[66:67] op_sel_hi:[0,1,1]
	v_pk_fma_f32 v[78:79], v[44:45], v[26:27], v[78:79] op_sel_hi:[0,1,1]
	v_pk_fma_f32 v[82:83], v[30:31], v[26:27], v[82:83] op_sel_hi:[0,1,1]
	v_pk_fma_f32 v[92:93], v[44:45], v[36:37], v[92:93] op_sel_hi:[0,1,1]
	v_pk_fma_f32 v[96:97], v[30:31], v[36:37], v[96:97] op_sel_hi:[0,1,1]
	v_pk_fma_f32 v[106:107], v[44:45], v[48:49], v[106:107] op_sel_hi:[0,1,1]
	v_pk_fma_f32 v[110:111], v[30:31], v[48:49], v[110:111] op_sel_hi:[0,1,1]
	v_pk_fma_f32 v[120:121], v[44:45], v[52:53], v[120:121] op_sel_hi:[0,1,1]
	v_pk_fma_f32 v[124:125], v[30:31], v[52:53], v[124:125] op_sel_hi:[0,1,1]
	v_mov_b32_e32 v23, v5
	v_pk_add_f32 v[130:131], v[130:131], v[176:177] neg_lo:[0,1] neg_hi:[0,1]
	v_pk_add_f32 v[176:177], v[138:139], v[182:183] op_sel:[0,1] op_sel_hi:[1,0] neg_hi:[0,1]
	v_pk_add_f32 v[138:139], v[138:139], v[182:183] op_sel:[0,1] op_sel_hi:[1,0] neg_lo:[0,1]
	v_pk_add_f32 v[182:183], v[178:179], v[186:187]
	v_pk_add_f32 v[178:179], v[178:179], v[186:187] neg_lo:[0,1] neg_hi:[0,1]
	v_pk_add_f32 v[186:187], v[160:161], v[180:181] op_sel:[0,1] op_sel_hi:[1,0] neg_hi:[0,1]
	v_pk_add_f32 v[160:161], v[160:161], v[180:181] op_sel:[0,1] op_sel_hi:[1,0] neg_lo:[0,1]
	v_pk_add_f32 v[180:181], v[168:169], v[188:189]
	v_pk_fma_f32 v[30:31], v[30:31], v[136:137], v[34:35] op_sel_hi:[0,1,1]
	v_pk_mul_f32 v[34:35], v[44:45], v[152:153] op_sel:[1,1] op_sel_hi:[1,0] neg_lo:[1,0]
	v_pk_mul_f32 v[2:3], v[46:47], v[4:5] op_sel:[1,1] op_sel_hi:[1,0] neg_lo:[1,0]
	v_xor_b32_e32 v12, 0x80000000, v9
	v_pk_mul_f32 v[24:25], v[46:47], v[10:11] op_sel:[1,1] op_sel_hi:[1,0] neg_lo:[1,0]
	v_xor_b32_e32 v38, 0x80000000, v33
	v_xor_b32_e32 v50, 0x80000000, v11
	v_pk_mul_f32 v[56:57], v[46:47], v[20:21] op_sel:[1,1] op_sel_hi:[1,0] neg_lo:[1,0]
	v_xor_b32_e32 v64, 0x80000000, v63
	v_xor_b32_e32 v70, 0x80000000, v21
	v_pk_mul_f32 v[74:75], v[46:47], v[26:27] op_sel:[1,1] op_sel_hi:[1,0] neg_lo:[1,0]
	v_xor_b32_e32 v80, 0x80000000, v79
	v_xor_b32_e32 v86, 0x80000000, v27
	v_pk_mul_f32 v[88:89], v[46:47], v[36:37] op_sel:[1,1] op_sel_hi:[1,0] neg_lo:[1,0]
	v_xor_b32_e32 v94, 0x80000000, v93
	v_xor_b32_e32 v100, 0x80000000, v37
	v_pk_mul_f32 v[102:103], v[46:47], v[48:49] op_sel:[1,1] op_sel_hi:[1,0] neg_lo:[1,0]
	v_pk_mul_f32 v[116:117], v[52:53], v[46:47] op_sel:[1,1] op_sel_hi:[0,1] neg_lo:[0,1]
	v_mov_b32_e32 v101, v37
	v_mov_b32_e32 v95, v93
	v_mov_b32_e32 v87, v27
	v_mov_b32_e32 v81, v79
	v_mov_b32_e32 v71, v21
	v_mov_b32_e32 v65, v63
	v_mov_b32_e32 v51, v11
	v_mov_b32_e32 v39, v33
	v_mov_b32_e32 v13, v9
	v_pk_fma_f32 v[34:35], v[44:45], v[152:153], v[34:35] op_sel_hi:[0,1,1]
	v_pk_mul_f32 v[44:45], v[46:47], v[180:181] op_sel:[1,1] op_sel_hi:[1,0] neg_lo:[1,0]
	v_pk_mul_f32 v[22:23], v[150:151], v[22:23] op_sel:[1,0] op_sel_hi:[0,1]
	v_pk_fma_f32 v[2:3], v[46:47], v[4:5], v[2:3] op_sel_hi:[0,1,1]
	v_pk_fma_f32 v[24:25], v[46:47], v[10:11], v[24:25] op_sel_hi:[0,1,1]
	v_pk_fma_f32 v[56:57], v[46:47], v[20:21], v[56:57] op_sel_hi:[0,1,1]
	v_pk_fma_f32 v[74:75], v[46:47], v[26:27], v[74:75] op_sel_hi:[0,1,1]
	v_pk_fma_f32 v[88:89], v[46:47], v[36:37], v[88:89] op_sel_hi:[0,1,1]
	v_pk_fma_f32 v[102:103], v[46:47], v[48:49], v[102:103] op_sel_hi:[0,1,1]
	v_pk_fma_f32 v[116:117], v[52:53], v[46:47], v[116:117] op_sel_hi:[1,0,1]
	v_pk_fma_f32 v[44:45], v[46:47], v[180:181], v[44:45] op_sel_hi:[0,1,1]
	v_pk_mul_f32 v[46:47], v[52:53], v[192:193] op_sel:[1,1] op_sel_hi:[1,0] neg_lo:[1,0]
	v_pk_mul_f32 v[54:55], v[120:121], v[154:155] op_sel:[1,1] op_sel_hi:[1,0] neg_lo:[1,0]
	v_pk_mul_f32 v[72:73], v[48:49], v[194:195] op_sel:[1,1] op_sel_hi:[1,0] neg_lo:[1,0]
	v_pk_mul_f32 v[108:109], v[106:107], v[158:159] op_sel:[1,1] op_sel_hi:[1,0] neg_lo:[1,0]
	v_pk_mul_f32 v[100:101], v[100:101], v[156:157] op_sel:[0,1] op_sel_hi:[1,0]
	v_pk_mul_f32 v[94:95], v[94:95], v[144:145] op_sel:[0,1] op_sel_hi:[1,0]
	v_pk_mul_f32 v[86:87], v[174:175], v[86:87] op_sel:[1,0] op_sel_hi:[0,1]
	v_pk_mul_f32 v[80:81], v[140:141], v[80:81] op_sel:[1,0] op_sel_hi:[0,1]
	v_pk_mul_f32 v[70:71], v[148:149], v[70:71] op_sel:[1,0] op_sel_hi:[0,1]
	v_pk_mul_f32 v[64:65], v[132:133], v[64:65] op_sel:[1,0] op_sel_hi:[0,1]
	v_pk_mul_f32 v[50:51], v[190:191], v[50:51] op_sel:[1,0] op_sel_hi:[0,1]
	v_pk_mul_f32 v[38:39], v[142:143], v[38:39] op_sel:[1,0] op_sel_hi:[0,1]
	v_pk_fma_f32 v[4:5], v[150:151], v[4:5], v[22:23] op_sel_hi:[1,0,1]
	v_pk_mul_f32 v[12:13], v[134:135], v[12:13] op_sel:[1,0] op_sel_hi:[0,1]
	v_pk_fma_f32 v[46:47], v[52:53], v[192:193], v[46:47] op_sel_hi:[0,1,1]
	v_pk_fma_f32 v[54:55], v[120:121], v[154:155], v[54:55] op_sel_hi:[0,1,1]
	v_pk_fma_f32 v[48:49], v[48:49], v[194:195], v[72:73] op_sel_hi:[0,1,1]
	v_pk_fma_f32 v[106:107], v[106:107], v[158:159], v[108:109] op_sel_hi:[0,1,1]
	v_pk_fma_f32 v[36:37], v[36:37], v[156:157], v[100:101] op_sel_hi:[0,1,1]
	v_pk_fma_f32 v[92:93], v[92:93], v[144:145], v[94:95] op_sel_hi:[0,1,1]
	v_pk_fma_f32 v[26:27], v[174:175], v[26:27], v[86:87] op_sel_hi:[1,0,1]
	v_pk_mul_f32 v[84:85], v[130:131], v[82:83] op_sel:[1,1] op_sel_hi:[0,1] neg_lo:[0,1]
	v_pk_fma_f32 v[78:79], v[140:141], v[78:79], v[80:81] op_sel_hi:[1,0,1]
	v_pk_fma_f32 v[20:21], v[148:149], v[20:21], v[70:71] op_sel_hi:[1,0,1]
	v_pk_fma_f32 v[62:63], v[132:133], v[62:63], v[64:65] op_sel_hi:[1,0,1]
	v_pk_fma_f32 v[10:11], v[190:191], v[10:11], v[50:51] op_sel_hi:[1,0,1]
	v_pk_fma_f32 v[32:33], v[142:143], v[32:33], v[38:39] op_sel_hi:[1,0,1]
	v_pk_fma_f32 v[8:9], v[134:135], v[8:9], v[12:13] op_sel_hi:[1,0,1]
	ds_write_b64 v18, v[162:163]
	ds_write_b64 v18, v[26:27] offset:4224
	ds_write_b64 v18, v[48:49] offset:8448
	ds_write_b64 v18, v[10:11] offset:12672
	ds_write_b64 v18, v[46:47] offset:16896
	ds_write_b64 v18, v[20:21] offset:21120
	ds_write_b64 v18, v[36:37] offset:25344
	ds_write_b64 v18, v[4:5] offset:29568
	ds_write_b64 v18, v[34:35] offset:33792
	ds_write_b64 v18, v[78:79] offset:38016
	ds_write_b64 v18, v[106:107] offset:42240
	ds_write_b64 v18, v[32:33] offset:46464
	ds_write_b64 v18, v[54:55] offset:50688
	ds_write_b64 v18, v[62:63] offset:54912
	ds_write_b64 v18, v[92:93] offset:59136
	ds_write_b64 v18, v[8:9] offset:63360
	v_add_u32_e32 v4, 0x10800, v18
	v_pk_mul_f32 v[72:73], v[110:111], v[176:177] op_sel:[1,1] op_sel_hi:[1,0] neg_lo:[1,0]
	v_pk_fma_f32 v[82:83], v[130:131], v[82:83], v[84:85] op_sel_hi:[1,0,1]
	ds_write_b64 v4, v[30:31]
	v_add_u32_e32 v4, 0x11880, v18
	v_pk_fma_f32 v[72:73], v[110:111], v[176:177], v[72:73] op_sel_hi:[0,1,1]
	v_pk_mul_f32 v[42:43], v[138:139], v[40:41] op_sel:[1,1] op_sel_hi:[0,1] neg_lo:[0,1]
	ds_write_b64 v4, v[82:83]
	v_add_u32_e32 v4, 0x12900, v18
	v_pk_mul_f32 v[52:53], v[124:125], v[182:183] op_sel:[1,1] op_sel_hi:[1,0] neg_lo:[1,0]
	v_pk_fma_f32 v[40:41], v[138:139], v[40:41], v[42:43] op_sel_hi:[1,0,1]
	ds_write_b64 v4, v[72:73]
	v_add_u32_e32 v4, 0x13980, v18
	v_pk_fma_f32 v[52:53], v[124:125], v[182:183], v[52:53] op_sel_hi:[0,1,1]
	v_pk_mul_f32 v[68:69], v[178:179], v[66:67] op_sel:[1,1] op_sel_hi:[0,1] neg_lo:[0,1]
	ds_write_b64 v4, v[40:41]
	v_add_u32_e32 v4, 0x14a00, v18
	v_pk_mul_f32 v[98:99], v[96:97], v[186:187] op_sel:[1,1] op_sel_hi:[1,0] neg_lo:[1,0]
	v_pk_fma_f32 v[66:67], v[178:179], v[66:67], v[68:69] op_sel_hi:[1,0,1]
	ds_write_b64 v4, v[52:53]
	v_add_u32_e32 v4, 0x15a80, v18
	v_pk_fma_f32 v[96:97], v[96:97], v[186:187], v[98:99] op_sel_hi:[0,1,1]
	v_pk_mul_f32 v[16:17], v[160:161], v[14:15] op_sel:[1,1] op_sel_hi:[0,1] neg_lo:[0,1]
	ds_write_b64 v4, v[66:67]
	v_add_u32_e32 v4, 0x16b00, v18
	v_pk_add_f32 v[168:169], v[168:169], v[188:189] neg_lo:[0,1] neg_hi:[0,1]
	v_pk_fma_f32 v[14:15], v[160:161], v[14:15], v[16:17] op_sel_hi:[1,0,1]
	ds_write_b64 v4, v[96:97]
	v_add_u32_e32 v4, 0x17b80, v18
	v_pk_add_f32 v[188:189], v[170:171], v[184:185] op_sel:[0,1] op_sel_hi:[1,0] neg_hi:[0,1]
	v_pk_mul_f32 v[76:77], v[168:169], v[74:75] op_sel:[1,1] op_sel_hi:[0,1] neg_lo:[0,1]
	ds_write_b64 v4, v[14:15]
	v_add_u32_e32 v4, 0x18c00, v18
	v_pk_add_f32 v[170:171], v[170:171], v[184:185] op_sel:[0,1] op_sel_hi:[1,0] neg_lo:[0,1]
	v_pk_mul_f32 v[104:105], v[102:103], v[188:189] op_sel:[1,1] op_sel_hi:[1,0] neg_lo:[1,0]
	v_pk_fma_f32 v[74:75], v[168:169], v[74:75], v[76:77] op_sel_hi:[1,0,1]
	ds_write_b64 v4, v[44:45]
	v_add_u32_e32 v4, 0x19c80, v18
	v_pk_add_f32 v[184:185], v[164:165], v[172:173]
	v_pk_fma_f32 v[102:103], v[102:103], v[188:189], v[104:105] op_sel_hi:[0,1,1]
	v_pk_mul_f32 v[28:29], v[170:171], v[24:25] op_sel:[1,1] op_sel_hi:[0,1] neg_lo:[0,1]
	ds_write_b64 v4, v[74:75]
	v_add_u32_e32 v4, 0x1ad00, v18
	v_pk_add_f32 v[164:165], v[164:165], v[172:173] neg_lo:[0,1] neg_hi:[0,1]
	v_pk_mul_f32 v[58:59], v[116:117], v[184:185] op_sel:[1,1] op_sel_hi:[1,0] neg_lo:[1,0]
	v_pk_fma_f32 v[24:25], v[170:171], v[24:25], v[28:29] op_sel_hi:[1,0,1]
	ds_write_b64 v4, v[102:103]
	v_add_u32_e32 v4, 0x1bd80, v18
	v_pk_add_f32 v[172:173], v[128:129], v[166:167] op_sel:[0,1] op_sel_hi:[1,0] neg_hi:[0,1]
	v_pk_fma_f32 v[58:59], v[116:117], v[184:185], v[58:59] op_sel_hi:[0,1,1]
	v_pk_mul_f32 v[60:61], v[164:165], v[56:57] op_sel:[1,1] op_sel_hi:[0,1] neg_lo:[0,1]
	ds_write_b64 v4, v[24:25]
	v_add_u32_e32 v4, 0x1ce00, v18
	v_pk_add_f32 v[128:129], v[128:129], v[166:167] op_sel:[0,1] op_sel_hi:[1,0] neg_lo:[0,1]
	v_pk_mul_f32 v[90:91], v[88:89], v[172:173] op_sel:[1,1] op_sel_hi:[1,0] neg_lo:[1,0]
	v_pk_fma_f32 v[56:57], v[164:165], v[56:57], v[60:61] op_sel_hi:[1,0,1]
	ds_write_b64 v4, v[58:59]
	v_add_u32_e32 v4, 0x1de80, v18
	v_pk_fma_f32 v[88:89], v[88:89], v[172:173], v[90:91] op_sel_hi:[0,1,1]
	v_pk_mul_f32 v[6:7], v[128:129], v[2:3] op_sel:[1,1] op_sel_hi:[0,1] neg_lo:[0,1]
	ds_write_b64 v4, v[56:57]
	v_add_u32_e32 v4, 0x1ef00, v18
	v_pk_fma_f32 v[2:3], v[128:129], v[2:3], v[6:7] op_sel_hi:[1,0,1]
	ds_write_b64 v4, v[88:89]
	v_add_u32_e32 v4, 0x1ff80, v18
	ds_write_b64 v4, v[2:3]
	v_mov_b32_e32 v2, v210
	s_waitcnt lgkmcnt(0)
	s_barrier
	s_ashr_i32 s77, s76, 31
	v_and_b32_e32 v3, 15, v2
	v_lshlrev_b32_e32 v2, 5, v2
	v_and_b32_e32 v4, 0xfffffe00, v2
	v_lshl_add_u32 v5, v4, 3, 0
	v_lshlrev_b32_e32 v6, 3, v3
	v_ashrrev_i32_e32 v7, 2, v4
	v_add3_u32 v18, v5, v6, v7
	v_add_u32_e32 v196, 0x800, v18
	ds_read2_b64 v[128:131], v18 offset1:16
	ds_read2_b64 v[132:135], v18 offset0:33 offset1:49
	ds_read2_b64 v[136:139], v18 offset0:66 offset1:82
	ds_read2_b64 v[140:143], v18 offset0:99 offset1:115
	ds_read2_b64 v[148:151], v18 offset0:132 offset1:148
	ds_read2_b64 v[152:155], v18 offset0:165 offset1:181
	ds_read2_b64 v[156:159], v18 offset0:198 offset1:214
	ds_read2_b64 v[160:163], v18 offset0:231 offset1:247
	ds_read2_b64 v[164:167], v196 offset0:8 offset1:24
	ds_read2_b64 v[168:171], v196 offset0:41 offset1:57
	ds_read2_b64 v[172:175], v196 offset0:74 offset1:90
	ds_read2_b64 v[176:179], v196 offset0:107 offset1:123
	ds_read2_b64 v[180:183], v196 offset0:140 offset1:156
	ds_read2_b64 v[184:187], v196 offset0:173 offset1:189
	ds_read2_b64 v[188:191], v196 offset0:206 offset1:222
	ds_read2_b64 v[192:195], v196 offset0:239 offset1:255
	s_waitcnt lgkmcnt(7)
	v_pk_add_f32 v[144:145], v[128:129], v[164:165]
	v_pk_add_f32 v[128:129], v[128:129], v[164:165] neg_lo:[0,1] neg_hi:[0,1]
	v_pk_add_f32 v[164:165], v[130:131], v[166:167]
	v_pk_add_f32 v[130:131], v[130:131], v[166:167] neg_lo:[0,1] neg_hi:[0,1]
	v_cvt_f32_ubyte0_e32 v2, v3
	v_pk_mul_f32 v[166:167], v[130:131], s[10:11]
	v_mul_f32_e32 v3, 0x3b000000, v2
	v_pk_fma_f32 v[130:131], v[130:131], s[8:9], v[166:167] op_sel:[0,0,1] op_sel_hi:[1,0,0]
	s_waitcnt lgkmcnt(6)
	v_pk_add_f32 v[166:167], v[132:133], v[168:169]
	v_pk_add_f32 v[132:133], v[132:133], v[168:169] neg_lo:[0,1] neg_hi:[0,1]
	v_sin_f32_e32 v2, v3
	v_pk_mul_f32 v[168:169], v[132:133], s[18:19]
	v_cos_f32_e32 v4, v3
	v_pk_fma_f32 v[132:133], v[132:133], s[16:17], v[168:169] op_sel:[0,0,1] op_sel_hi:[1,0,0]
	v_pk_add_f32 v[168:169], v[134:135], v[170:171]
	v_pk_add_f32 v[134:135], v[134:135], v[170:171] neg_lo:[0,1] neg_hi:[0,1]
	v_xor_b32_e32 v5, 0x80000000, v2
	v_pk_mul_f32 v[170:171], v[134:135], s[26:27]
	v_mov_b32_e32 v3, v5
	v_pk_fma_f32 v[134:135], v[134:135], s[24:25], v[170:171] op_sel:[0,0,1] op_sel_hi:[1,0,0]
	s_waitcnt lgkmcnt(5)
	v_pk_add_f32 v[170:171], v[136:137], v[172:173]
	v_pk_add_f32 v[136:137], v[136:137], v[172:173] neg_lo:[0,1] neg_hi:[0,1]
	v_pk_mul_f32 v[6:7], v[4:5], v[2:3] op_sel:[1,0] op_sel_hi:[0,1]
	v_pk_mul_f32 v[172:173], v[136:137], s[36:37]
	v_pk_fma_f32 v[6:7], v[4:5], v[4:5], v[6:7] op_sel_hi:[1,0,1]
	v_pk_fma_f32 v[136:137], v[136:137], s[78:79], v[172:173] op_sel:[0,0,1] op_sel_hi:[1,0,0]
	v_pk_add_f32 v[172:173], v[138:139], v[174:175]
	v_pk_add_f32 v[138:139], v[138:139], v[174:175] neg_lo:[0,1] neg_hi:[0,1]
	v_pk_mul_f32 v[174:175], v[138:139], s[38:39]
	v_pk_fma_f32 v[138:139], v[138:139], s[0:1], v[174:175] op_sel:[0,0,1] op_sel_hi:[1,0,0]
	s_waitcnt lgkmcnt(4)
	v_pk_add_f32 v[174:175], v[140:141], v[176:177]
	v_pk_add_f32 v[140:141], v[140:141], v[176:177] neg_lo:[0,1] neg_hi:[0,1]
	v_pk_mul_f32 v[10:11], v[6:7], v[6:7] op_sel:[1,1] op_sel_hi:[0,1] neg_lo:[0,1]
	v_pk_mul_f32 v[176:177], v[140:141], s[40:41]
	v_pk_fma_f32 v[10:11], v[6:7], v[6:7], v[10:11] op_sel_hi:[1,0,1]
	v_pk_fma_f32 v[140:141], v[140:141], s[80:81], v[176:177] op_sel:[0,0,1] op_sel_hi:[1,0,0]
	v_pk_add_f32 v[176:177], v[142:143], v[178:179]
	v_pk_add_f32 v[142:143], v[142:143], v[178:179] neg_lo:[0,1] neg_hi:[0,1]
	v_pk_mul_f32 v[178:179], v[142:143], s[42:43]
	v_pk_fma_f32 v[142:143], v[142:143], s[74:75], v[178:179] op_sel:[0,0,1] op_sel_hi:[1,0,0]
	s_waitcnt lgkmcnt(3)
	v_pk_add_f32 v[178:179], v[148:149], v[180:181]
	v_pk_add_f32 v[180:181], v[148:149], v[180:181] neg_lo:[0,1] neg_hi:[0,1]
	v_pk_mul_f32 v[28:29], v[10:11], v[10:11] op_sel:[1,1] op_sel_hi:[0,1] neg_lo:[0,1]
	v_pk_add_f32 v[148:149], v[150:151], v[182:183]
	v_pk_add_f32 v[150:151], v[150:151], v[182:183] neg_lo:[0,1] neg_hi:[0,1]
	v_pk_fma_f32 v[28:29], v[10:11], v[10:11], v[28:29] op_sel_hi:[1,0,1]
	v_pk_mul_f32 v[182:183], v[150:151], s[42:43]
	v_pk_mul_f32 v[44:45], v[10:11], v[28:29] op_sel:[1,1] op_sel_hi:[1,0] neg_lo:[1,0]
	v_pk_fma_f32 v[150:151], v[150:151], s[74:75], v[182:183] op_sel:[0,0,1] op_sel_hi:[1,0,0] neg_lo:[1,0,0] neg_hi:[1,0,0]
	s_waitcnt lgkmcnt(2)
	v_pk_add_f32 v[182:183], v[152:153], v[184:185]
	v_pk_add_f32 v[152:153], v[152:153], v[184:185] neg_lo:[0,1] neg_hi:[0,1]
	v_pk_fma_f32 v[44:45], v[10:11], v[28:29], v[44:45] op_sel_hi:[0,1,1]
	v_pk_mul_f32 v[184:185], v[152:153], s[40:41]
	v_pk_mul_f32 v[60:61], v[10:11], v[44:45] op_sel:[1,1] op_sel_hi:[1,0] neg_lo:[1,0]
	v_pk_fma_f32 v[152:153], v[152:153], s[80:81], v[184:185] op_sel:[0,0,1] op_sel_hi:[1,0,0] neg_lo:[1,0,0] neg_hi:[1,0,0]
	v_pk_add_f32 v[184:185], v[154:155], v[186:187]
	v_pk_add_f32 v[154:155], v[154:155], v[186:187] neg_lo:[0,1] neg_hi:[0,1]
	v_pk_fma_f32 v[60:61], v[10:11], v[44:45], v[60:61] op_sel_hi:[0,1,1]
	v_pk_mul_f32 v[186:187], v[154:155], s[38:39]
	v_pk_mul_f32 v[76:77], v[10:11], v[60:61] op_sel:[1,1] op_sel_hi:[1,0] neg_lo:[1,0]
	v_pk_fma_f32 v[154:155], v[154:155], s[0:1], v[186:187] op_sel:[0,0,1] op_sel_hi:[1,0,0] neg_lo:[1,0,0] neg_hi:[1,0,0]
	s_waitcnt lgkmcnt(1)
	v_pk_add_f32 v[186:187], v[156:157], v[188:189]
	v_pk_add_f32 v[156:157], v[156:157], v[188:189] neg_lo:[0,1] neg_hi:[0,1]
	v_pk_fma_f32 v[76:77], v[10:11], v[60:61], v[76:77] op_sel_hi:[0,1,1]
	v_pk_mul_f32 v[188:189], v[156:157], s[36:37]
	v_pk_mul_f32 v[92:93], v[10:11], v[76:77] op_sel:[1,1] op_sel_hi:[1,0] neg_lo:[1,0]
	v_pk_fma_f32 v[156:157], v[156:157], s[78:79], v[188:189] op_sel:[0,0,1] op_sel_hi:[1,0,0] neg_lo:[1,0,0] neg_hi:[1,0,0]
	v_pk_add_f32 v[188:189], v[158:159], v[190:191]
	v_pk_add_f32 v[158:159], v[158:159], v[190:191] neg_lo:[0,1] neg_hi:[0,1]
	v_pk_fma_f32 v[92:93], v[10:11], v[76:77], v[92:93] op_sel_hi:[0,1,1]
	v_pk_mul_f32 v[190:191], v[158:159], s[26:27]
	v_pk_mul_f32 v[108:109], v[10:11], v[92:93] op_sel:[1,1] op_sel_hi:[1,0] neg_lo:[1,0]
	v_pk_fma_f32 v[158:159], v[158:159], s[24:25], v[190:191] op_sel:[0,0,1] op_sel_hi:[1,0,0] neg_lo:[1,0,0] neg_hi:[1,0,0]
	s_waitcnt lgkmcnt(0)
	v_pk_add_f32 v[190:191], v[160:161], v[192:193]
	v_pk_add_f32 v[160:161], v[160:161], v[192:193] neg_lo:[0,1] neg_hi:[0,1]
	v_pk_mul_f32 v[8:9], v[2:3], v[6:7] op_sel:[0,1] op_sel_hi:[1,0]
	v_pk_mul_f32 v[192:193], v[160:161], s[18:19]
	v_pk_fma_f32 v[108:109], v[10:11], v[92:93], v[108:109] op_sel_hi:[0,1,1]
	v_pk_fma_f32 v[160:161], v[160:161], s[16:17], v[192:193] op_sel:[0,0,1] op_sel_hi:[1,0,0] neg_lo:[1,0,0] neg_hi:[1,0,0]
	v_pk_add_f32 v[192:193], v[162:163], v[194:195]
	v_pk_add_f32 v[162:163], v[162:163], v[194:195] neg_lo:[0,1] neg_hi:[0,1]
	v_pk_fma_f32 v[8:9], v[4:5], v[6:7], v[8:9] op_sel_hi:[0,1,1]
	v_pk_mul_f32 v[194:195], v[162:163], s[10:11]
	v_pk_mul_f32 v[16:17], v[2:3], v[10:11] op_sel:[0,1] op_sel_hi:[1,0]
	v_pk_fma_f32 v[162:163], v[162:163], s[8:9], v[194:195] op_sel:[0,0,1] op_sel_hi:[1,0,0] neg_lo:[1,0,0] neg_hi:[1,0,0]
	v_pk_add_f32 v[194:195], v[144:145], v[178:179]
	v_pk_add_f32 v[144:145], v[144:145], v[178:179] neg_lo:[0,1] neg_hi:[0,1]
	v_pk_add_f32 v[178:179], v[164:165], v[148:149]
	v_pk_add_f32 v[148:149], v[164:165], v[148:149] neg_lo:[0,1] neg_hi:[0,1]
	v_pk_mul_f32 v[32:33], v[2:3], v[28:29] op_sel:[0,1] op_sel_hi:[1,0]
	v_pk_mul_f32 v[164:165], v[148:149], s[18:19]
	v_pk_mul_f32 v[48:49], v[2:3], v[44:45] op_sel:[0,1] op_sel_hi:[1,0]
	v_pk_fma_f32 v[148:149], v[148:149], s[16:17], v[164:165] op_sel:[0,0,1] op_sel_hi:[1,0,0]
	v_pk_add_f32 v[164:165], v[166:167], v[182:183]
	v_pk_add_f32 v[166:167], v[166:167], v[182:183] neg_lo:[0,1] neg_hi:[0,1]
	v_pk_mul_f32 v[64:65], v[2:3], v[60:61] op_sel:[0,1] op_sel_hi:[1,0]
	v_pk_mul_f32 v[182:183], v[166:167], s[36:37]
	v_pk_mul_f32 v[80:81], v[2:3], v[76:77] op_sel:[0,1] op_sel_hi:[1,0]
	v_pk_fma_f32 v[166:167], v[166:167], s[78:79], v[182:183] op_sel:[0,0,1] op_sel_hi:[1,0,0]
	v_pk_add_f32 v[182:183], v[168:169], v[184:185]
	v_pk_add_f32 v[168:169], v[168:169], v[184:185] neg_lo:[0,1] neg_hi:[0,1]
	v_pk_mul_f32 v[96:97], v[2:3], v[92:93] op_sel:[0,1] op_sel_hi:[1,0]
	v_pk_mul_f32 v[184:185], v[168:169], s[40:41]
	v_pk_mul_f32 v[112:113], v[2:3], v[108:109] op_sel:[0,1] op_sel_hi:[1,0]
	v_pk_fma_f32 v[168:169], v[168:169], s[80:81], v[184:185] op_sel:[0,0,1] op_sel_hi:[1,0,0]
	v_pk_add_f32 v[184:185], v[170:171], v[186:187]
	v_pk_add_f32 v[186:187], v[170:171], v[186:187] neg_lo:[0,1] neg_hi:[0,1]
	v_pk_add_f32 v[170:171], v[172:173], v[188:189]
	v_pk_add_f32 v[172:173], v[172:173], v[188:189] neg_lo:[0,1] neg_hi:[0,1]
	v_pk_mul_f32 v[188:189], v[172:173], s[40:41]
	v_pk_fma_f32 v[16:17], v[4:5], v[10:11], v[16:17] op_sel_hi:[0,1,1]
	v_pk_fma_f32 v[172:173], v[172:173], s[80:81], v[188:189] op_sel:[0,0,1] op_sel_hi:[1,0,0] neg_lo:[1,0,0] neg_hi:[1,0,0]
	v_pk_add_f32 v[188:189], v[174:175], v[190:191]
	v_pk_add_f32 v[174:175], v[174:175], v[190:191] neg_lo:[0,1] neg_hi:[0,1]
	v_pk_mul_f32 v[20:21], v[6:7], v[10:11] op_sel:[1,1] op_sel_hi:[1,0] neg_lo:[1,0]
	v_pk_mul_f32 v[190:191], v[174:175], s[36:37]
	v_pk_fma_f32 v[32:33], v[4:5], v[28:29], v[32:33] op_sel_hi:[0,1,1]
	v_pk_fma_f32 v[174:175], v[174:175], s[78:79], v[190:191] op_sel:[0,0,1] op_sel_hi:[1,0,0] neg_lo:[1,0,0] neg_hi:[1,0,0]
	v_pk_add_f32 v[190:191], v[176:177], v[192:193]
	v_pk_add_f32 v[176:177], v[176:177], v[192:193] neg_lo:[0,1] neg_hi:[0,1]
	v_pk_mul_f32 v[36:37], v[6:7], v[28:29] op_sel:[1,1] op_sel_hi:[1,0] neg_lo:[1,0]
	v_pk_mul_f32 v[192:193], v[176:177], s[18:19]
	v_pk_fma_f32 v[48:49], v[4:5], v[44:45], v[48:49] op_sel_hi:[0,1,1]
	v_pk_fma_f32 v[176:177], v[176:177], s[16:17], v[192:193] op_sel:[0,0,1] op_sel_hi:[1,0,0] neg_lo:[1,0,0] neg_hi:[1,0,0]
	v_pk_add_f32 v[192:193], v[128:129], v[180:181] op_sel:[0,1] op_sel_hi:[1,0] neg_hi:[0,1]
	v_pk_add_f32 v[128:129], v[128:129], v[180:181] op_sel:[0,1] op_sel_hi:[1,0] neg_lo:[0,1]
	v_pk_add_f32 v[180:181], v[130:131], v[150:151]
	v_pk_add_f32 v[130:131], v[130:131], v[150:151] neg_lo:[0,1] neg_hi:[0,1]
	v_pk_mul_f32 v[52:53], v[6:7], v[44:45] op_sel:[1,1] op_sel_hi:[1,0] neg_lo:[1,0]
	v_pk_mul_f32 v[150:151], v[130:131], s[18:19]
	v_pk_fma_f32 v[64:65], v[4:5], v[60:61], v[64:65] op_sel_hi:[0,1,1]
	v_pk_fma_f32 v[130:131], v[130:131], s[16:17], v[150:151] op_sel:[0,0,1] op_sel_hi:[1,0,0]
	v_pk_add_f32 v[150:151], v[132:133], v[152:153]
	v_pk_add_f32 v[132:133], v[132:133], v[152:153] neg_lo:[0,1] neg_hi:[0,1]
	v_pk_mul_f32 v[68:69], v[6:7], v[60:61] op_sel:[1,1] op_sel_hi:[1,0] neg_lo:[1,0]
	v_pk_mul_f32 v[152:153], v[132:133], s[36:37]
	v_pk_fma_f32 v[80:81], v[4:5], v[76:77], v[80:81] op_sel_hi:[0,1,1]
	v_pk_fma_f32 v[132:133], v[132:133], s[78:79], v[152:153] op_sel:[0,0,1] op_sel_hi:[1,0,0]
	v_pk_add_f32 v[152:153], v[134:135], v[154:155]
	v_pk_add_f32 v[134:135], v[134:135], v[154:155] neg_lo:[0,1] neg_hi:[0,1]
	v_pk_mul_f32 v[84:85], v[6:7], v[76:77] op_sel:[1,1] op_sel_hi:[1,0] neg_lo:[1,0]
	v_pk_mul_f32 v[154:155], v[134:135], s[40:41]
	v_pk_fma_f32 v[96:97], v[4:5], v[92:93], v[96:97] op_sel_hi:[0,1,1]
	v_pk_fma_f32 v[134:135], v[134:135], s[80:81], v[154:155] op_sel:[0,0,1] op_sel_hi:[1,0,0]
	v_pk_add_f32 v[154:155], v[136:137], v[156:157]
	v_pk_add_f32 v[156:157], v[136:137], v[156:157] neg_lo:[0,1] neg_hi:[0,1]
	v_pk_mul_f32 v[100:101], v[6:7], v[92:93] op_sel:[1,1] op_sel_hi:[1,0] neg_lo:[1,0]
	v_pk_add_f32 v[136:137], v[138:139], v[158:159]
	v_pk_add_f32 v[138:139], v[138:139], v[158:159] neg_lo:[0,1] neg_hi:[0,1]
	v_pk_fma_f32 v[112:113], v[4:5], v[108:109], v[112:113] op_sel_hi:[0,1,1]
	v_pk_mul_f32 v[158:159], v[138:139], s[40:41]
	v_pk_mul_f32 v[116:117], v[6:7], v[108:109] op_sel:[1,1] op_sel_hi:[1,0] neg_lo:[1,0]
	v_pk_fma_f32 v[138:139], v[138:139], s[80:81], v[158:159] op_sel:[0,0,1] op_sel_hi:[1,0,0] neg_lo:[1,0,0] neg_hi:[1,0,0]
	v_pk_add_f32 v[158:159], v[140:141], v[160:161]
	v_pk_add_f32 v[140:141], v[140:141], v[160:161] neg_lo:[0,1] neg_hi:[0,1]
	v_pk_fma_f32 v[20:21], v[6:7], v[10:11], v[20:21] op_sel_hi:[0,1,1]
	v_pk_mul_f32 v[160:161], v[140:141], s[36:37]
	v_pk_mul_f32 v[24:25], v[10:11], v[8:9] op_sel:[1,1] op_sel_hi:[0,1] neg_lo:[0,1]
	v_pk_fma_f32 v[140:141], v[140:141], s[78:79], v[160:161] op_sel:[0,0,1] op_sel_hi:[1,0,0] neg_lo:[1,0,0] neg_hi:[1,0,0]
	v_pk_add_f32 v[160:161], v[142:143], v[162:163]
	v_pk_add_f32 v[142:143], v[142:143], v[162:163] neg_lo:[0,1] neg_hi:[0,1]
	v_pk_fma_f32 v[36:37], v[6:7], v[28:29], v[36:37] op_sel_hi:[0,1,1]
	v_pk_mul_f32 v[162:163], v[142:143], s[18:19]
	v_pk_mul_f32 v[40:41], v[8:9], v[28:29] op_sel:[1,1] op_sel_hi:[1,0] neg_lo:[1,0]
	v_pk_fma_f32 v[142:143], v[142:143], s[16:17], v[162:163] op_sel:[0,0,1] op_sel_hi:[1,0,0] neg_lo:[1,0,0] neg_hi:[1,0,0]
	v_pk_add_f32 v[162:163], v[194:195], v[184:185]
	v_pk_add_f32 v[184:185], v[194:195], v[184:185] neg_lo:[0,1] neg_hi:[0,1]
	v_pk_add_f32 v[194:195], v[178:179], v[170:171]
	v_pk_add_f32 v[170:171], v[178:179], v[170:171] neg_lo:[0,1] neg_hi:[0,1]
	v_pk_fma_f32 v[52:53], v[6:7], v[44:45], v[52:53] op_sel_hi:[0,1,1]
	v_pk_mul_f32 v[178:179], v[170:171], s[36:37]
	v_pk_mul_f32 v[56:57], v[8:9], v[44:45] op_sel:[1,1] op_sel_hi:[1,0] neg_lo:[1,0]
	v_pk_fma_f32 v[170:171], v[170:171], s[78:79], v[178:179] op_sel:[0,0,1] op_sel_hi:[1,0,0]
	v_pk_add_f32 v[178:179], v[164:165], v[188:189]
	v_pk_add_f32 v[188:189], v[164:165], v[188:189] neg_lo:[0,1] neg_hi:[0,1]
	v_pk_fma_f32 v[68:69], v[6:7], v[60:61], v[68:69] op_sel_hi:[0,1,1]
	v_pk_add_f32 v[164:165], v[182:183], v[190:191]
	v_pk_add_f32 v[182:183], v[182:183], v[190:191] neg_lo:[0,1] neg_hi:[0,1]
	v_pk_mul_f32 v[72:73], v[8:9], v[60:61] op_sel:[1,1] op_sel_hi:[1,0] neg_lo:[1,0]
	v_pk_mul_f32 v[190:191], v[182:183], s[36:37]
	v_pk_fma_f32 v[84:85], v[6:7], v[76:77], v[84:85] op_sel_hi:[0,1,1]
	v_pk_fma_f32 v[182:183], v[182:183], s[78:79], v[190:191] op_sel:[0,0,1] op_sel_hi:[1,0,0] neg_lo:[1,0,0] neg_hi:[1,0,0]
	v_pk_add_f32 v[190:191], v[144:145], v[186:187] op_sel:[0,1] op_sel_hi:[1,0] neg_hi:[0,1]
	v_pk_add_f32 v[144:145], v[144:145], v[186:187] op_sel:[0,1] op_sel_hi:[1,0] neg_lo:[0,1]
	v_pk_add_f32 v[186:187], v[148:149], v[172:173]
	v_pk_add_f32 v[148:149], v[148:149], v[172:173] neg_lo:[0,1] neg_hi:[0,1]
	v_pk_mul_f32 v[88:89], v[8:9], v[76:77] op_sel:[1,1] op_sel_hi:[1,0] neg_lo:[1,0]
	v_pk_mul_f32 v[172:173], v[148:149], s[36:37]
	v_pk_fma_f32 v[100:101], v[6:7], v[92:93], v[100:101] op_sel_hi:[0,1,1]
	v_pk_fma_f32 v[148:149], v[148:149], s[78:79], v[172:173] op_sel:[0,0,1] op_sel_hi:[1,0,0]
	v_pk_add_f32 v[172:173], v[166:167], v[174:175]
	v_pk_add_f32 v[174:175], v[166:167], v[174:175] neg_lo:[0,1] neg_hi:[0,1]
	v_pk_mul_f32 v[104:105], v[8:9], v[92:93] op_sel:[1,1] op_sel_hi:[1,0] neg_lo:[1,0]
	v_pk_add_f32 v[166:167], v[168:169], v[176:177]
	v_pk_add_f32 v[168:169], v[168:169], v[176:177] neg_lo:[0,1] neg_hi:[0,1]
	v_pk_fma_f32 v[116:117], v[6:7], v[108:109], v[116:117] op_sel_hi:[0,1,1]
	v_pk_mul_f32 v[176:177], v[168:169], s[36:37]
	v_pk_mul_f32 v[120:121], v[8:9], v[108:109] op_sel:[1,1] op_sel_hi:[1,0] neg_lo:[1,0]
	v_pk_fma_f32 v[168:169], v[168:169], s[78:79], v[176:177] op_sel:[0,0,1] op_sel_hi:[1,0,0] neg_lo:[1,0,0] neg_hi:[1,0,0]
	v_pk_add_f32 v[176:177], v[192:193], v[154:155]
	v_pk_add_f32 v[154:155], v[192:193], v[154:155] neg_lo:[0,1] neg_hi:[0,1]
	v_pk_add_f32 v[192:193], v[180:181], v[136:137]
	v_pk_add_f32 v[136:137], v[180:181], v[136:137] neg_lo:[0,1] neg_hi:[0,1]
	v_xor_b32_e32 v26, 0x80000000, v17
	v_pk_mul_f32 v[180:181], v[136:137], s[36:37]
	v_xor_b32_e32 v30, 0x80000000, v21
	v_pk_fma_f32 v[136:137], v[136:137], s[78:79], v[180:181] op_sel:[0,0,1] op_sel_hi:[1,0,0]
	v_pk_add_f32 v[180:181], v[150:151], v[158:159]
	v_pk_add_f32 v[158:159], v[150:151], v[158:159] neg_lo:[0,1] neg_hi:[0,1]
	v_pk_fma_f32 v[24:25], v[10:11], v[8:9], v[24:25] op_sel_hi:[1,0,1]
	v_pk_add_f32 v[150:151], v[152:153], v[160:161]
	v_pk_add_f32 v[152:153], v[152:153], v[160:161] neg_lo:[0,1] neg_hi:[0,1]
	v_pk_fma_f32 v[40:41], v[8:9], v[28:29], v[40:41] op_sel_hi:[0,1,1]
	v_pk_mul_f32 v[160:161], v[152:153], s[36:37]
	v_pk_fma_f32 v[56:57], v[8:9], v[44:45], v[56:57] op_sel_hi:[0,1,1]
	v_pk_fma_f32 v[152:153], v[152:153], s[78:79], v[160:161] op_sel:[0,0,1] op_sel_hi:[1,0,0] neg_lo:[1,0,0] neg_hi:[1,0,0]
	v_pk_add_f32 v[160:161], v[128:129], v[156:157] op_sel:[0,1] op_sel_hi:[1,0] neg_hi:[0,1]
	v_pk_add_f32 v[128:129], v[128:129], v[156:157] op_sel:[0,1] op_sel_hi:[1,0] neg_lo:[0,1]
	v_pk_add_f32 v[156:157], v[130:131], v[138:139]
	v_pk_add_f32 v[130:131], v[130:131], v[138:139] neg_lo:[0,1] neg_hi:[0,1]
	v_pk_fma_f32 v[72:73], v[8:9], v[60:61], v[72:73] op_sel_hi:[0,1,1]
	v_pk_mul_f32 v[138:139], v[130:131], s[36:37]
	v_pk_fma_f32 v[88:89], v[8:9], v[76:77], v[88:89] op_sel_hi:[0,1,1]
	v_pk_fma_f32 v[130:131], v[130:131], s[78:79], v[138:139] op_sel:[0,0,1] op_sel_hi:[1,0,0]
	v_pk_add_f32 v[138:139], v[132:133], v[140:141]
	v_pk_add_f32 v[140:141], v[132:133], v[140:141] neg_lo:[0,1] neg_hi:[0,1]
	v_pk_fma_f32 v[104:105], v[8:9], v[92:93], v[104:105] op_sel_hi:[0,1,1]
	v_pk_add_f32 v[132:133], v[134:135], v[142:143]
	v_pk_add_f32 v[134:135], v[134:135], v[142:143] neg_lo:[0,1] neg_hi:[0,1]
	v_pk_fma_f32 v[120:121], v[8:9], v[108:109], v[120:121] op_sel_hi:[0,1,1]
	v_pk_mul_f32 v[142:143], v[134:135], s[36:37]
	v_mov_b32_e32 v27, v17
	v_pk_fma_f32 v[134:135], v[134:135], s[78:79], v[142:143] op_sel:[0,0,1] op_sel_hi:[1,0,0] neg_lo:[1,0,0] neg_hi:[1,0,0]
	v_pk_add_f32 v[142:143], v[162:163], v[178:179]
	v_pk_add_f32 v[162:163], v[162:163], v[178:179] neg_lo:[0,1] neg_hi:[0,1]
	v_pk_add_f32 v[178:179], v[194:195], v[164:165]
	v_pk_add_f32 v[194:195], v[194:195], v[164:165] neg_lo:[0,1] neg_hi:[0,1]
	v_mov_b32_e32 v31, v21
	v_pk_add_f32 v[164:165], v[184:185], v[188:189] op_sel:[0,1] op_sel_hi:[1,0] neg_hi:[0,1]
	v_pk_add_f32 v[184:185], v[184:185], v[188:189] op_sel:[0,1] op_sel_hi:[1,0] neg_lo:[0,1]
	v_pk_add_f32 v[188:189], v[170:171], v[182:183]
	v_pk_add_f32 v[182:183], v[170:171], v[182:183] neg_lo:[0,1] neg_hi:[0,1]
	v_xor_b32_e32 v34, 0x80000000, v25
	v_pk_add_f32 v[170:171], v[190:191], v[172:173]
	v_pk_add_f32 v[172:173], v[190:191], v[172:173] neg_lo:[0,1] neg_hi:[0,1]
	v_pk_add_f32 v[190:191], v[186:187], v[166:167]
	v_pk_add_f32 v[186:187], v[186:187], v[166:167] neg_lo:[0,1] neg_hi:[0,1]
	v_xor_b32_e32 v38, 0x80000000, v29
	v_pk_add_f32 v[166:167], v[144:145], v[174:175] op_sel:[0,1] op_sel_hi:[1,0] neg_hi:[0,1]
	v_pk_add_f32 v[144:145], v[144:145], v[174:175] op_sel:[0,1] op_sel_hi:[1,0] neg_lo:[0,1]
	v_pk_add_f32 v[174:175], v[148:149], v[168:169]
	v_pk_add_f32 v[168:169], v[148:149], v[168:169] neg_lo:[0,1] neg_hi:[0,1]
	v_xor_b32_e32 v42, 0x80000000, v33
	v_pk_add_f32 v[148:149], v[176:177], v[180:181]
	v_pk_add_f32 v[176:177], v[176:177], v[180:181] neg_lo:[0,1] neg_hi:[0,1]
	v_pk_add_f32 v[180:181], v[192:193], v[150:151]
	v_pk_add_f32 v[192:193], v[192:193], v[150:151] neg_lo:[0,1] neg_hi:[0,1]
	v_xor_b32_e32 v46, 0x80000000, v37
	v_pk_add_f32 v[150:151], v[154:155], v[158:159] op_sel:[0,1] op_sel_hi:[1,0] neg_hi:[0,1]
	v_pk_add_f32 v[154:155], v[154:155], v[158:159] op_sel:[0,1] op_sel_hi:[1,0] neg_lo:[0,1]
	v_pk_add_f32 v[158:159], v[136:137], v[152:153]
	v_pk_add_f32 v[152:153], v[136:137], v[152:153] neg_lo:[0,1] neg_hi:[0,1]
	v_mov_b32_e32 v35, v25
	v_pk_add_f32 v[136:137], v[160:161], v[138:139]
	v_pk_add_f32 v[138:139], v[160:161], v[138:139] neg_lo:[0,1] neg_hi:[0,1]
	v_pk_add_f32 v[160:161], v[156:157], v[132:133]
	v_pk_add_f32 v[156:157], v[156:157], v[132:133] neg_lo:[0,1] neg_hi:[0,1]
	v_mov_b32_e32 v39, v29
	v_pk_add_f32 v[132:133], v[128:129], v[140:141] op_sel:[0,1] op_sel_hi:[1,0] neg_hi:[0,1]
	v_pk_add_f32 v[128:129], v[128:129], v[140:141] op_sel:[0,1] op_sel_hi:[1,0] neg_lo:[0,1]
	v_pk_add_f32 v[140:141], v[130:131], v[134:135]
	v_pk_add_f32 v[134:135], v[130:131], v[134:135] neg_lo:[0,1] neg_hi:[0,1]
	v_mov_b32_e32 v43, v33
	v_pk_add_f32 v[130:131], v[142:143], v[178:179]
	v_pk_add_f32 v[142:143], v[142:143], v[178:179] neg_lo:[0,1] neg_hi:[0,1]
	v_pk_add_f32 v[178:179], v[162:163], v[194:195] op_sel:[0,1] op_sel_hi:[1,0] neg_hi:[0,1]
	v_pk_add_f32 v[162:163], v[162:163], v[194:195] op_sel:[0,1] op_sel_hi:[1,0] neg_lo:[0,1]
	v_pk_add_f32 v[194:195], v[164:165], v[188:189]
	v_pk_add_f32 v[164:165], v[164:165], v[188:189] neg_lo:[0,1] neg_hi:[0,1]
	v_pk_add_f32 v[188:189], v[184:185], v[182:183] op_sel:[0,1] op_sel_hi:[1,0] neg_hi:[0,1]
	v_pk_add_f32 v[182:183], v[184:185], v[182:183] op_sel:[0,1] op_sel_hi:[1,0] neg_lo:[0,1]
	v_pk_add_f32 v[184:185], v[170:171], v[190:191]
	v_pk_add_f32 v[170:171], v[170:171], v[190:191] neg_lo:[0,1] neg_hi:[0,1]
	v_pk_add_f32 v[190:191], v[172:173], v[186:187] op_sel:[0,1] op_sel_hi:[1,0] neg_hi:[0,1]
	v_pk_add_f32 v[172:173], v[172:173], v[186:187] op_sel:[0,1] op_sel_hi:[1,0] neg_lo:[0,1]
	v_pk_add_f32 v[186:187], v[166:167], v[174:175]
	v_pk_add_f32 v[166:167], v[166:167], v[174:175] neg_lo:[0,1] neg_hi:[0,1]
	v_pk_add_f32 v[174:175], v[144:145], v[168:169] op_sel:[0,1] op_sel_hi:[1,0] neg_hi:[0,1]
	v_pk_add_f32 v[144:145], v[144:145], v[168:169] op_sel:[0,1] op_sel_hi:[1,0] neg_lo:[0,1]
	v_pk_add_f32 v[168:169], v[148:149], v[180:181]
	v_pk_add_f32 v[148:149], v[148:149], v[180:181] neg_lo:[0,1] neg_hi:[0,1]
	v_pk_mul_f32 v[2:3], v[2:3], v[168:169] op_sel:[0,1] op_sel_hi:[1,0]
	v_pk_add_f32 v[180:181], v[176:177], v[192:193] op_sel:[0,1] op_sel_hi:[1,0] neg_hi:[0,1]
	v_pk_add_f32 v[176:177], v[176:177], v[192:193] op_sel:[0,1] op_sel_hi:[1,0] neg_lo:[0,1]
	v_pk_add_f32 v[192:193], v[150:151], v[158:159]
	v_pk_add_f32 v[150:151], v[150:151], v[158:159] neg_lo:[0,1] neg_hi:[0,1]
	v_pk_add_f32 v[158:159], v[154:155], v[152:153] op_sel:[0,1] op_sel_hi:[1,0] neg_hi:[0,1]
	v_pk_add_f32 v[152:153], v[154:155], v[152:153] op_sel:[0,1] op_sel_hi:[1,0] neg_lo:[0,1]
	v_pk_add_f32 v[154:155], v[136:137], v[160:161]
	v_pk_fma_f32 v[2:3], v[4:5], v[168:169], v[2:3] op_sel_hi:[0,1,1]
	v_pk_mul_f32 v[4:5], v[6:7], v[184:185] op_sel:[1,1] op_sel_hi:[1,0] neg_lo:[1,0]
	v_mov_b32_e32 v47, v37
	v_pk_fma_f32 v[4:5], v[6:7], v[184:185], v[4:5] op_sel_hi:[0,1,1]
	v_pk_mul_f32 v[6:7], v[8:9], v[154:155] op_sel:[1,1] op_sel_hi:[1,0] neg_lo:[1,0]
	v_pk_add_f32 v[136:137], v[136:137], v[160:161] neg_lo:[0,1] neg_hi:[0,1]
	v_pk_fma_f32 v[6:7], v[8:9], v[154:155], v[6:7] op_sel_hi:[0,1,1]
	v_pk_mul_f32 v[8:9], v[10:11], v[194:195] op_sel:[1,1] op_sel_hi:[1,0] neg_lo:[1,0]
	v_pk_add_f32 v[160:161], v[138:139], v[156:157] op_sel:[0,1] op_sel_hi:[1,0] neg_hi:[0,1]
	v_pk_add_f32 v[138:139], v[138:139], v[156:157] op_sel:[0,1] op_sel_hi:[1,0] neg_lo:[0,1]
	v_pk_add_f32 v[156:157], v[132:133], v[140:141]
	v_pk_fma_f32 v[8:9], v[10:11], v[194:195], v[8:9] op_sel_hi:[0,1,1]
	v_pk_mul_f32 v[10:11], v[26:27], v[192:193] op_sel:[0,1] op_sel_hi:[1,0]
	v_pk_mul_f32 v[12:13], v[30:31], v[186:187] op_sel:[0,1] op_sel_hi:[1,0]
	v_pk_add_f32 v[132:133], v[132:133], v[140:141] neg_lo:[0,1] neg_hi:[0,1]
	v_pk_add_f32 v[140:141], v[128:129], v[134:135] op_sel:[0,1] op_sel_hi:[1,0] neg_hi:[0,1]
	v_pk_fma_f32 v[10:11], v[16:17], v[192:193], v[10:11] op_sel_hi:[0,1,1]
	v_pk_fma_f32 v[12:13], v[20:21], v[186:187], v[12:13] op_sel_hi:[0,1,1]
	v_pk_mul_f32 v[14:15], v[34:35], v[156:157] op_sel:[0,1] op_sel_hi:[1,0]
	v_pk_mul_f32 v[16:17], v[38:39], v[178:179] op_sel:[0,1] op_sel_hi:[1,0]
	v_pk_mul_f32 v[20:21], v[42:43], v[180:181] op_sel:[0,1] op_sel_hi:[1,0]
	v_pk_mul_f32 v[22:23], v[46:47], v[190:191] op_sel:[0,1] op_sel_hi:[1,0]
	v_xor_b32_e32 v78, 0x80000000, v69
	v_xor_b32_e32 v82, 0x80000000, v73
	v_xor_b32_e32 v86, 0x80000000, v77
	v_xor_b32_e32 v90, 0x80000000, v81
	v_xor_b32_e32 v94, 0x80000000, v85
	v_xor_b32_e32 v98, 0x80000000, v89
	v_xor_b32_e32 v102, 0x80000000, v93
	v_xor_b32_e32 v106, 0x80000000, v97
	v_xor_b32_e32 v110, 0x80000000, v101
	v_xor_b32_e32 v114, 0x80000000, v105
	v_xor_b32_e32 v118, 0x80000000, v109
	v_xor_b32_e32 v122, 0x80000000, v113
	v_xor_b32_e32 v124, 0x80000000, v117
	v_xor_b32_e32 v126, 0x80000000, v121
	v_mov_b32_e32 v79, v69
	v_mov_b32_e32 v83, v73
	v_mov_b32_e32 v87, v77
	v_mov_b32_e32 v91, v81
	v_mov_b32_e32 v95, v85
	v_mov_b32_e32 v99, v89
	v_mov_b32_e32 v103, v93
	v_mov_b32_e32 v107, v97
	v_mov_b32_e32 v111, v101
	v_mov_b32_e32 v115, v105
	v_mov_b32_e32 v119, v109
	v_mov_b32_e32 v123, v113
	v_mov_b32_e32 v125, v117
	v_mov_b32_e32 v127, v121
	v_pk_add_f32 v[128:129], v[128:129], v[134:135] op_sel:[0,1] op_sel_hi:[1,0] neg_lo:[0,1]
	v_pk_fma_f32 v[14:15], v[24:25], v[156:157], v[14:15] op_sel_hi:[0,1,1]
	v_pk_fma_f32 v[16:17], v[28:29], v[178:179], v[16:17] op_sel_hi:[0,1,1]
	v_pk_fma_f32 v[20:21], v[32:33], v[180:181], v[20:21] op_sel_hi:[0,1,1]
	v_pk_fma_f32 v[22:23], v[36:37], v[190:191], v[22:23] op_sel_hi:[0,1,1]
	v_pk_mul_f32 v[24:25], v[40:41], v[160:161] op_sel:[1,1] op_sel_hi:[1,0] neg_lo:[1,0]
	v_pk_mul_f32 v[26:27], v[44:45], v[188:189] op_sel:[1,1] op_sel_hi:[1,0] neg_lo:[1,0]
	v_pk_mul_f32 v[28:29], v[48:49], v[158:159] op_sel:[1,1] op_sel_hi:[1,0] neg_lo:[1,0]
	v_pk_mul_f32 v[30:31], v[52:53], v[174:175] op_sel:[1,1] op_sel_hi:[1,0] neg_lo:[1,0]
	v_pk_mul_f32 v[32:33], v[56:57], v[140:141] op_sel:[1,1] op_sel_hi:[1,0] neg_lo:[1,0]
	v_pk_mul_f32 v[34:35], v[60:61], v[142:143] op_sel:[1,1] op_sel_hi:[1,0] neg_lo:[1,0]
	v_pk_mul_f32 v[36:37], v[64:65], v[148:149] op_sel:[1,1] op_sel_hi:[1,0] neg_lo:[1,0]
	v_pk_fma_f32 v[24:25], v[40:41], v[160:161], v[24:25] op_sel_hi:[0,1,1]
	v_pk_fma_f32 v[26:27], v[44:45], v[188:189], v[26:27] op_sel_hi:[0,1,1]
	v_pk_fma_f32 v[28:29], v[48:49], v[158:159], v[28:29] op_sel_hi:[0,1,1]
	v_pk_fma_f32 v[30:31], v[52:53], v[174:175], v[30:31] op_sel_hi:[0,1,1]
	v_pk_fma_f32 v[32:33], v[56:57], v[140:141], v[32:33] op_sel_hi:[0,1,1]
	v_pk_fma_f32 v[34:35], v[60:61], v[142:143], v[34:35] op_sel_hi:[0,1,1]
	v_pk_fma_f32 v[36:37], v[64:65], v[148:149], v[36:37] op_sel_hi:[0,1,1]
	v_pk_mul_f32 v[38:39], v[78:79], v[170:171] op_sel:[0,1] op_sel_hi:[1,0]
	v_pk_mul_f32 v[40:41], v[82:83], v[136:137] op_sel:[0,1] op_sel_hi:[1,0]
	v_pk_mul_f32 v[42:43], v[86:87], v[164:165] op_sel:[0,1] op_sel_hi:[1,0]
	v_pk_mul_f32 v[44:45], v[90:91], v[150:151] op_sel:[0,1] op_sel_hi:[1,0]
	v_pk_mul_f32 v[46:47], v[94:95], v[166:167] op_sel:[0,1] op_sel_hi:[1,0]
	v_pk_mul_f32 v[48:49], v[98:99], v[132:133] op_sel:[0,1] op_sel_hi:[1,0]
	v_pk_mul_f32 v[50:51], v[102:103], v[162:163] op_sel:[0,1] op_sel_hi:[1,0]
	v_pk_mul_f32 v[52:53], v[106:107], v[176:177] op_sel:[0,1] op_sel_hi:[1,0]
	v_pk_mul_f32 v[54:55], v[110:111], v[172:173] op_sel:[0,1] op_sel_hi:[1,0]
	v_pk_mul_f32 v[56:57], v[114:115], v[138:139] op_sel:[0,1] op_sel_hi:[1,0]
	v_pk_mul_f32 v[58:59], v[118:119], v[182:183] op_sel:[0,1] op_sel_hi:[1,0]
	v_pk_mul_f32 v[60:61], v[122:123], v[152:153] op_sel:[0,1] op_sel_hi:[1,0]
	v_pk_mul_f32 v[62:63], v[124:125], v[144:145] op_sel:[0,1] op_sel_hi:[1,0]
	v_pk_mul_f32 v[64:65], v[126:127], v[128:129] op_sel:[0,1] op_sel_hi:[1,0]
	v_pk_fma_f32 v[38:39], v[68:69], v[170:171], v[38:39] op_sel_hi:[0,1,1]
	v_pk_fma_f32 v[40:41], v[72:73], v[136:137], v[40:41] op_sel_hi:[0,1,1]
	v_pk_fma_f32 v[42:43], v[76:77], v[164:165], v[42:43] op_sel_hi:[0,1,1]
	v_pk_fma_f32 v[44:45], v[80:81], v[150:151], v[44:45] op_sel_hi:[0,1,1]
	v_pk_fma_f32 v[46:47], v[84:85], v[166:167], v[46:47] op_sel_hi:[0,1,1]
	v_pk_fma_f32 v[48:49], v[88:89], v[132:133], v[48:49] op_sel_hi:[0,1,1]
	v_pk_fma_f32 v[50:51], v[92:93], v[162:163], v[50:51] op_sel_hi:[0,1,1]
	v_pk_fma_f32 v[52:53], v[96:97], v[176:177], v[52:53] op_sel_hi:[0,1,1]
	v_pk_fma_f32 v[54:55], v[100:101], v[172:173], v[54:55] op_sel_hi:[0,1,1]
	v_pk_fma_f32 v[56:57], v[104:105], v[138:139], v[56:57] op_sel_hi:[0,1,1]
	v_pk_fma_f32 v[58:59], v[108:109], v[182:183], v[58:59] op_sel_hi:[0,1,1]
	v_pk_fma_f32 v[60:61], v[112:113], v[152:153], v[60:61] op_sel_hi:[0,1,1]
	v_pk_fma_f32 v[62:63], v[116:117], v[144:145], v[62:63] op_sel_hi:[0,1,1]
	v_pk_fma_f32 v[64:65], v[120:121], v[128:129], v[64:65] op_sel_hi:[0,1,1]
	ds_write2_b64 v18, v[130:131], v[34:35] offset1:16
	ds_write2_b64 v18, v[16:17], v[50:51] offset0:33 offset1:49
	ds_write2_b64 v18, v[8:9], v[42:43] offset0:66 offset1:82
	ds_write2_b64 v18, v[26:27], v[58:59] offset0:99 offset1:115
	ds_write2_b64 v18, v[4:5], v[38:39] offset0:132 offset1:148
	ds_write2_b64 v18, v[22:23], v[54:55] offset0:165 offset1:181
	ds_write2_b64 v18, v[12:13], v[46:47] offset0:198 offset1:214
	ds_write2_b64 v18, v[30:31], v[62:63] offset0:231 offset1:247
	ds_write2_b64 v196, v[2:3], v[36:37] offset0:8 offset1:24
	ds_write2_b64 v196, v[20:21], v[52:53] offset0:41 offset1:57
	ds_write2_b64 v196, v[10:11], v[44:45] offset0:74 offset1:90
	ds_write2_b64 v196, v[28:29], v[60:61] offset0:107 offset1:123
	ds_write2_b64 v196, v[6:7], v[40:41] offset0:140 offset1:156
	ds_write2_b64 v196, v[24:25], v[56:57] offset0:173 offset1:189
	ds_write2_b64 v196, v[14:15], v[48:49] offset0:206 offset1:222
	ds_write2_b64 v196, v[32:33], v[64:65] offset0:239 offset1:255
	v_ashrrev_i32_e32 v2, 31, v210
	v_lshrrev_b32_e32 v2, 23, v2
	v_add_u32_e32 v2, v210, v2
	s_lshl_b64 s[74:75], s[76:77], 16
	v_and_b32_e32 v2, 0xfffffe00, v2
	s_add_u32 s0, s54, s74
	v_sub_u32_e32 v2, v210, v2
	s_addc_u32 s1, s55, s75
	v_ashrrev_i32_e32 v3, 31, v2
	v_lshl_add_u64 v[14:15], v[2:3], 3, s[0:1]
	v_add_co_u32_e32 v2, vcc, s92, v14
	s_mov_b32 s0, 0x8000
	s_nop 0
	v_addc_co_u32_e32 v3, vcc, 0, v15, vcc
	v_add_co_u32_e32 v4, vcc, s95, v14
	s_waitcnt lgkmcnt(0)
	s_nop 0
	v_addc_co_u32_e32 v5, vcc, 0, v15, vcc
	v_add_co_u32_e32 v8, vcc, s96, v14
	s_barrier
	s_nop 0
	v_addc_co_u32_e32 v9, vcc, 0, v15, vcc
	global_load_dwordx2 v[24:25], v[4:5], off offset:-4096 nt
	global_load_dwordx2 v[12:13], v[4:5], off nt
	global_load_dwordx2 v[6:7], v[8:9], off offset:-4096 nt
	s_nop 0
	global_load_dwordx2 v[4:5], v[8:9], off nt
	v_add_co_u32_e32 v8, vcc, s0, v14
	s_waitcnt vmcnt(3)
	v_cvt_f32_f16_sdwa v174, v24 dst_sel:DWORD dst_unused:UNUSED_PAD src0_sel:WORD_1
	v_addc_co_u32_e32 v9, vcc, 0, v15, vcc
	v_add_co_u32_e32 v10, vcc, s34, v14
	v_cvt_f32_f16_e32 v175, v25
	s_nop 0
	v_addc_co_u32_e32 v11, vcc, 0, v15, vcc
	global_load_dwordx2 v[16:17], v[8:9], off offset:-4096 nt
	global_load_dwordx2 v[122:123], v[8:9], off nt
	global_load_dwordx2 v[46:47], v[10:11], off offset:-4096 nt
	global_load_dwordx2 v[36:37], v[10:11], off nt
	v_add_co_u32_e32 v8, vcc, s35, v14
	v_cvt_f32_f16_sdwa v177, v25 dst_sel:DWORD dst_unused:UNUSED_PAD src0_sel:WORD_1
	s_nop 0
	v_addc_co_u32_e32 v9, vcc, 0, v15, vcc
	v_add_co_u32_e32 v22, vcc, s30, v14
	v_cvt_f32_f16_e32 v176, v24
	s_nop 0
	v_addc_co_u32_e32 v23, vcc, 0, v15, vcc
	global_load_dwordx2 v[26:27], v[8:9], off offset:-4096 nt
	global_load_dwordx2 v[20:21], v[8:9], off nt
	global_load_dwordx2 v[10:11], v[22:23], off offset:-4096 nt
	s_nop 0
	global_load_dwordx2 v[8:9], v[22:23], off nt
	v_add_co_u32_e32 v22, vcc, s31, v14
	s_waitcnt vmcnt(10)
	v_cvt_f32_f16_sdwa v164, v12 dst_sel:DWORD dst_unused:UNUSED_PAD src0_sel:WORD_1
	v_addc_co_u32_e32 v23, vcc, 0, v15, vcc
	global_load_dwordx2 v[30:31], v[2:3], off offset:-4096 nt
	global_load_dwordx2 v[28:29], v[2:3], off nt
	s_nop 0
	global_load_dwordx2 v[2:3], v[22:23], off nt
	global_load_dwordx2 v[32:33], v[14:15], off nt
	v_mov_b32_e32 v14, v210
	v_cvt_f32_f16_e32 v165, v13
	v_ashrrev_i32_e32 v15, 31, v14
	v_lshrrev_b32_e32 v15, 23, v15
	v_add_u32_e32 v15, v14, v15
	v_ashrrev_i32_e32 v15, 9, v15
	v_mul_i32_i24_e32 v18, 0x200, v15
	v_sub_u32_e32 v18, v14, v18
	v_lshlrev_b32_e32 v14, 14, v15
	v_lshlrev_b32_e32 v15, 1, v18
	v_bfrev_b32_e32 v15, v15
	v_lshrrev_b32_e32 v15, 22, v15
	v_sub_u32_e32 v15, 0x400, v15
	v_bfrev_b32_e32 v15, v15
	v_lshrrev_b32_e32 v15, 18, v15
	v_and_b32_e32 v15, 0x3ff0, v15
	v_cmp_eq_u32_e64 s[0:1], 0, v18
	v_lshl_add_u32 v22, v18, 5, v14
	v_lshl_add_u32 v23, v22, 3, 0
	v_cndmask_b32_e64 v15, v15, 16, s[0:1]
	v_or_b32_e32 v14, v15, v14
	v_ashrrev_i32_e32 v22, 2, v22
	v_ashrrev_i32_e32 v15, 5, v14
	v_add_u32_e32 v211, v23, v22
	v_lshlrev_b32_e32 v14, 3, v14
	v_lshlrev_b32_e32 v15, 3, v15
	v_add3_u32 v212, 0, v14, v15
	ds_read2_b64 v[38:41], v211 offset1:1
	ds_read2_b64 v[42:45], v211 offset0:2 offset1:3
	ds_read2_b64 v[48:51], v212 offset1:1
	ds_read2_b64 v[52:55], v212 offset0:2 offset1:3
	ds_read2_b64 v[56:59], v211 offset0:4 offset1:5
	ds_read2_b64 v[60:63], v211 offset0:6 offset1:7
	ds_read2_b64 v[68:71], v212 offset0:4 offset1:5
	ds_read2_b64 v[72:75], v212 offset0:6 offset1:7
	ds_read2_b64 v[64:67], v211 offset0:8 offset1:9
	ds_read2_b64 v[76:79], v211 offset0:10 offset1:11
	ds_read2_b64 v[80:83], v212 offset0:8 offset1:9
	ds_read2_b64 v[98:101], v212 offset0:10 offset1:11
	ds_read2_b64 v[84:87], v211 offset0:12 offset1:13
	ds_read2_b64 v[88:91], v211 offset0:14 offset1:15
	ds_read2_b64 v[102:105], v212 offset0:12 offset1:13
	ds_read2_b64 v[106:109], v212 offset0:14 offset1:15
	s_waitcnt lgkmcnt(7)
	v_pk_add_f32 v[14:15], v[38:39], v[64:65]
	v_pk_add_f32 v[22:23], v[38:39], v[64:65] neg_lo:[0,1] neg_hi:[0,1]
	v_pk_add_f32 v[38:39], v[40:41], v[66:67] neg_lo:[0,1] neg_hi:[0,1]
	v_pk_add_f32 v[34:35], v[40:41], v[66:67]
	v_pk_mul_f32 v[40:41], v[38:39], s[18:19]
	v_cmp_ne_u32_e32 vcc, 0, v18
	v_pk_fma_f32 v[38:39], v[38:39], s[16:17], v[40:41] op_sel:[0,0,1] op_sel_hi:[1,0,0]
	s_waitcnt lgkmcnt(6)
	v_pk_add_f32 v[40:41], v[42:43], v[76:77]
	v_pk_add_f32 v[42:43], v[42:43], v[76:77] neg_lo:[0,1] neg_hi:[0,1]
	v_bfrev_b32_e32 v18, v18
	v_pk_mul_f32 v[64:65], v[42:43], s[36:37]
	v_lshrrev_b32_e32 v18, 23, v18
	v_pk_fma_f32 v[42:43], v[42:43], s[78:79], v[64:65] op_sel:[0,0,1] op_sel_hi:[1,0,0]
	v_pk_add_f32 v[64:65], v[44:45], v[78:79]
	v_pk_add_f32 v[44:45], v[44:45], v[78:79] neg_lo:[0,1] neg_hi:[0,1]
	s_waitcnt lgkmcnt(3)
	v_pk_add_f32 v[78:79], v[58:59], v[86:87]
	v_pk_mul_f32 v[66:67], v[44:45], s[40:41]
	v_pk_add_f32 v[58:59], v[58:59], v[86:87] neg_lo:[0,1] neg_hi:[0,1]
	v_pk_fma_f32 v[44:45], v[44:45], s[80:81], v[66:67] op_sel:[0,0,1] op_sel_hi:[1,0,0]
	v_pk_add_f32 v[66:67], v[56:57], v[84:85]
	v_pk_add_f32 v[76:77], v[56:57], v[84:85] neg_lo:[0,1] neg_hi:[0,1]
	v_pk_mul_f32 v[84:85], v[58:59], s[40:41]
	v_pk_fma_f32 v[58:59], v[58:59], s[80:81], v[84:85] op_sel:[0,0,1] op_sel_hi:[1,0,0] neg_lo:[1,0,0] neg_hi:[1,0,0]
	s_waitcnt lgkmcnt(2)
	v_pk_add_f32 v[84:85], v[60:61], v[88:89]
	v_pk_add_f32 v[60:61], v[60:61], v[88:89] neg_lo:[0,1] neg_hi:[0,1]
	v_pk_mul_f32 v[86:87], v[60:61], s[36:37]
	v_pk_add_f32 v[56:57], v[22:23], v[76:77] op_sel:[0,1] op_sel_hi:[1,0] neg_hi:[0,1]
	v_pk_fma_f32 v[60:61], v[60:61], s[78:79], v[86:87] op_sel:[0,0,1] op_sel_hi:[1,0,0] neg_lo:[1,0,0] neg_hi:[1,0,0]
	v_pk_add_f32 v[86:87], v[62:63], v[90:91]
	v_pk_add_f32 v[62:63], v[62:63], v[90:91] neg_lo:[0,1] neg_hi:[0,1]
	v_pk_add_f32 v[90:91], v[64:65], v[86:87]
	v_pk_mul_f32 v[88:89], v[62:63], s[18:19]
	v_pk_add_f32 v[64:65], v[64:65], v[86:87] neg_lo:[0,1] neg_hi:[0,1]
	v_pk_fma_f32 v[62:63], v[62:63], s[16:17], v[88:89] op_sel:[0,0,1] op_sel_hi:[1,0,0] neg_lo:[1,0,0] neg_hi:[1,0,0]
	v_pk_add_f32 v[88:89], v[14:15], v[66:67]
	v_pk_add_f32 v[14:15], v[14:15], v[66:67] neg_lo:[0,1] neg_hi:[0,1]
	v_pk_add_f32 v[66:67], v[34:35], v[78:79]
	v_pk_add_f32 v[34:35], v[34:35], v[78:79] neg_lo:[0,1] neg_hi:[0,1]
	v_pk_add_f32 v[22:23], v[22:23], v[76:77] op_sel:[0,1] op_sel_hi:[1,0] neg_lo:[0,1]
	v_pk_mul_f32 v[78:79], v[34:35], s[36:37]
	v_pk_add_f32 v[76:77], v[38:39], v[58:59]
	v_pk_add_f32 v[38:39], v[38:39], v[58:59] neg_lo:[0,1] neg_hi:[0,1]
	v_pk_fma_f32 v[34:35], v[34:35], s[78:79], v[78:79] op_sel:[0,0,1] op_sel_hi:[1,0,0]
	v_pk_add_f32 v[78:79], v[40:41], v[84:85]
	v_pk_add_f32 v[84:85], v[40:41], v[84:85] neg_lo:[0,1] neg_hi:[0,1]
	v_pk_mul_f32 v[86:87], v[64:65], s[36:37]
	v_pk_mul_f32 v[58:59], v[38:39], s[36:37]
	v_pk_fma_f32 v[64:65], v[64:65], s[78:79], v[86:87] op_sel:[0,0,1] op_sel_hi:[1,0,0] neg_lo:[1,0,0] neg_hi:[1,0,0]
	v_pk_fma_f32 v[38:39], v[38:39], s[78:79], v[58:59] op_sel:[0,0,1] op_sel_hi:[1,0,0]
	v_pk_add_f32 v[58:59], v[42:43], v[60:61]
	v_pk_add_f32 v[86:87], v[44:45], v[62:63]
	v_pk_add_f32 v[44:45], v[44:45], v[62:63] neg_lo:[0,1] neg_hi:[0,1]
	v_pk_mul_f32 v[62:63], v[44:45], s[36:37]
	v_pk_add_f32 v[40:41], v[14:15], v[84:85] op_sel:[0,1] op_sel_hi:[1,0] neg_hi:[0,1]
	v_pk_add_f32 v[14:15], v[14:15], v[84:85] op_sel:[0,1] op_sel_hi:[1,0] neg_lo:[0,1]
	v_pk_add_f32 v[84:85], v[34:35], v[64:65]
	v_pk_add_f32 v[64:65], v[34:35], v[64:65] neg_lo:[0,1] neg_hi:[0,1]
	v_pk_add_f32 v[94:95], v[56:57], v[58:59]
	v_pk_add_f32 v[56:57], v[56:57], v[58:59] neg_lo:[0,1] neg_hi:[0,1]
	v_pk_add_f32 v[58:59], v[76:77], v[86:87]
	v_pk_fma_f32 v[44:45], v[44:45], s[78:79], v[62:63] op_sel:[0,0,1] op_sel_hi:[1,0,0] neg_lo:[1,0,0] neg_hi:[1,0,0]
	v_pk_add_f32 v[62:63], v[88:89], v[78:79]
	v_pk_add_f32 v[78:79], v[88:89], v[78:79] neg_lo:[0,1] neg_hi:[0,1]
	v_pk_add_f32 v[88:89], v[66:67], v[90:91]
	v_pk_add_f32 v[110:111], v[76:77], v[86:87] neg_lo:[0,1] neg_hi:[0,1]
	v_pk_add_f32 v[86:87], v[94:95], v[58:59]
	v_pk_add_f32 v[34:35], v[94:95], v[58:59] neg_lo:[0,1] neg_hi:[0,1]
	v_pk_add_f32 v[58:59], v[50:51], v[82:83]
	v_pk_add_f32 v[50:51], v[50:51], v[82:83] neg_lo:[0,1] neg_hi:[0,1]
	v_pk_add_f32 v[60:61], v[42:43], v[60:61] neg_lo:[0,1] neg_hi:[0,1]
	v_pk_add_f32 v[148:149], v[62:63], v[88:89]
	v_pk_add_f32 v[138:139], v[62:63], v[88:89] neg_lo:[0,1] neg_hi:[0,1]
	v_pk_mul_f32 v[62:63], v[50:51], s[18:19]
	v_pk_add_f32 v[90:91], v[66:67], v[90:91] neg_lo:[0,1] neg_hi:[0,1]
	v_pk_fma_f32 v[50:51], v[50:51], s[16:17], v[62:63] op_sel:[0,0,1] op_sel_hi:[1,0,0]
	v_pk_add_f32 v[62:63], v[52:53], v[98:99]
	v_pk_add_f32 v[52:53], v[52:53], v[98:99] neg_lo:[0,1] neg_hi:[0,1]
	v_pk_add_f32 v[112:113], v[22:23], v[60:61] op_sel:[0,1] op_sel_hi:[1,0] neg_hi:[0,1]
	v_pk_add_f32 v[114:115], v[22:23], v[60:61] op_sel:[0,1] op_sel_hi:[1,0] neg_lo:[0,1]
	v_pk_add_f32 v[96:97], v[40:41], v[84:85]
	v_pk_add_f32 v[66:67], v[40:41], v[84:85] neg_lo:[0,1] neg_hi:[0,1]
	v_pk_add_f32 v[60:61], v[14:15], v[64:65] op_sel:[0,1] op_sel_hi:[1,0] neg_hi:[0,1]
	v_pk_add_f32 v[84:85], v[14:15], v[64:65] op_sel:[0,1] op_sel_hi:[1,0] neg_lo:[0,1]
	v_pk_mul_f32 v[64:65], v[52:53], s[36:37]
	v_pk_fma_f32 v[52:53], v[52:53], s[78:79], v[64:65] op_sel:[0,0,1] op_sel_hi:[1,0,0]
	v_pk_add_f32 v[64:65], v[54:55], v[100:101]
	v_pk_add_f32 v[54:55], v[54:55], v[100:101] neg_lo:[0,1] neg_hi:[0,1]
	v_pk_mul_f32 v[76:77], v[54:55], s[40:41]
	v_pk_add_f32 v[92:93], v[78:79], v[90:91] op_sel:[0,1] op_sel_hi:[1,0] neg_hi:[0,1]
	v_pk_fma_f32 v[54:55], v[54:55], s[80:81], v[76:77] op_sel:[0,0,1] op_sel_hi:[1,0,0]
	s_waitcnt lgkmcnt(1)
	v_pk_add_f32 v[76:77], v[68:69], v[102:103]
	v_pk_add_f32 v[68:69], v[68:69], v[102:103] neg_lo:[0,1] neg_hi:[0,1]
	v_pk_add_f32 v[88:89], v[78:79], v[90:91] op_sel:[0,1] op_sel_hi:[1,0] neg_lo:[0,1]
	v_xor_b32_e32 v79, 0x80000000, v68
	v_mov_b32_e32 v78, v69
	v_pk_add_f32 v[68:69], v[70:71], v[104:105]
	v_pk_add_f32 v[70:71], v[70:71], v[104:105] neg_lo:[0,1] neg_hi:[0,1]
	v_pk_add_f32 v[22:23], v[38:39], v[44:45]
	v_pk_add_f32 v[116:117], v[38:39], v[44:45] neg_lo:[0,1] neg_hi:[0,1]
	v_pk_add_f32 v[40:41], v[56:57], v[110:111] op_sel:[0,1] op_sel_hi:[1,0] neg_hi:[0,1]
	v_pk_add_f32 v[44:45], v[56:57], v[110:111] op_sel:[0,1] op_sel_hi:[1,0] neg_lo:[0,1]
	v_pk_add_f32 v[56:57], v[48:49], v[80:81]
	v_pk_add_f32 v[48:49], v[48:49], v[80:81] neg_lo:[0,1] neg_hi:[0,1]
	v_pk_mul_f32 v[80:81], v[70:71], s[40:41]
	v_cvt_f32_u32_e32 v18, v18
	v_pk_fma_f32 v[70:71], v[70:71], s[80:81], v[80:81] op_sel:[0,0,1] op_sel_hi:[1,0,0] neg_lo:[1,0,0] neg_hi:[1,0,0]
	s_waitcnt lgkmcnt(0)
	v_pk_add_f32 v[80:81], v[72:73], v[106:107]
	v_pk_add_f32 v[72:73], v[72:73], v[106:107] neg_lo:[0,1] neg_hi:[0,1]
	v_mul_f32_e32 v18, 0x38000000, v18
	v_pk_mul_f32 v[82:83], v[72:73], s[36:37]
	v_cndmask_b32_e64 v18, v18, v208, s[0:1]
	v_pk_fma_f32 v[72:73], v[72:73], s[78:79], v[82:83] op_sel:[0,0,1] op_sel_hi:[1,0,0] neg_lo:[1,0,0] neg_hi:[1,0,0]
	v_pk_add_f32 v[82:83], v[74:75], v[108:109]
	v_pk_add_f32 v[74:75], v[74:75], v[108:109] neg_lo:[0,1] neg_hi:[0,1]
	s_nop 0
	v_pk_mul_f32 v[90:91], v[74:75], s[18:19]
	v_pk_fma_f32 v[74:75], v[74:75], s[16:17], v[90:91] op_sel:[0,0,1] op_sel_hi:[1,0,0] neg_lo:[1,0,0] neg_hi:[1,0,0]
	v_pk_add_f32 v[90:91], v[56:57], v[76:77]
	v_pk_add_f32 v[56:57], v[56:57], v[76:77] neg_lo:[0,1] neg_hi:[0,1]
	v_pk_add_f32 v[76:77], v[58:59], v[68:69]
	v_pk_add_f32 v[58:59], v[58:59], v[68:69] neg_lo:[0,1] neg_hi:[0,1]
	v_pk_add_f32 v[14:15], v[114:115], v[116:117] op_sel:[0,1] op_sel_hi:[1,0] neg_hi:[0,1]
	v_pk_mul_f32 v[68:69], v[58:59], s[36:37]
	v_pk_add_f32 v[38:39], v[114:115], v[116:117] op_sel:[0,1] op_sel_hi:[1,0] neg_lo:[0,1]
	v_pk_fma_f32 v[58:59], v[58:59], s[78:79], v[68:69] op_sel:[0,0,1] op_sel_hi:[1,0,0]
	v_pk_add_f32 v[68:69], v[62:63], v[80:81]
	v_pk_add_f32 v[80:81], v[62:63], v[80:81] neg_lo:[0,1] neg_hi:[0,1]
	s_waitcnt vmcnt(0)
	v_cvt_f32_f16_e32 v193, v33
	s_nop 0
	s_nop 0
	v_pk_add_f32 v[62:63], v[64:65], v[82:83]
	v_pk_add_f32 v[64:65], v[64:65], v[82:83] neg_lo:[0,1] neg_hi:[0,1]
	v_cvt_f32_f16_sdwa v192, v32 dst_sel:DWORD dst_unused:UNUSED_PAD src0_sel:WORD_1
	v_pk_mul_f32 v[82:83], v[64:65], s[36:37]
	v_cvt_f32_f16_e32 v194, v32
	v_pk_fma_f32 v[64:65], v[64:65], s[78:79], v[82:83] op_sel:[0,0,1] op_sel_hi:[1,0,0] neg_lo:[1,0,0] neg_hi:[1,0,0]
	v_pk_add_f32 v[82:83], v[48:49], v[78:79]
	v_pk_add_f32 v[48:49], v[48:49], v[78:79] neg_lo:[0,1] neg_hi:[0,1]
	v_pk_add_f32 v[78:79], v[50:51], v[70:71]
	v_pk_add_f32 v[50:51], v[50:51], v[70:71] neg_lo:[0,1] neg_hi:[0,1]
	v_cvt_f32_f16_sdwa v195, v33 dst_sel:DWORD dst_unused:UNUSED_PAD src0_sel:WORD_1
	v_pk_mul_f32 v[70:71], v[50:51], s[36:37]
	v_cvt_f32_f16_sdwa v170, v30 dst_sel:DWORD dst_unused:UNUSED_PAD src0_sel:WORD_1
	v_pk_fma_f32 v[50:51], v[50:51], s[78:79], v[70:71] op_sel:[0,0,1] op_sel_hi:[1,0,0]
	v_pk_add_f32 v[70:71], v[52:53], v[72:73]
	v_pk_add_f32 v[72:73], v[52:53], v[72:73] neg_lo:[0,1] neg_hi:[0,1]
	v_cvt_f32_f16_e32 v171, v31
	s_nop 0
	s_nop 0
	v_pk_add_f32 v[52:53], v[54:55], v[74:75]
	v_pk_add_f32 v[54:55], v[54:55], v[74:75] neg_lo:[0,1] neg_hi:[0,1]
	v_cvt_f32_f16_sdwa v185, v31 dst_sel:DWORD dst_unused:UNUSED_PAD src0_sel:WORD_1
	v_pk_mul_f32 v[74:75], v[54:55], s[36:37]
	v_cvt_f32_f16_e32 v184, v30
	v_pk_fma_f32 v[54:55], v[54:55], s[78:79], v[74:75] op_sel:[0,0,1] op_sel_hi:[1,0,0] neg_lo:[1,0,0] neg_hi:[1,0,0]
	v_pk_add_f32 v[74:75], v[90:91], v[68:69]
	v_pk_add_f32 v[68:69], v[90:91], v[68:69] neg_lo:[0,1] neg_hi:[0,1]
	v_pk_add_f32 v[90:91], v[76:77], v[62:63]
	v_pk_add_f32 v[62:63], v[76:77], v[62:63] neg_lo:[0,1] neg_hi:[0,1]
	v_cvt_f32_f16_sdwa v172, v28 dst_sel:DWORD dst_unused:UNUSED_PAD src0_sel:WORD_1
	v_xor_b32_e32 v77, 0x80000000, v62
	v_mov_b32_e32 v76, v63
	v_pk_add_f32 v[62:63], v[56:57], v[80:81] op_sel:[0,1] op_sel_hi:[1,0] neg_hi:[0,1]
	v_pk_add_f32 v[56:57], v[56:57], v[80:81] op_sel:[0,1] op_sel_hi:[1,0] neg_lo:[0,1]
	v_pk_add_f32 v[80:81], v[58:59], v[64:65]
	v_pk_add_f32 v[58:59], v[58:59], v[64:65] neg_lo:[0,1] neg_hi:[0,1]
	v_cvt_f32_f16_e32 v173, v29
	v_xor_b32_e32 v65, 0x80000000, v58
	v_mov_b32_e32 v64, v59
	v_pk_add_f32 v[58:59], v[82:83], v[70:71]
	v_pk_add_f32 v[70:71], v[82:83], v[70:71] neg_lo:[0,1] neg_hi:[0,1]
	v_pk_add_f32 v[82:83], v[78:79], v[52:53]
	v_pk_add_f32 v[52:53], v[78:79], v[52:53] neg_lo:[0,1] neg_hi:[0,1]
	v_pk_add_f32 v[118:119], v[58:59], v[82:83]
	v_pk_add_f32 v[134:135], v[58:59], v[82:83] neg_lo:[0,1] neg_hi:[0,1]
	v_cos_f32_e32 v83, v18
	v_sin_f32_e32 v82, v18
	v_cvt_f32_f16_sdwa v181, v29 dst_sel:DWORD dst_unused:UNUSED_PAD src0_sel:WORD_1
	v_cvt_f32_f16_e32 v180, v28
	v_cvt_f32_f16_sdwa v167, v13 dst_sel:DWORD dst_unused:UNUSED_PAD src0_sel:WORD_1
	v_cvt_f32_f16_e32 v166, v12
	v_cvt_f32_f16_e32 v154, v6
	v_cvt_f32_f16_e32 v155, v7
	v_cvt_f32_f16_sdwa v157, v7 dst_sel:DWORD dst_unused:UNUSED_PAD src0_sel:WORD_1
	v_cvt_f32_f16_sdwa v156, v6 dst_sel:DWORD dst_unused:UNUSED_PAD src0_sel:WORD_1
	v_cvt_f32_f16_sdwa v140, v4 dst_sel:DWORD dst_unused:UNUSED_PAD src0_sel:WORD_1
	v_cvt_f32_f16_e32 v141, v5
	v_cvt_f32_f16_sdwa v143, v5 dst_sel:DWORD dst_unused:UNUSED_PAD src0_sel:WORD_1
	v_cvt_f32_f16_e32 v142, v4
	v_cvt_f32_f16_e32 v124, v16
	v_cvt_f32_f16_e32 v125, v17
	v_cvt_f32_f16_sdwa v127, v17 dst_sel:DWORD dst_unused:UNUSED_PAD src0_sel:WORD_1
	v_cvt_f32_f16_sdwa v126, v16 dst_sel:DWORD dst_unused:UNUSED_PAD src0_sel:WORD_1
	v_cvt_f32_f16_sdwa v114, v122 dst_sel:DWORD dst_unused:UNUSED_PAD src0_sel:WORD_1
	v_cvt_f32_f16_e32 v115, v123
	v_cvt_f32_f16_sdwa v117, v123 dst_sel:DWORD dst_unused:UNUSED_PAD src0_sel:WORD_1
	v_cvt_f32_f16_e32 v116, v122
	v_xor_b32_e32 v79, 0x80000000, v52
	v_mov_b32_e32 v78, v53
	v_pk_add_f32 v[52:53], v[48:49], v[72:73] op_sel:[0,1] op_sel_hi:[1,0] neg_hi:[0,1]
	v_pk_add_f32 v[48:49], v[48:49], v[72:73] op_sel:[0,1] op_sel_hi:[1,0] neg_lo:[0,1]
	v_pk_add_f32 v[72:73], v[50:51], v[54:55]
	v_pk_add_f32 v[50:51], v[50:51], v[54:55] neg_lo:[0,1] neg_hi:[0,1]
	v_pk_fma_f32 v[160:161], v[82:83], 0, v[82:83] op_sel:[0,0,1] op_sel_hi:[1,0,0] neg_lo:[1,0,0] neg_hi:[1,0,0]
	v_xor_b32_e32 v55, 0x80000000, v50
	v_mov_b32_e32 v54, v51
	v_pk_fma_f32 v[198:199], v[82:83], 0, v[82:83] op_sel:[0,0,1] op_sel_hi:[1,0,0]
	v_pk_add_f32 v[42:43], v[112:113], v[22:23]
	v_pk_add_f32 v[22:23], v[112:113], v[22:23] neg_lo:[0,1] neg_hi:[0,1]
	v_pk_add_f32 v[98:99], v[74:75], v[90:91]
	v_pk_add_f32 v[100:101], v[74:75], v[90:91] neg_lo:[0,1] neg_hi:[0,1]
	v_pk_add_f32 v[102:103], v[68:69], v[76:77]
	v_pk_add_f32 v[106:107], v[68:69], v[76:77] neg_lo:[0,1] neg_hi:[0,1]
	v_pk_add_f32 v[104:105], v[62:63], v[80:81]
	v_pk_add_f32 v[108:109], v[62:63], v[80:81] neg_lo:[0,1] neg_hi:[0,1]
	v_pk_add_f32 v[110:111], v[56:57], v[64:65]
	v_pk_add_f32 v[112:113], v[56:57], v[64:65] neg_lo:[0,1] neg_hi:[0,1]
	v_pk_add_f32 v[152:153], v[70:71], v[78:79]
	v_pk_add_f32 v[162:163], v[70:71], v[78:79] neg_lo:[0,1] neg_hi:[0,1]
	v_pk_add_f32 v[178:179], v[52:53], v[72:73]
	v_pk_add_f32 v[182:183], v[52:53], v[72:73] neg_lo:[0,1] neg_hi:[0,1]
	v_pk_add_f32 v[188:189], v[48:49], v[54:55]
	v_pk_add_f32 v[196:197], v[48:49], v[54:55] neg_lo:[0,1] neg_hi:[0,1]
	v_pk_mul_f32 v[186:187], v[82:83], 0 op_sel_hi:[1,0]
	v_mov_b32_e32 v190, v160
	v_mov_b32_e32 v191, v199
	v_mul_f32_e32 v18, 0x3f3504f3, v83
	v_mul_f32_e32 v158, 0xbec3ef15, v83
	v_mul_f32_e32 v132, 0xbf6c835e, v83
	s_and_saveexec_b64 s[0:1], vcc
	s_xor_b64 s[0:1], exec, s[0:1]
	s_cbranch_execz .LBB0_501
	v_pk_add_f32 v[4:5], v[148:149], v[196:197]
	v_pk_add_f32 v[6:7], v[148:149], v[196:197] neg_lo:[0,1] neg_hi:[0,1]
	v_mul_f32_e32 v4, 0.5, v4
	v_mul_f32_e32 v12, 0.5, v7
	v_mov_b32_e32 v7, v5
	v_pk_mul_f32 v[6:7], v[6:7], s[44:45]
	v_pk_mov_b32 v[16:17], v[198:199], v[160:161] op_sel:[1,0]
	v_pk_mul_f32 v[24:25], v[190:191], v[6:7] op_sel:[0,1] op_sel_hi:[1,0]
	v_pk_mul_f32 v[6:7], v[190:191], v[6:7]
	v_pk_add_f32 v[24:25], v[24:25], v[24:25] op_sel:[0,1] op_sel_hi:[0,1]
	v_pk_add_f32 v[28:29], v[4:5], v[24:25] op_sel_hi:[0,1] neg_hi:[0,1]
	v_pk_add_f32 v[4:5], v[6:7], v[6:7] op_sel:[0,1] op_sel_hi:[0,1] neg_lo:[0,1] neg_hi:[0,1]
	v_pk_add_f32 v[6:7], v[12:13], v[4:5] op_sel_hi:[0,1] neg_hi:[0,1]
	v_pk_mul_f32 v[4:5], v[6:7], v[194:195]
	v_pk_mul_f32 v[6:7], v[6:7], v[192:193]
	v_pk_fma_f32 v[4:5], v[28:29], v[192:193], v[4:5]
	v_pk_fma_f32 v[6:7], v[28:29], v[194:195], v[6:7] neg_lo:[0,0,1] neg_hi:[0,0,1]
	s_mov_b32 s78, s19
	v_pk_add_f32 v[12:13], v[6:7], v[4:5] op_sel:[0,1] op_sel_hi:[1,0] neg_lo:[0,1]
	v_pk_add_f32 v[28:29], v[6:7], v[4:5] op_sel:[0,1] op_sel_hi:[1,0]
	v_pk_add_f32 v[4:5], v[4:5], v[6:7] op_sel:[1,0] op_sel_hi:[0,1] neg_lo:[0,1] neg_hi:[0,1]
	s_nop 0
	v_pk_mul_f32 v[12:13], v[12:13], 0.5 op_sel_hi:[1,0]
	v_mov_b32_e32 v29, v5
	v_mul_f32_e32 v24, v190, v12
	v_pk_fma_f32 v[30:31], v[190:191], v[12:13], v[24:25] op_sel_hi:[1,1,0] neg_lo:[1,0,0] neg_hi:[1,0,0]
	v_mul_f32_e32 v24, v160, v13
	v_pk_fma_f32 v[12:13], v[16:17], v[12:13], v[24:25] op_sel_hi:[1,1,0]
	v_mov_b32_e32 v16, v83
	v_mov_b32_e32 v30, v12
	v_pk_fma_f32 v[4:5], v[28:29], 0.5, v[12:13] op_sel_hi:[1,0,1] neg_lo:[0,0,1] neg_hi:[0,0,1]
	v_pk_fma_f32 v[122:123], v[28:29], 0.5, v[30:31] op_sel_hi:[1,0,1]
	v_pk_fma_f32 v[6:7], v[28:29], 0.5, v[30:31] op_sel_hi:[1,0,1] neg_lo:[1,0,0] neg_hi:[1,0,0]
	v_mov_b32_e32 v5, v123
	v_pk_mul_f32 v[24:25], v[4:5], s[6:7] op_sel_hi:[1,0]
	v_pk_add_f32 v[4:5], v[138:139], v[188:189]
	v_pk_add_f32 v[12:13], v[138:139], v[188:189] neg_lo:[0,1] neg_hi:[0,1]
	v_mov_b32_e32 v17, v82
	v_mul_f32_e32 v6, 0.5, v13
	v_pk_add_f32 v[28:29], v[186:187], v[16:17] neg_lo:[0,1] neg_hi:[0,1]
	v_pk_add_f32 v[30:31], v[186:187], v[16:17]
	v_mov_b32_e32 v13, v5
	v_pk_mov_b32 v[32:33], v[28:29], v[30:31] op_sel:[1,0]
	v_pk_mul_f32 v[12:13], v[12:13], s[44:45]
	v_mul_f32_e32 v4, 0.5, v4
	v_pk_mul_f32 v[48:49], v[32:33], v[12:13] op_sel:[0,1] op_sel_hi:[1,0]
	v_pk_mul_f32 v[12:13], v[32:33], v[12:13]
	v_pk_add_f32 v[48:49], v[48:49], v[48:49] op_sel:[0,1] op_sel_hi:[0,1]
	v_pk_add_f32 v[50:51], v[4:5], v[48:49] op_sel_hi:[0,1] neg_hi:[0,1]
	v_pk_add_f32 v[4:5], v[12:13], v[12:13] op_sel:[0,1] op_sel_hi:[0,1] neg_lo:[0,1] neg_hi:[0,1]
	v_pk_add_f32 v[12:13], v[6:7], v[4:5] op_sel_hi:[0,1] neg_hi:[0,1]
	v_pk_mul_f32 v[4:5], v[12:13], v[184:185]
	v_pk_mul_f32 v[12:13], v[12:13], v[170:171]
	v_pk_fma_f32 v[4:5], v[50:51], v[170:171], v[4:5]
	v_pk_fma_f32 v[12:13], v[50:51], v[184:185], v[12:13] neg_lo:[0,0,1] neg_hi:[0,0,1]
	v_mov_b32_e32 v31, v29
	v_pk_add_f32 v[48:49], v[12:13], v[4:5] op_sel:[0,1] op_sel_hi:[1,0] neg_lo:[0,1]
	v_pk_add_f32 v[50:51], v[12:13], v[4:5] op_sel:[0,1] op_sel_hi:[1,0]
	v_pk_add_f32 v[4:5], v[4:5], v[12:13] op_sel:[1,0] op_sel_hi:[0,1] neg_lo:[0,1] neg_hi:[0,1]
	v_pk_mul_f32 v[48:49], v[48:49], 0.5 op_sel_hi:[1,0]
	v_mov_b32_e32 v51, v5
	v_mul_f32_e32 v6, v29, v48
	v_pk_fma_f32 v[32:33], v[32:33], v[48:49], v[6:7] op_sel_hi:[1,1,0] neg_lo:[1,0,0] neg_hi:[1,0,0]
	v_mul_f32_e32 v6, v29, v49
	v_pk_fma_f32 v[28:29], v[30:31], v[48:49], v[6:7] op_sel_hi:[1,1,0]
	v_pk_mul_f32 v[12:13], v[16:17], s[36:37]
	v_mov_b32_e32 v32, v28
	v_pk_fma_f32 v[4:5], v[50:51], 0.5, v[28:29] op_sel_hi:[1,0,1] neg_lo:[0,0,1] neg_hi:[0,0,1]
	v_pk_fma_f32 v[138:139], v[50:51], 0.5, v[32:33] op_sel_hi:[1,0,1]
	v_pk_add_f32 v[16:17], v[92:93], v[182:183]
	v_mov_b32_e32 v5, v139
	v_pk_add_f32 v[28:29], v[92:93], v[182:183] neg_lo:[0,1] neg_hi:[0,1]
	v_pk_mul_f32 v[30:31], v[4:5], s[6:7] op_sel_hi:[1,0]
	v_pk_fma_f32 v[4:5], v[50:51], 0.5, v[32:33] op_sel_hi:[1,0,1] neg_lo:[1,0,0] neg_hi:[1,0,0]
	v_mul_f32_e32 v6, 0.5, v29
	v_pk_add_f32 v[32:33], v[18:19], v[12:13] op_sel:[0,1] op_sel_hi:[0,1] neg_lo:[0,1] neg_hi:[0,1]
	v_pk_add_f32 v[48:49], v[18:19], v[12:13] op_sel:[0,1] op_sel_hi:[0,1]
	v_mov_b32_e32 v29, v17
	v_mul_f32_e32 v4, 0.5, v16
	v_mov_b32_e32 v50, v32
	v_mov_b32_e32 v51, v49
	v_pk_mul_f32 v[16:17], v[28:29], s[44:45]
	v_pk_mov_b32 v[48:49], v[48:49], v[32:33] op_sel:[1,0]
	v_pk_mul_f32 v[28:29], v[50:51], v[16:17] op_sel:[0,1] op_sel_hi:[1,0]
	v_pk_mul_f32 v[16:17], v[50:51], v[16:17]
	v_pk_add_f32 v[28:29], v[28:29], v[28:29] op_sel:[0,1] op_sel_hi:[0,1]
	v_pk_add_f32 v[52:53], v[4:5], v[28:29] op_sel_hi:[0,1] neg_hi:[0,1]
	v_pk_add_f32 v[16:17], v[16:17], v[16:17] op_sel:[0,1] op_sel_hi:[0,1] neg_lo:[0,1] neg_hi:[0,1]
	v_pk_add_f32 v[28:29], v[6:7], v[16:17] op_sel_hi:[0,1] neg_hi:[0,1]
	v_pk_mul_f32 v[16:17], v[28:29], v[180:181]
	v_pk_mul_f32 v[28:29], v[28:29], v[172:173]
	v_pk_fma_f32 v[16:17], v[52:53], v[172:173], v[16:17]
	v_pk_fma_f32 v[28:29], v[52:53], v[180:181], v[28:29] neg_lo:[0,0,1] neg_hi:[0,0,1]
	v_sub_f32_e32 v6, v89, v179
	v_pk_add_f32 v[52:53], v[28:29], v[16:17] op_sel:[0,1] op_sel_hi:[1,0] neg_lo:[0,1]
	v_pk_add_f32 v[54:55], v[28:29], v[16:17] op_sel:[0,1] op_sel_hi:[1,0]
	v_pk_add_f32 v[16:17], v[16:17], v[28:29] op_sel:[1,0] op_sel_hi:[0,1] neg_lo:[0,1] neg_hi:[0,1]
	v_pk_mul_f32 v[52:53], v[52:53], 0.5 op_sel_hi:[1,0]
	v_mov_b32_e32 v55, v17
	v_mul_f32_e32 v4, v32, v52
	v_pk_fma_f32 v[56:57], v[50:51], v[52:53], v[4:5] op_sel_hi:[1,1,0] neg_lo:[1,0,0] neg_hi:[1,0,0]
	v_mul_f32_e32 v4, v32, v53
	v_pk_fma_f32 v[48:49], v[48:49], v[52:53], v[4:5] op_sel_hi:[1,1,0]
	v_pk_add_f32 v[28:29], v[88:89], v[178:179]
	v_mov_b32_e32 v56, v48
	v_pk_fma_f32 v[16:17], v[54:55], 0.5, v[48:49] op_sel_hi:[1,0,1] neg_lo:[0,0,1] neg_hi:[0,0,1]
	v_mov_b32_e32 v48, v12
	v_mov_b32_e32 v49, v88
	v_pk_mov_b32 v[12:13], v[12:13], v[178:179] op_sel:[1,0]
	v_mul_f32_e32 v18, 0.5, v29
	v_pk_add_f32 v[12:13], v[48:49], v[12:13] neg_lo:[0,1] neg_hi:[0,1]
	v_mul_f32_e32 v4, 0.5, v28
	v_pk_mul_f32 v[48:49], v[12:13], v[18:19]
	v_mov_b32_e32 v13, v32
	v_pk_fma_f32 v[50:51], v[50:51], v[48:49], v[48:49] op_sel:[0,1,0] op_sel_hi:[1,0,1]
	v_mov_b32_e32 v48, v49
	v_mov_b32_e32 v49, v18
	v_pk_mul_f32 v[48:49], v[12:13], v[48:49]
	v_pk_add_f32 v[52:53], v[4:5], v[50:51]
	v_mul_f32_e32 v6, 0.5, v6
	v_fma_f32 v53, v28, 0.5, -v50
	v_pk_add_f32 v[28:29], v[48:49], v[48:49] op_sel:[0,1] op_sel_hi:[0,1] neg_lo:[0,1] neg_hi:[0,1]
	v_pk_add_f32 v[48:49], v[6:7], v[28:29] op_sel_hi:[0,1] neg_hi:[0,1]
	v_pk_mul_f32 v[28:29], v[48:49], v[176:177]
	v_pk_mul_f32 v[48:49], v[48:49], v[174:175]
	v_pk_fma_f32 v[28:29], v[52:53], v[174:175], v[28:29]
	v_pk_fma_f32 v[48:49], v[52:53], v[176:177], v[48:49] neg_lo:[0,0,1] neg_hi:[0,0,1]
	v_pk_fma_f32 v[92:93], v[54:55], 0.5, v[56:57] op_sel_hi:[1,0,1]
	v_pk_add_f32 v[50:51], v[48:49], v[28:29] op_sel:[0,1] op_sel_hi:[1,0] neg_lo:[0,1]
	v_pk_add_f32 v[52:53], v[48:49], v[28:29] op_sel:[0,1] op_sel_hi:[1,0]
	v_mov_b32_e32 v17, v93
	v_pk_mul_f32 v[50:51], v[50:51], 0.5 op_sel_hi:[1,0]
	v_pk_mul_f32 v[64:65], v[16:17], s[6:7] op_sel_hi:[1,0]
	v_mul_f32_e32 v4, v12, v50
	v_pk_fma_f32 v[16:17], v[54:55], 0.5, v[56:57] op_sel_hi:[1,0,1] neg_lo:[1,0,0] neg_hi:[1,0,0]
	v_pk_fma_f32 v[54:55], v[12:13], v[50:51], v[4:5] op_sel_hi:[1,1,0] neg_lo:[1,0,0] neg_hi:[1,0,0]
	v_mov_b32_e32 v33, v12
	v_mul_f32_e32 v4, v12, v51
	v_pk_fma_f32 v[12:13], v[32:33], v[50:51], v[4:5] op_sel_hi:[1,1,0]
	v_pk_add_f32 v[28:29], v[28:29], v[48:49] op_sel:[1,0] op_sel_hi:[0,1] neg_lo:[0,1] neg_hi:[0,1]
	v_mov_b32_e32 v53, v29
	v_mov_b32_e32 v54, v12
	v_pk_fma_f32 v[12:13], v[52:53], 0.5, v[12:13] op_sel_hi:[1,0,1] neg_lo:[0,0,1] neg_hi:[0,0,1]
	v_pk_fma_f32 v[88:89], v[52:53], 0.5, v[54:55] op_sel_hi:[1,0,1]
	s_mov_b32 s79, s16
	v_mov_b32_e32 v13, v89
	v_pk_mul_f32 v[68:69], v[12:13], s[6:7] op_sel_hi:[1,0]
	v_pk_fma_f32 v[12:13], v[52:53], 0.5, v[54:55] op_sel_hi:[1,0,1] neg_lo:[1,0,0] neg_hi:[1,0,0]
	v_mov_b32_e32 v4, v83
	s_mov_b32 s17, s19
	v_pk_mul_f32 v[48:49], v[82:83], s[78:79] op_sel_hi:[0,1]
	v_pk_add_f32 v[28:29], v[96:97], v[162:163]
	v_pk_add_f32 v[32:33], v[96:97], v[162:163] neg_lo:[0,1] neg_hi:[0,1]
	v_pk_fma_f32 v[52:53], v[4:5], s[16:17], v[48:49] op_sel_hi:[0,1,1] neg_lo:[0,0,1] neg_hi:[0,0,1]
	v_mul_f32_e32 v12, 0.5, v33
	v_pk_fma_f32 v[50:51], v[4:5], s[16:17], v[48:49] op_sel_hi:[0,1,1]
	v_mov_b32_e32 v33, v29
	v_mul_f32_e32 v6, 0.5, v28
	v_mov_b32_e32 v54, v52
	v_mov_b32_e32 v55, v51
	v_pk_mul_f32 v[28:29], v[32:33], s[44:45]
	v_pk_mov_b32 v[56:57], v[50:51], v[52:53] op_sel:[1,0]
	v_pk_mul_f32 v[32:33], v[54:55], v[28:29] op_sel:[0,1] op_sel_hi:[1,0]
	v_pk_mul_f32 v[28:29], v[54:55], v[28:29]
	v_pk_add_f32 v[32:33], v[32:33], v[32:33] op_sel:[0,1] op_sel_hi:[0,1]
	v_pk_add_f32 v[58:59], v[6:7], v[32:33] op_sel_hi:[0,1] neg_hi:[0,1]
	v_pk_add_f32 v[28:29], v[28:29], v[28:29] op_sel:[0,1] op_sel_hi:[0,1] neg_lo:[0,1] neg_hi:[0,1]
	v_pk_add_f32 v[32:33], v[12:13], v[28:29] op_sel_hi:[0,1] neg_hi:[0,1]
	v_pk_mul_f32 v[28:29], v[32:33], v[166:167]
	v_pk_mul_f32 v[32:33], v[32:33], v[164:165]
	v_pk_fma_f32 v[28:29], v[58:59], v[164:165], v[28:29]
	v_pk_fma_f32 v[32:33], v[58:59], v[166:167], v[32:33] neg_lo:[0,0,1] neg_hi:[0,0,1]
	v_mov_b32_e32 v159, v66
	v_pk_add_f32 v[58:59], v[32:33], v[28:29] op_sel:[0,1] op_sel_hi:[1,0] neg_lo:[0,1]
	v_pk_add_f32 v[70:71], v[32:33], v[28:29] op_sel:[0,1] op_sel_hi:[1,0]
	v_pk_add_f32 v[28:29], v[28:29], v[32:33] op_sel:[1,0] op_sel_hi:[0,1] neg_lo:[0,1] neg_hi:[0,1]
	v_pk_mul_f32 v[58:59], v[58:59], 0.5 op_sel_hi:[1,0]
	v_mov_b32_e32 v71, v29
	v_mul_f32_e32 v6, v52, v58
	v_pk_fma_f32 v[72:73], v[54:55], v[58:59], v[6:7] op_sel_hi:[1,1,0] neg_lo:[1,0,0] neg_hi:[1,0,0]
	v_mul_f32_e32 v6, v52, v59
	v_pk_fma_f32 v[56:57], v[56:57], v[58:59], v[6:7] op_sel_hi:[1,1,0]
	v_sub_f32_e32 v12, v67, v153
	v_mov_b32_e32 v72, v56
	v_pk_fma_f32 v[28:29], v[70:71], 0.5, v[56:57] op_sel_hi:[1,0,1] neg_lo:[0,0,1] neg_hi:[0,0,1]
	v_pk_fma_f32 v[96:97], v[70:71], 0.5, v[72:73] op_sel_hi:[1,0,1]
	v_pk_mov_b32 v[56:57], v[48:49], v[152:153] op_sel:[1,0]
	v_mov_b32_e32 v29, v97
	v_pk_mul_f32 v[62:63], v[28:29], s[6:7] op_sel_hi:[1,0]
	v_pk_add_f32 v[28:29], v[66:67], v[152:153]
	v_pk_add_f32 v[56:57], v[158:159], v[56:57] neg_lo:[0,1] neg_hi:[0,1]
	v_mul_f32_e32 v18, 0.5, v29
	v_pk_mul_f32 v[58:59], v[56:57], v[18:19]
	v_mul_f32_e32 v6, 0.5, v28
	v_pk_fma_f32 v[54:55], v[54:55], v[58:59], v[58:59] op_sel:[0,1,0] op_sel_hi:[1,0,1]
	v_mov_b32_e32 v66, v56
	v_mov_b32_e32 v67, v52
	v_mov_b32_e32 v58, v59
	v_mov_b32_e32 v59, v18
	v_pk_mul_f32 v[58:59], v[66:67], v[58:59]
	v_pk_add_f32 v[66:67], v[6:7], v[54:55]
	v_mul_f32_e32 v12, 0.5, v12
	v_fma_f32 v67, v28, 0.5, -v54
	v_pk_add_f32 v[28:29], v[58:59], v[58:59] op_sel:[0,1] op_sel_hi:[0,1] neg_lo:[0,1] neg_hi:[0,1]
	v_pk_add_f32 v[54:55], v[12:13], v[28:29] op_sel_hi:[0,1] neg_hi:[0,1]
	v_pk_mul_f32 v[28:29], v[54:55], v[156:157]
	v_pk_mul_f32 v[54:55], v[54:55], v[154:155]
	v_pk_fma_f32 v[32:33], v[70:71], 0.5, v[72:73] op_sel_hi:[1,0,1] neg_lo:[1,0,0] neg_hi:[1,0,0]
	v_pk_fma_f32 v[58:59], v[66:67], v[154:155], v[28:29] neg_lo:[0,0,1] neg_hi:[0,0,1]
	v_pk_fma_f32 v[28:29], v[66:67], v[154:155], v[28:29]
	v_pk_fma_f32 v[70:71], v[66:67], v[156:157], v[54:55]
	v_pk_fma_f32 v[54:55], v[66:67], v[156:157], v[54:55] neg_lo:[0,0,1] neg_hi:[0,0,1]
	v_pk_add_f32 v[72:73], v[58:59], v[28:29] op_sel:[0,1] op_sel_hi:[1,0]
	v_pk_add_f32 v[66:67], v[70:71], v[54:55] op_sel_hi:[0,1] neg_lo:[0,1] neg_hi:[0,1]
	v_pk_add_f32 v[28:29], v[58:59], v[28:29] op_sel_hi:[0,1] neg_lo:[0,1] neg_hi:[0,1]
	v_pk_add_f32 v[54:55], v[70:71], v[54:55] op_sel:[0,1] op_sel_hi:[1,0]
	v_mov_b32_e32 v73, v67
	v_mov_b32_e32 v55, v29
	v_pk_mul_f32 v[28:29], v[54:55], 0.5 op_sel_hi:[1,0]
	v_mov_b32_e32 v133, v84
	v_pk_mul_f32 v[54:55], v[52:53], v[28:29] op_sel:[0,1] op_sel_hi:[0,0]
	v_pk_fma_f32 v[58:59], v[56:57], v[28:29], v[54:55] op_sel_hi:[0,1,1]
	v_pk_fma_f32 v[28:29], v[56:57], v[28:29], v[54:55] op_sel_hi:[0,1,1] neg_hi:[0,0,1]
	v_pk_fma_f32 v[54:55], v[72:73], 0.5, v[58:59] op_sel_hi:[1,0,1] neg_lo:[0,0,1] neg_hi:[0,0,1]
	v_pk_fma_f32 v[66:67], v[72:73], 0.5, v[28:29] op_sel_hi:[1,0,1]
	v_pk_add_f32 v[56:57], v[60:61], v[134:135] neg_lo:[0,1] neg_hi:[0,1]
	v_mov_b32_e32 v55, v67
	v_pk_mul_f32 v[90:91], v[54:55], s[6:7] op_sel_hi:[1,0]
	v_pk_add_f32 v[54:55], v[134:135], v[60:61]
	v_mul_f32_e32 v12, 0.5, v57
	v_mov_b32_e32 v57, v55
	v_mul_f32_e32 v6, 0.5, v54
	v_pk_mov_b32 v[58:59], v[52:53], v[50:51] op_sel:[1,0]
	v_pk_mul_f32 v[54:55], v[56:57], s[44:45]
	v_pk_fma_f32 v[28:29], v[72:73], 0.5, v[28:29] op_sel_hi:[1,0,1] neg_lo:[1,0,0] neg_hi:[1,0,0]
	v_pk_mul_f32 v[56:57], v[58:59], v[54:55] op_sel:[0,1] op_sel_hi:[1,0]
	v_pk_mul_f32 v[54:55], v[58:59], v[54:55]
	v_pk_add_f32 v[56:57], v[56:57], v[56:57] op_sel:[0,1] op_sel_hi:[0,1]
	v_pk_add_f32 v[60:61], v[6:7], v[56:57] op_sel_hi:[0,1] neg_hi:[0,1]
	v_pk_add_f32 v[54:55], v[54:55], v[54:55] op_sel:[0,1] op_sel_hi:[0,1] neg_lo:[0,1] neg_hi:[0,1]
	v_pk_add_f32 v[56:57], v[12:13], v[54:55] op_sel_hi:[0,1] neg_hi:[0,1]
	v_pk_mul_f32 v[54:55], v[56:57], v[142:143]
	v_pk_mul_f32 v[56:57], v[56:57], v[140:141]
	v_pk_fma_f32 v[54:55], v[60:61], v[140:141], v[54:55]
	v_pk_fma_f32 v[56:57], v[60:61], v[142:143], v[56:57] neg_lo:[0,0,1] neg_hi:[0,0,1]
	v_mov_b32_e32 v51, v53
	v_pk_add_f32 v[60:61], v[56:57], v[54:55] op_sel:[0,1] op_sel_hi:[1,0] neg_lo:[0,1]
	v_pk_add_f32 v[70:71], v[56:57], v[54:55] op_sel:[0,1] op_sel_hi:[1,0]
	v_pk_add_f32 v[54:55], v[54:55], v[56:57] op_sel:[1,0] op_sel_hi:[0,1] neg_lo:[0,1] neg_hi:[0,1]
	v_pk_mul_f32 v[60:61], v[60:61], 0.5 op_sel_hi:[1,0]
	v_mov_b32_e32 v71, v55
	v_mul_f32_e32 v6, v53, v60
	v_pk_fma_f32 v[72:73], v[58:59], v[60:61], v[6:7] op_sel_hi:[1,1,0] neg_lo:[1,0,0] neg_hi:[1,0,0]
	v_mul_f32_e32 v6, v53, v61
	v_pk_fma_f32 v[50:51], v[50:51], v[60:61], v[6:7] op_sel_hi:[1,1,0]
	v_pk_add_f32 v[54:55], v[118:119], v[84:85]
	v_mov_b32_e32 v72, v50
	v_mov_b32_e32 v49, v118
	v_pk_fma_f32 v[50:51], v[70:71], 0.5, v[50:51] op_sel_hi:[1,0,1] neg_lo:[0,0,1] neg_hi:[0,0,1]
	v_pk_fma_f32 v[60:61], v[70:71], 0.5, v[72:73] op_sel_hi:[1,0,1]
	v_mul_f32_e32 v18, 0.5, v55
	v_pk_add_f32 v[48:49], v[132:133], v[48:49] neg_lo:[0,1] neg_hi:[0,1]
	v_mov_b32_e32 v51, v61
	v_pk_mul_f32 v[56:57], v[48:49], v[18:19]
	v_pk_mul_f32 v[94:95], v[50:51], s[6:7] op_sel_hi:[1,0]
	v_pk_fma_f32 v[50:51], v[70:71], 0.5, v[72:73] op_sel_hi:[1,0,1] neg_lo:[1,0,0] neg_hi:[1,0,0]
	v_mul_f32_e32 v6, 0.5, v54
	v_pk_fma_f32 v[58:59], v[58:59], v[56:57], v[56:57] op_sel:[0,1,0] op_sel_hi:[1,0,1]
	v_mov_b32_e32 v70, v48
	v_mov_b32_e32 v71, v53
	v_mov_b32_e32 v56, v57
	v_mov_b32_e32 v57, v18
	v_sub_f32_e32 v12, v85, v119
	v_pk_mul_f32 v[56:57], v[70:71], v[56:57]
	v_pk_add_f32 v[70:71], v[6:7], v[58:59]
	v_mul_f32_e32 v12, 0.5, v12
	v_fma_f32 v71, v54, 0.5, -v58
	v_pk_add_f32 v[54:55], v[56:57], v[56:57] op_sel:[0,1] op_sel_hi:[0,1] neg_lo:[0,1] neg_hi:[0,1]
	v_pk_add_f32 v[56:57], v[12:13], v[54:55] op_sel_hi:[0,1] neg_hi:[0,1]
	v_pk_mul_f32 v[54:55], v[56:57], v[126:127]
	v_pk_mul_f32 v[56:57], v[56:57], v[124:125]
	v_pk_fma_f32 v[58:59], v[70:71], v[124:125], v[54:55] neg_lo:[0,0,1] neg_hi:[0,0,1]
	v_pk_fma_f32 v[54:55], v[70:71], v[124:125], v[54:55]
	v_pk_fma_f32 v[72:73], v[70:71], v[126:127], v[56:57]
	v_pk_fma_f32 v[56:57], v[70:71], v[126:127], v[56:57] neg_lo:[0,0,1] neg_hi:[0,0,1]
	v_pk_add_f32 v[70:71], v[58:59], v[54:55] op_sel:[0,1] op_sel_hi:[1,0]
	v_pk_add_f32 v[74:75], v[72:73], v[56:57] op_sel_hi:[0,1] neg_lo:[0,1] neg_hi:[0,1]
	v_pk_add_f32 v[54:55], v[58:59], v[54:55] op_sel_hi:[0,1] neg_lo:[0,1] neg_hi:[0,1]
	v_pk_add_f32 v[56:57], v[72:73], v[56:57] op_sel:[0,1] op_sel_hi:[1,0]
	v_mov_b32_e32 v71, v75
	v_mov_b32_e32 v57, v55
	v_pk_mul_f32 v[54:55], v[56:57], 0.5 op_sel_hi:[1,0]
	s_mov_b32 s78, s11
	v_pk_mul_f32 v[52:53], v[52:53], v[54:55] op_sel:[1,1] op_sel_hi:[1,0]
	s_mov_b32 s79, s8
	v_pk_fma_f32 v[56:57], v[48:49], v[54:55], v[52:53] op_sel_hi:[0,1,1]
	v_pk_fma_f32 v[48:49], v[48:49], v[54:55], v[52:53] op_sel_hi:[0,1,1] neg_hi:[0,0,1]
	s_nop 0
	v_pk_fma_f32 v[52:53], v[70:71], 0.5, v[56:57] op_sel_hi:[1,0,1] neg_lo:[0,0,1] neg_hi:[0,0,1]
	v_pk_fma_f32 v[84:85], v[70:71], 0.5, v[48:49] op_sel_hi:[1,0,1]
	s_mov_b32 s9, s11
	v_mov_b32_e32 v53, v85
	v_pk_mul_f32 v[80:81], v[52:53], s[6:7] op_sel_hi:[1,0]
	v_pk_mul_f32 v[118:119], v[82:83], s[78:79] op_sel_hi:[0,1]
	v_pk_add_f32 v[52:53], v[86:87], v[112:113]
	v_pk_add_f32 v[54:55], v[86:87], v[112:113] neg_lo:[0,1] neg_hi:[0,1]
	v_pk_fma_f32 v[58:59], v[4:5], s[8:9], v[118:119] op_sel_hi:[0,1,1] neg_lo:[0,0,1] neg_hi:[0,0,1]
	v_mul_f32_e32 v12, 0.5, v55
	v_pk_fma_f32 v[72:73], v[4:5], s[8:9], v[118:119] op_sel_hi:[0,1,1]
	v_mov_b32_e32 v55, v53
	v_mul_f32_e32 v6, 0.5, v52
	v_mov_b32_e32 v56, v58
	v_mov_b32_e32 v57, v73
	v_pk_mul_f32 v[52:53], v[54:55], s[44:45]
	v_pk_fma_f32 v[48:49], v[70:71], 0.5, v[48:49] op_sel_hi:[1,0,1] neg_lo:[1,0,0] neg_hi:[1,0,0]
	v_pk_mul_f32 v[54:55], v[56:57], v[52:53] op_sel:[0,1] op_sel_hi:[1,0]
	v_pk_mul_f32 v[52:53], v[56:57], v[52:53]
	v_pk_add_f32 v[54:55], v[54:55], v[54:55] op_sel:[0,1] op_sel_hi:[0,1]
	v_pk_add_f32 v[74:75], v[6:7], v[54:55] op_sel_hi:[0,1] neg_hi:[0,1]
	v_pk_add_f32 v[52:53], v[52:53], v[52:53] op_sel:[0,1] op_sel_hi:[0,1] neg_lo:[0,1] neg_hi:[0,1]
	v_pk_add_f32 v[54:55], v[12:13], v[52:53] op_sel_hi:[0,1] neg_hi:[0,1]
	v_pk_mul_f32 v[52:53], v[54:55], v[116:117]
	v_pk_mul_f32 v[54:55], v[54:55], v[114:115]
	v_pk_fma_f32 v[52:53], v[74:75], v[114:115], v[52:53]
	v_pk_fma_f32 v[54:55], v[74:75], v[116:117], v[54:55] neg_lo:[0,0,1] neg_hi:[0,0,1]
	v_pk_mov_b32 v[70:71], v[72:73], v[58:59] op_sel:[1,0]
	v_pk_add_f32 v[74:75], v[54:55], v[52:53] op_sel:[0,1] op_sel_hi:[1,0] neg_lo:[0,1]
	v_pk_add_f32 v[76:77], v[54:55], v[52:53] op_sel:[0,1] op_sel_hi:[1,0]
	v_pk_add_f32 v[52:53], v[52:53], v[54:55] op_sel:[1,0] op_sel_hi:[0,1] neg_lo:[0,1] neg_hi:[0,1]
	v_pk_mul_f32 v[74:75], v[74:75], 0.5 op_sel_hi:[1,0]
	v_mov_b32_e32 v77, v53
	v_mul_f32_e32 v6, v58, v74
	v_pk_fma_f32 v[112:113], v[56:57], v[74:75], v[6:7] op_sel_hi:[1,1,0] neg_lo:[1,0,0] neg_hi:[1,0,0]
	v_mul_f32_e32 v6, v58, v75
	v_pk_fma_f32 v[70:71], v[70:71], v[74:75], v[6:7] op_sel_hi:[1,1,0]
	v_pk_add_f32 v[54:55], v[34:35], v[110:111]
	v_mov_b32_e32 v112, v70
	v_pk_fma_f32 v[52:53], v[76:77], 0.5, v[70:71] op_sel_hi:[1,0,1] neg_lo:[0,0,1] neg_hi:[0,0,1]
	v_pk_fma_f32 v[86:87], v[76:77], 0.5, v[112:113] op_sel_hi:[1,0,1]
	v_sub_f32_e32 v12, v35, v111
	v_mov_b32_e32 v53, v87
	v_pk_mul_f32 v[78:79], v[52:53], s[6:7] op_sel_hi:[1,0]
	v_mul_f32_e32 v52, 0xbe47c5c2, v83
	v_mov_b32_e32 v53, v34
	v_pk_mov_b32 v[34:35], v[118:119], v[110:111] op_sel:[1,0]
	v_mul_f32_e32 v18, 0.5, v55
	v_pk_add_f32 v[34:35], v[52:53], v[34:35] neg_lo:[0,1] neg_hi:[0,1]
	v_mov_b32_e32 v71, v58
	v_pk_mul_f32 v[52:53], v[34:35], v[18:19]
	v_mov_b32_e32 v70, v34
	v_pk_fma_f32 v[56:57], v[56:57], v[52:53], v[52:53] op_sel:[0,1,0] op_sel_hi:[1,0,1]
	v_mov_b32_e32 v52, v53
	v_mov_b32_e32 v53, v18
	v_mul_f32_e32 v6, 0.5, v54
	v_pk_mul_f32 v[52:53], v[70:71], v[52:53]
	v_cvt_f32_f16_e32 v70, v46
	v_cvt_f32_f16_e32 v71, v47
	v_cvt_f32_f16_sdwa v47, v47 dst_sel:DWORD dst_unused:UNUSED_PAD src0_sel:WORD_1
	v_cvt_f32_f16_sdwa v46, v46 dst_sel:DWORD dst_unused:UNUSED_PAD src0_sel:WORD_1
	v_pk_fma_f32 v[74:75], v[76:77], 0.5, v[112:113] op_sel_hi:[1,0,1] neg_lo:[1,0,0] neg_hi:[1,0,0]
	v_mul_f32_e32 v12, 0.5, v12
	v_pk_add_f32 v[76:77], v[6:7], v[56:57]
	v_pk_add_f32 v[52:53], v[52:53], v[52:53] op_sel:[0,1] op_sel_hi:[0,1] neg_lo:[0,1] neg_hi:[0,1]
	v_fma_f32 v77, v54, 0.5, -v56
	v_pk_add_f32 v[54:55], v[12:13], v[52:53] op_sel_hi:[0,1] neg_hi:[0,1]
	v_pk_mul_f32 v[52:53], v[54:55], v[46:47]
	v_pk_mul_f32 v[54:55], v[54:55], v[70:71]
	v_pk_fma_f32 v[56:57], v[76:77], v[70:71], v[52:53] neg_lo:[0,0,1] neg_hi:[0,0,1]
	v_pk_fma_f32 v[52:53], v[76:77], v[70:71], v[52:53]
	v_pk_fma_f32 v[70:71], v[76:77], v[46:47], v[54:55]
	v_pk_fma_f32 v[46:47], v[76:77], v[46:47], v[54:55] neg_lo:[0,0,1] neg_hi:[0,0,1]
	v_pk_add_f32 v[54:55], v[56:57], v[52:53] op_sel:[0,1] op_sel_hi:[1,0]
	v_pk_add_f32 v[76:77], v[70:71], v[46:47] op_sel_hi:[0,1] neg_lo:[0,1] neg_hi:[0,1]
	v_pk_add_f32 v[52:53], v[56:57], v[52:53] op_sel_hi:[0,1] neg_lo:[0,1] neg_hi:[0,1]
	v_pk_add_f32 v[46:47], v[70:71], v[46:47] op_sel:[0,1] op_sel_hi:[1,0]
	v_mov_b32_e32 v55, v77
	v_mov_b32_e32 v47, v53
	v_pk_mul_f32 v[46:47], v[46:47], 0.5 op_sel_hi:[1,0]
	s_mov_b32 s25, s27
	v_pk_mul_f32 v[52:53], v[58:59], v[46:47] op_sel:[0,1] op_sel_hi:[0,0]
	v_pk_fma_f32 v[56:57], v[34:35], v[46:47], v[52:53] op_sel_hi:[0,1,1]
	v_pk_fma_f32 v[46:47], v[34:35], v[46:47], v[52:53] op_sel_hi:[0,1,1] neg_hi:[0,0,1]
	s_nop 0
	v_pk_fma_f32 v[52:53], v[54:55], 0.5, v[56:57] op_sel_hi:[1,0,1] neg_lo:[0,0,1] neg_hi:[0,0,1]
	v_pk_fma_f32 v[34:35], v[54:55], 0.5, v[46:47] op_sel_hi:[1,0,1]
	s_mov_b32 s78, s27
	v_mov_b32_e32 v53, v35
	v_pk_mul_f32 v[136:137], v[52:53], s[6:7] op_sel_hi:[1,0]
	v_pk_fma_f32 v[52:53], v[54:55], 0.5, v[46:47] op_sel_hi:[1,0,1] neg_lo:[1,0,0] neg_hi:[1,0,0]
	s_mov_b32 s79, s24
	v_pk_mul_f32 v[46:47], v[82:83], s[24:25] op_sel_hi:[0,1]
	v_pk_add_f32 v[54:55], v[108:109], v[40:41]
	v_pk_add_f32 v[40:41], v[40:41], v[108:109] neg_lo:[0,1] neg_hi:[0,1]
	v_pk_fma_f32 v[108:109], v[4:5], s[78:79], v[46:47] op_sel_hi:[0,1,1] neg_lo:[0,0,1] neg_hi:[0,0,1]
	v_mul_f32_e32 v12, 0.5, v41
	v_pk_fma_f32 v[70:71], v[4:5], s[78:79], v[46:47] op_sel_hi:[0,1,1]
	v_mov_b32_e32 v41, v55
	v_mov_b32_e32 v56, v108
	v_mov_b32_e32 v57, v71
	v_pk_mul_f32 v[40:41], v[40:41], s[44:45]
	v_mul_f32_e32 v6, 0.5, v54
	v_pk_mul_f32 v[54:55], v[56:57], v[40:41] op_sel:[0,1] op_sel_hi:[1,0]
	v_cvt_f32_f16_sdwa v76, v36 dst_sel:DWORD dst_unused:UNUSED_PAD src0_sel:WORD_1
	v_cvt_f32_f16_e32 v77, v37
	v_cvt_f32_f16_sdwa v37, v37 dst_sel:DWORD dst_unused:UNUSED_PAD src0_sel:WORD_1
	v_cvt_f32_f16_e32 v36, v36
	v_pk_mul_f32 v[40:41], v[56:57], v[40:41]
	v_pk_add_f32 v[54:55], v[54:55], v[54:55] op_sel:[0,1] op_sel_hi:[0,1]
	v_pk_add_f32 v[112:113], v[6:7], v[54:55] op_sel_hi:[0,1] neg_hi:[0,1]
	s_nop 0
	v_pk_add_f32 v[40:41], v[40:41], v[40:41] op_sel:[0,1] op_sel_hi:[0,1] neg_lo:[0,1] neg_hi:[0,1]
	v_pk_add_f32 v[54:55], v[12:13], v[40:41] op_sel_hi:[0,1] neg_hi:[0,1]
	v_pk_mul_f32 v[40:41], v[54:55], v[36:37]
	v_pk_mul_f32 v[54:55], v[54:55], v[76:77]
	v_pk_fma_f32 v[40:41], v[112:113], v[76:77], v[40:41]
	v_pk_fma_f32 v[36:37], v[112:113], v[36:37], v[54:55] neg_lo:[0,0,1] neg_hi:[0,0,1]
	v_pk_mov_b32 v[110:111], v[70:71], v[108:109] op_sel:[1,0]
	v_pk_add_f32 v[54:55], v[36:37], v[40:41] op_sel:[0,1] op_sel_hi:[1,0] neg_lo:[0,1]
	v_pk_add_f32 v[76:77], v[36:37], v[40:41] op_sel:[0,1] op_sel_hi:[1,0]
	v_pk_add_f32 v[36:37], v[40:41], v[36:37] op_sel:[1,0] op_sel_hi:[0,1] neg_lo:[0,1] neg_hi:[0,1]
	v_pk_mul_f32 v[54:55], v[54:55], 0.5 op_sel_hi:[1,0]
	v_mov_b32_e32 v77, v37
	v_mul_f32_e32 v4, v108, v54
	v_pk_fma_f32 v[112:113], v[56:57], v[54:55], v[4:5] op_sel_hi:[1,1,0] neg_lo:[1,0,0] neg_hi:[1,0,0]
	v_mul_f32_e32 v4, v108, v55
	v_pk_fma_f32 v[54:55], v[110:111], v[54:55], v[4:5] op_sel_hi:[1,1,0]
	v_sub_f32_e32 v6, v45, v105
	v_mov_b32_e32 v112, v54
	v_pk_fma_f32 v[40:41], v[76:77], 0.5, v[54:55] op_sel_hi:[1,0,1] neg_lo:[0,0,1] neg_hi:[0,0,1]
	v_pk_fma_f32 v[36:37], v[76:77], 0.5, v[112:113] op_sel_hi:[1,0,1]
	v_pk_add_f32 v[54:55], v[104:105], v[44:45]
	v_mov_b32_e32 v41, v37
	v_pk_mul_f32 v[130:131], v[40:41], s[6:7] op_sel_hi:[1,0]
	v_mul_f32_e32 v40, 0xbf54db31, v83
	v_mov_b32_e32 v41, v44
	v_pk_mov_b32 v[44:45], v[46:47], v[104:105] op_sel:[1,0]
	v_mul_f32_e32 v18, 0.5, v55
	v_pk_add_f32 v[40:41], v[40:41], v[44:45] neg_lo:[0,1] neg_hi:[0,1]
	v_mov_b32_e32 v105, v108
	v_pk_mul_f32 v[44:45], v[40:41], v[18:19]
	v_mov_b32_e32 v104, v40
	v_pk_fma_f32 v[56:57], v[56:57], v[44:45], v[44:45] op_sel:[0,1,0] op_sel_hi:[1,0,1]
	v_mov_b32_e32 v44, v45
	v_mov_b32_e32 v45, v18
	v_mul_f32_e32 v4, 0.5, v54
	v_pk_mul_f32 v[44:45], v[104:105], v[44:45]
	v_cvt_f32_f16_e32 v104, v26
	v_cvt_f32_f16_e32 v105, v27
	v_cvt_f32_f16_sdwa v27, v27 dst_sel:DWORD dst_unused:UNUSED_PAD src0_sel:WORD_1
	v_cvt_f32_f16_sdwa v26, v26 dst_sel:DWORD dst_unused:UNUSED_PAD src0_sel:WORD_1
	v_mul_f32_e32 v6, 0.5, v6
	v_pk_add_f32 v[110:111], v[4:5], v[56:57]
	v_pk_add_f32 v[44:45], v[44:45], v[44:45] op_sel:[0,1] op_sel_hi:[0,1] neg_lo:[0,1] neg_hi:[0,1]
	v_fma_f32 v111, v54, 0.5, -v56
	v_pk_add_f32 v[54:55], v[6:7], v[44:45] op_sel_hi:[0,1] neg_hi:[0,1]
	v_pk_mul_f32 v[44:45], v[54:55], v[26:27]
	v_pk_mul_f32 v[54:55], v[54:55], v[104:105]
	v_pk_fma_f32 v[56:57], v[110:111], v[104:105], v[44:45] neg_lo:[0,0,1] neg_hi:[0,0,1]
	v_pk_fma_f32 v[44:45], v[110:111], v[104:105], v[44:45]
	v_pk_fma_f32 v[104:105], v[110:111], v[26:27], v[54:55]
	v_pk_fma_f32 v[26:27], v[110:111], v[26:27], v[54:55] neg_lo:[0,0,1] neg_hi:[0,0,1]
	v_pk_add_f32 v[54:55], v[56:57], v[44:45] op_sel:[0,1] op_sel_hi:[1,0]
	v_pk_add_f32 v[110:111], v[104:105], v[26:27] op_sel_hi:[0,1] neg_lo:[0,1] neg_hi:[0,1]
	v_pk_add_f32 v[44:45], v[56:57], v[44:45] op_sel_hi:[0,1] neg_lo:[0,1] neg_hi:[0,1]
	v_pk_add_f32 v[26:27], v[104:105], v[26:27] op_sel:[0,1] op_sel_hi:[1,0]
	v_mov_b32_e32 v55, v111
	v_mov_b32_e32 v27, v45
	v_pk_mul_f32 v[26:27], v[26:27], 0.5 op_sel_hi:[1,0]
	v_mov_b32_e32 v47, v102
	v_pk_mul_f32 v[44:45], v[108:109], v[26:27] op_sel:[0,1] op_sel_hi:[0,0]
	v_pk_fma_f32 v[56:57], v[40:41], v[26:27], v[44:45] op_sel_hi:[0,1,1]
	v_pk_fma_f32 v[40:41], v[40:41], v[26:27], v[44:45] op_sel_hi:[0,1,1] neg_hi:[0,0,1]
	v_pk_fma_f32 v[44:45], v[54:55], 0.5, v[56:57] op_sel_hi:[1,0,1] neg_lo:[0,0,1] neg_hi:[0,0,1]
	v_pk_fma_f32 v[26:27], v[54:55], 0.5, v[40:41] op_sel_hi:[1,0,1]
	v_pk_fma_f32 v[56:57], v[54:55], 0.5, v[40:41] op_sel_hi:[1,0,1] neg_lo:[1,0,0] neg_hi:[1,0,0]
	v_pk_add_f32 v[40:41], v[106:107], v[42:43]
	v_pk_add_f32 v[42:43], v[42:43], v[106:107] neg_lo:[0,1] neg_hi:[0,1]
	v_mov_b32_e32 v45, v27
	v_mul_f32_e32 v6, 0.5, v43
	v_mov_b32_e32 v43, v41
	v_pk_mul_f32 v[120:121], v[44:45], s[6:7] op_sel_hi:[1,0]
	v_mul_f32_e32 v4, 0.5, v40
	v_pk_mov_b32 v[44:45], v[108:109], v[70:71] op_sel:[1,0]
	v_pk_mul_f32 v[40:41], v[42:43], s[44:45]
	v_cvt_f32_f16_sdwa v54, v20 dst_sel:DWORD dst_unused:UNUSED_PAD src0_sel:WORD_1
	v_pk_mul_f32 v[42:43], v[44:45], v[40:41] op_sel:[0,1] op_sel_hi:[1,0]
	v_cvt_f32_f16_e32 v55, v21
	v_cvt_f32_f16_sdwa v21, v21 dst_sel:DWORD dst_unused:UNUSED_PAD src0_sel:WORD_1
	v_cvt_f32_f16_e32 v20, v20
	v_pk_mul_f32 v[40:41], v[44:45], v[40:41]
	v_pk_add_f32 v[42:43], v[42:43], v[42:43] op_sel:[0,1] op_sel_hi:[0,1]
	v_pk_add_f32 v[104:105], v[4:5], v[42:43] op_sel_hi:[0,1] neg_hi:[0,1]
	s_nop 0
	v_pk_add_f32 v[40:41], v[40:41], v[40:41] op_sel:[0,1] op_sel_hi:[0,1] neg_lo:[0,1] neg_hi:[0,1]
	v_pk_add_f32 v[42:43], v[6:7], v[40:41] op_sel_hi:[0,1] neg_hi:[0,1]
	v_pk_mul_f32 v[40:41], v[42:43], v[20:21]
	v_pk_mul_f32 v[42:43], v[42:43], v[54:55]
	v_pk_fma_f32 v[40:41], v[104:105], v[54:55], v[40:41]
	v_pk_fma_f32 v[20:21], v[104:105], v[20:21], v[42:43] neg_lo:[0,0,1] neg_hi:[0,0,1]
	v_mov_b32_e32 v71, v109
	v_pk_add_f32 v[42:43], v[20:21], v[40:41] op_sel:[0,1] op_sel_hi:[1,0] neg_lo:[0,1]
	v_pk_add_f32 v[54:55], v[20:21], v[40:41] op_sel:[0,1] op_sel_hi:[1,0]
	v_pk_add_f32 v[20:21], v[40:41], v[20:21] op_sel:[1,0] op_sel_hi:[0,1] neg_lo:[0,1] neg_hi:[0,1]
	v_pk_mul_f32 v[42:43], v[42:43], 0.5 op_sel_hi:[1,0]
	v_mov_b32_e32 v55, v21
	v_mul_f32_e32 v4, v109, v42
	v_pk_fma_f32 v[104:105], v[44:45], v[42:43], v[4:5] op_sel_hi:[1,1,0] neg_lo:[1,0,0] neg_hi:[1,0,0]
	v_mul_f32_e32 v4, v109, v43
	v_pk_fma_f32 v[42:43], v[70:71], v[42:43], v[4:5] op_sel_hi:[1,1,0]
	v_sub_f32_e32 v6, v23, v103
	v_mov_b32_e32 v104, v42
	v_pk_fma_f32 v[40:41], v[54:55], 0.5, v[42:43] op_sel_hi:[1,0,1] neg_lo:[0,0,1] neg_hi:[0,0,1]
	v_pk_fma_f32 v[20:21], v[54:55], 0.5, v[104:105] op_sel_hi:[1,0,1]
	v_pk_add_f32 v[42:43], v[102:103], v[22:23]
	v_mov_b32_e32 v41, v21
	v_pk_mul_f32 v[128:129], v[40:41], s[6:7] op_sel_hi:[1,0]
	v_mul_f32_e32 v40, 0xbf0e39da, v83
	v_mov_b32_e32 v41, v22
	v_mul_f32_e32 v18, 0.5, v43
	v_pk_add_f32 v[22:23], v[40:41], v[46:47] neg_lo:[0,1] neg_hi:[0,1]
	v_mov_b32_e32 v47, v109
	v_pk_mul_f32 v[40:41], v[22:23], v[18:19]
	v_mov_b32_e32 v46, v22
	v_pk_fma_f32 v[44:45], v[44:45], v[40:41], v[40:41] op_sel:[0,1,0] op_sel_hi:[1,0,1]
	v_mov_b32_e32 v40, v41
	v_mov_b32_e32 v41, v18
	v_mul_f32_e32 v4, 0.5, v42
	v_pk_mul_f32 v[40:41], v[46:47], v[40:41]
	v_cvt_f32_f16_e32 v46, v10
	v_cvt_f32_f16_e32 v47, v11
	v_cvt_f32_f16_sdwa v11, v11 dst_sel:DWORD dst_unused:UNUSED_PAD src0_sel:WORD_1
	v_cvt_f32_f16_sdwa v10, v10 dst_sel:DWORD dst_unused:UNUSED_PAD src0_sel:WORD_1
	v_pk_fma_f32 v[70:71], v[54:55], 0.5, v[104:105] op_sel_hi:[1,0,1] neg_lo:[1,0,0] neg_hi:[1,0,0]
	v_mul_f32_e32 v6, 0.5, v6
	v_pk_add_f32 v[54:55], v[4:5], v[44:45]
	v_pk_add_f32 v[40:41], v[40:41], v[40:41] op_sel:[0,1] op_sel_hi:[0,1] neg_lo:[0,1] neg_hi:[0,1]
	v_fma_f32 v55, v42, 0.5, -v44
	v_pk_add_f32 v[42:43], v[6:7], v[40:41] op_sel_hi:[0,1] neg_hi:[0,1]
	v_pk_mul_f32 v[40:41], v[42:43], v[10:11]
	v_pk_mul_f32 v[42:43], v[42:43], v[46:47]
	v_pk_fma_f32 v[44:45], v[54:55], v[46:47], v[40:41] neg_lo:[0,0,1] neg_hi:[0,0,1]
	v_pk_fma_f32 v[40:41], v[54:55], v[46:47], v[40:41]
	v_pk_fma_f32 v[46:47], v[54:55], v[10:11], v[42:43]
	v_pk_fma_f32 v[10:11], v[54:55], v[10:11], v[42:43] neg_lo:[0,0,1] neg_hi:[0,0,1]
	v_pk_add_f32 v[42:43], v[44:45], v[40:41] op_sel:[0,1] op_sel_hi:[1,0]
	v_pk_add_f32 v[54:55], v[46:47], v[10:11] op_sel_hi:[0,1] neg_lo:[0,1] neg_hi:[0,1]
	v_pk_add_f32 v[40:41], v[44:45], v[40:41] op_sel_hi:[0,1] neg_lo:[0,1] neg_hi:[0,1]
	v_pk_add_f32 v[10:11], v[46:47], v[10:11] op_sel:[0,1] op_sel_hi:[1,0]
	v_mov_b32_e32 v43, v55
	v_mov_b32_e32 v11, v41
	v_pk_mul_f32 v[10:11], v[10:11], 0.5 op_sel_hi:[1,0]
	v_mov_b32_e32 v119, v98
	v_pk_mul_f32 v[40:41], v[108:109], v[10:11] op_sel:[1,1] op_sel_hi:[1,0]
	v_pk_fma_f32 v[76:77], v[76:77], 0.5, v[112:113] op_sel_hi:[1,0,1] neg_lo:[1,0,0] neg_hi:[1,0,0]
	v_pk_fma_f32 v[44:45], v[22:23], v[10:11], v[40:41] op_sel_hi:[0,1,1]
	v_pk_fma_f32 v[10:11], v[22:23], v[10:11], v[40:41] op_sel_hi:[0,1,1] neg_hi:[0,0,1]
	v_pk_fma_f32 v[22:23], v[42:43], 0.5, v[44:45] op_sel_hi:[1,0,1] neg_lo:[0,0,1] neg_hi:[0,0,1]
	v_pk_fma_f32 v[40:41], v[42:43], 0.5, v[10:11] op_sel_hi:[1,0,1]
	v_pk_fma_f32 v[54:55], v[42:43], 0.5, v[10:11] op_sel_hi:[1,0,1] neg_lo:[1,0,0] neg_hi:[1,0,0]
	v_pk_add_f32 v[10:11], v[100:101], v[14:15]
	v_pk_add_f32 v[14:15], v[14:15], v[100:101] neg_lo:[0,1] neg_hi:[0,1]
	v_mov_b32_e32 v23, v41
	v_mul_f32_e32 v6, 0.5, v15
	v_mov_b32_e32 v15, v11
	v_pk_mul_f32 v[150:151], v[22:23], s[6:7] op_sel_hi:[1,0]
	v_mul_f32_e32 v4, 0.5, v10
	v_pk_mov_b32 v[22:23], v[58:59], v[72:73] op_sel:[1,0]
	v_pk_mul_f32 v[10:11], v[14:15], s[44:45]
	v_cvt_f32_f16_sdwa v42, v8 dst_sel:DWORD dst_unused:UNUSED_PAD src0_sel:WORD_1
	v_pk_mul_f32 v[14:15], v[22:23], v[10:11] op_sel:[0,1] op_sel_hi:[1,0]
	v_cvt_f32_f16_e32 v43, v9
	v_cvt_f32_f16_sdwa v9, v9 dst_sel:DWORD dst_unused:UNUSED_PAD src0_sel:WORD_1
	v_cvt_f32_f16_e32 v8, v8
	v_pk_mul_f32 v[10:11], v[22:23], v[10:11]
	v_pk_add_f32 v[14:15], v[14:15], v[14:15] op_sel:[0,1] op_sel_hi:[0,1]
	v_pk_add_f32 v[44:45], v[4:5], v[14:15] op_sel_hi:[0,1] neg_hi:[0,1]
	s_nop 0
	v_pk_add_f32 v[10:11], v[10:11], v[10:11] op_sel:[0,1] op_sel_hi:[0,1] neg_lo:[0,1] neg_hi:[0,1]
	v_pk_add_f32 v[14:15], v[6:7], v[10:11] op_sel_hi:[0,1] neg_hi:[0,1]
	v_pk_mul_f32 v[10:11], v[14:15], v[8:9]
	v_pk_mul_f32 v[14:15], v[14:15], v[42:43]
	v_pk_fma_f32 v[10:11], v[44:45], v[42:43], v[10:11]
	v_pk_fma_f32 v[8:9], v[44:45], v[8:9], v[14:15] neg_lo:[0,0,1] neg_hi:[0,0,1]
	v_mov_b32_e32 v73, v59
	v_pk_add_f32 v[14:15], v[8:9], v[10:11] op_sel:[0,1] op_sel_hi:[1,0] neg_lo:[0,1]
	v_pk_add_f32 v[42:43], v[8:9], v[10:11] op_sel:[0,1] op_sel_hi:[1,0]
	v_pk_add_f32 v[8:9], v[10:11], v[8:9] op_sel:[1,0] op_sel_hi:[0,1] neg_lo:[0,1] neg_hi:[0,1]
	v_pk_mul_f32 v[14:15], v[14:15], 0.5 op_sel_hi:[1,0]
	v_mov_b32_e32 v43, v9
	v_mul_f32_e32 v4, v59, v14
	v_pk_fma_f32 v[44:45], v[22:23], v[14:15], v[4:5] op_sel_hi:[1,1,0] neg_lo:[1,0,0] neg_hi:[1,0,0]
	v_mul_f32_e32 v4, v59, v15
	v_pk_fma_f32 v[14:15], v[72:73], v[14:15], v[4:5] op_sel_hi:[1,1,0]
	v_sub_f32_e32 v6, v39, v99
	v_mov_b32_e32 v44, v14
	v_pk_fma_f32 v[8:9], v[42:43], 0.5, v[14:15] op_sel_hi:[1,0,1] neg_lo:[0,0,1] neg_hi:[0,0,1]
	v_pk_fma_f32 v[10:11], v[42:43], 0.5, v[44:45] op_sel_hi:[1,0,1]
	v_pk_add_f32 v[14:15], v[98:99], v[38:39]
	v_mov_b32_e32 v9, v11
	v_pk_mul_f32 v[168:169], v[8:9], s[6:7] op_sel_hi:[1,0]
	v_mul_f32_e32 v8, 0xbf7b14be, v83
	v_mov_b32_e32 v9, v38
	v_mul_f32_e32 v18, 0.5, v15
	v_pk_add_f32 v[8:9], v[8:9], v[118:119] neg_lo:[0,1] neg_hi:[0,1]
	v_pk_fma_f32 v[72:73], v[42:43], 0.5, v[44:45] op_sel_hi:[1,0,1] neg_lo:[1,0,0] neg_hi:[1,0,0]
	v_pk_mul_f32 v[38:39], v[8:9], v[18:19]
	v_mov_b32_e32 v42, v8
	v_pk_fma_f32 v[22:23], v[22:23], v[38:39], v[38:39] op_sel:[0,1,0] op_sel_hi:[1,0,1]
	v_mov_b32_e32 v43, v59
	v_mov_b32_e32 v38, v39
	v_mov_b32_e32 v39, v18
	v_mul_f32_e32 v4, 0.5, v14
	v_pk_mul_f32 v[38:39], v[42:43], v[38:39]
	v_cvt_f32_f16_e32 v44, v2
	v_cvt_f32_f16_e32 v45, v3
	v_cvt_f32_f16_sdwa v3, v3 dst_sel:DWORD dst_unused:UNUSED_PAD src0_sel:WORD_1
	v_cvt_f32_f16_sdwa v2, v2 dst_sel:DWORD dst_unused:UNUSED_PAD src0_sel:WORD_1
	v_mul_f32_e32 v6, 0.5, v6
	v_pk_add_f32 v[46:47], v[4:5], v[22:23]
	v_fma_f32 v4, v14, 0.5, -v22
	v_pk_add_f32 v[22:23], v[38:39], v[38:39] op_sel:[0,1] op_sel_hi:[0,1] neg_lo:[0,1] neg_hi:[0,1]
	v_pk_add_f32 v[38:39], v[6:7], v[22:23] op_sel_hi:[0,1] neg_hi:[0,1]
	v_mov_b32_e32 v14, v46
	v_mov_b32_e32 v15, v4
	v_pk_mul_f32 v[22:23], v[4:5], v[44:45] op_sel_hi:[0,1]
	v_pk_mul_f32 v[82:83], v[38:39], v[2:3]
	v_pk_mul_f32 v[46:47], v[46:47], v[2:3]
	v_pk_mul_f32 v[38:39], v[38:39], v[44:45]
	v_pk_fma_f32 v[98:99], v[14:15], v[44:45], v[82:83] neg_lo:[0,0,1] neg_hi:[0,0,1]
	v_pk_fma_f32 v[2:3], v[14:15], v[2:3], v[38:39] neg_lo:[0,0,1] neg_hi:[0,0,1]
	v_add_f32_e32 v4, v23, v83
	v_add_f32_e32 v6, v46, v38
	v_pk_add_f32 v[22:23], v[6:7], v[2:3] op_sel_hi:[0,1] neg_lo:[0,1] neg_hi:[0,1]
	v_pk_add_f32 v[38:39], v[98:99], v[4:5] op_sel_hi:[1,0] neg_lo:[0,1] neg_hi:[0,1]
	v_pk_add_f32 v[2:3], v[6:7], v[2:3] op_sel_hi:[0,1]
	v_mov_b32_e32 v39, v3
	v_pk_mul_f32 v[2:3], v[38:39], 0.5 op_sel_hi:[1,0]
	v_pk_add_f32 v[14:15], v[98:99], v[4:5] op_sel_hi:[1,0]
	v_mul_f32_e32 v4, v59, v3
	v_pk_fma_f32 v[38:39], v[42:43], v[2:3], v[4:5] op_sel_hi:[1,1,0] neg_lo:[0,0,1] neg_hi:[0,0,1]
	v_pk_mov_b32 v[42:43], v[58:59], v[8:9] op_sel:[1,0]
	v_mul_f32_e32 v4, v8, v3
	v_pk_fma_f32 v[2:3], v[42:43], v[2:3], v[4:5] op_sel_hi:[1,1,0]
	v_mov_b32_e32 v15, v23
	v_pk_fma_f32 v[8:9], v[14:15], 0.5, v[2:3] op_sel_hi:[1,0,1] neg_lo:[0,0,1] neg_hi:[0,0,1]
	v_pk_fma_f32 v[42:43], v[14:15], 0.5, v[38:39] op_sel_hi:[1,0,0]
	v_pk_fma_f32 v[2:3], v[14:15], 0.5, v[2:3] op_sel_hi:[1,0,1]
	v_mov_b32_e32 v9, v43
	v_pk_fma_f32 v[58:59], v[22:23], 0.5, v[38:39] op_sel_hi:[1,0,0] neg_lo:[1,0,0] neg_hi:[1,0,0]
	v_pk_mul_f32 v[144:145], v[8:9], s[6:7] op_sel_hi:[1,0]
	v_mov_b32_e32 v58, v2
	v_mov_b32_e32 v72, v10
	v_mov_b32_e32 v54, v40
	v_mov_b32_e32 v70, v20
	v_mov_b32_e32 v56, v26
	v_mov_b32_e32 v76, v36
	v_mov_b32_e32 v52, v34
	v_mov_b32_e32 v74, v86
	v_mov_b32_e32 v48, v84
	v_mov_b32_e32 v50, v60
	v_mov_b32_e32 v28, v66
	v_mov_b32_e32 v32, v96
	v_mov_b32_e32 v12, v88
	v_mov_b32_e32 v16, v92
	v_mov_b32_e32 v4, v138
	v_mov_b32_e32 v6, v122

.LBB0_534:
	v_mov_b32_e32 v2, v210
	s_mov_b32 s43, s8
	v_and_b32_e32 v3, 0xff, v2
	v_lshlrev_b32_e32 v4, 5, v2
	v_and_or_b32 v3, v4, s33, v3
	v_ashrrev_i32_e32 v4, 5, v3
	v_lshlrev_b32_e32 v3, 3, v3
	v_lshlrev_b32_e32 v4, 3, v4
	v_add3_u32 v18, 0, v3, v4
	ds_read_b64 v[128:129], v18
	ds_read_b64 v[132:133], v18 offset:2112
	ds_read_b64 v[134:135], v18 offset:4224
	ds_read_b64 v[136:137], v18 offset:6336
	ds_read_b64 v[138:139], v18 offset:8448
	ds_read_b64 v[140:141], v18 offset:10560
	ds_read_b64 v[142:143], v18 offset:12672
	ds_read_b64 v[130:131], v18 offset:14784
	ds_read_b64 v[144:145], v18 offset:16896
	ds_read_b64 v[148:149], v18 offset:19008
	ds_read_b64 v[150:151], v18 offset:21120
	ds_read_b64 v[152:153], v18 offset:23232
	s_waitcnt lgkmcnt(10)
	v_pk_mul_f32 v[162:163], v[132:133], s[10:11]
	s_mov_b32 s64, s11
	v_pk_fma_f32 v[162:163], v[132:133], s[8:9], v[162:163] op_sel:[0,0,1] op_sel_hi:[1,0,0]
	s_waitcnt lgkmcnt(2)
	v_pk_mul_f32 v[178:179], v[148:149], s[42:43]
	v_pk_add_f32 v[194:195], v[132:133], v[148:149]
	v_pk_add_f32 v[132:133], v[132:133], v[148:149] neg_lo:[0,1] neg_hi:[0,1]
	v_pk_mul_f32 v[164:165], v[134:135], s[18:19]
	s_mov_b32 s41, s16
	v_pk_fma_f32 v[178:179], v[148:149], s[64:65], v[178:179] op_sel:[0,0,1] op_sel_hi:[1,0,0] neg_lo:[1,0,0] neg_hi:[1,0,0]
	v_pk_mul_f32 v[148:149], v[132:133], s[18:19]
	v_pk_fma_f32 v[164:165], v[134:135], s[16:17], v[164:165] op_sel:[0,0,1] op_sel_hi:[1,0,0]
	s_mov_b32 s68, s19
	s_waitcnt lgkmcnt(1)
	v_pk_mul_f32 v[180:181], v[150:151], s[40:41]
	v_pk_fma_f32 v[132:133], v[132:133], s[16:17], v[148:149] op_sel:[0,0,1] op_sel_hi:[1,0,0]
	v_pk_add_f32 v[148:149], v[134:135], v[150:151]
	v_pk_add_f32 v[134:135], v[134:135], v[150:151] neg_lo:[0,1] neg_hi:[0,1]
	v_pk_mul_f32 v[166:167], v[136:137], s[26:27]
	s_mov_b32 s66, s37
	s_mov_b32 s39, s24
	v_pk_fma_f32 v[180:181], v[150:151], s[68:69], v[180:181] op_sel:[0,0,1] op_sel_hi:[1,0,0] neg_lo:[1,0,0] neg_hi:[1,0,0]
	v_pk_mul_f32 v[150:151], v[134:135], s[36:37]
	ds_read_b64 v[154:155], v18 offset:25344
	ds_read_b64 v[156:157], v18 offset:27456
	ds_read_b64 v[158:159], v18 offset:29568
	ds_read_b64 v[160:161], v18 offset:31680
	v_pk_fma_f32 v[166:167], v[136:137], s[24:25], v[166:167] op_sel:[0,0,1] op_sel_hi:[1,0,0]
	s_mov_b32 s0, s27
	s_waitcnt lgkmcnt(4)
	v_pk_mul_f32 v[182:183], v[152:153], s[38:39]
	v_pk_fma_f32 v[134:135], v[134:135], s[66:67], v[150:151] op_sel:[0,0,1] op_sel_hi:[1,0,0]
	v_pk_add_f32 v[150:151], v[136:137], v[152:153]
	v_pk_add_f32 v[136:137], v[136:137], v[152:153] neg_lo:[0,1] neg_hi:[0,1]
	v_pk_mul_f32 v[168:169], v[138:139], s[36:37]
	v_pk_fma_f32 v[182:183], v[152:153], s[0:1], v[182:183] op_sel:[0,0,1] op_sel_hi:[1,0,0] neg_lo:[1,0,0] neg_hi:[1,0,0]
	v_pk_mul_f32 v[152:153], v[136:137], s[40:41]
	v_pk_fma_f32 v[168:169], v[138:139], s[66:67], v[168:169] op_sel:[0,0,1] op_sel_hi:[1,0,0]
	v_pk_mul_f32 v[170:171], v[140:141], s[38:39]
	s_waitcnt lgkmcnt(3)
	v_pk_mul_f32 v[184:185], v[154:155], s[36:37]
	v_pk_fma_f32 v[136:137], v[136:137], s[68:69], v[152:153] op_sel:[0,0,1] op_sel_hi:[1,0,0]
	v_pk_add_f32 v[152:153], v[138:139], v[154:155]
	v_pk_add_f32 v[138:139], v[138:139], v[154:155] neg_lo:[0,1] neg_hi:[0,1]
	v_pk_fma_f32 v[170:171], v[140:141], s[0:1], v[170:171] op_sel:[0,0,1] op_sel_hi:[1,0,0]
	v_pk_fma_f32 v[184:185], v[154:155], s[66:67], v[184:185] op_sel:[0,0,1] op_sel_hi:[1,0,0] neg_lo:[1,0,0] neg_hi:[1,0,0]
	s_waitcnt lgkmcnt(2)
	v_pk_mul_f32 v[186:187], v[156:157], s[26:27]
	v_xor_b32_e32 v155, 0x80000000, v138
	v_mov_b32_e32 v154, v139
	v_pk_add_f32 v[138:139], v[140:141], v[156:157]
	v_pk_add_f32 v[140:141], v[140:141], v[156:157] neg_lo:[0,1] neg_hi:[0,1]
	v_pk_mul_f32 v[172:173], v[142:143], s[40:41]
	v_pk_fma_f32 v[186:187], v[156:157], s[24:25], v[186:187] op_sel:[0,0,1] op_sel_hi:[1,0,0] neg_lo:[1,0,0] neg_hi:[1,0,0]
	v_pk_mul_f32 v[156:157], v[140:141], s[40:41]
	v_pk_fma_f32 v[172:173], v[142:143], s[68:69], v[172:173] op_sel:[0,0,1] op_sel_hi:[1,0,0]
	s_waitcnt lgkmcnt(1)
	v_pk_mul_f32 v[188:189], v[158:159], s[18:19]
	v_pk_fma_f32 v[140:141], v[140:141], s[68:69], v[156:157] op_sel:[0,0,1] op_sel_hi:[1,0,0] neg_lo:[1,0,0] neg_hi:[1,0,0]
	v_pk_add_f32 v[156:157], v[142:143], v[158:159]
	v_pk_add_f32 v[142:143], v[142:143], v[158:159] neg_lo:[0,1] neg_hi:[0,1]
	v_pk_mul_f32 v[174:175], v[130:131], s[42:43]
	v_pk_fma_f32 v[188:189], v[158:159], s[16:17], v[188:189] op_sel:[0,0,1] op_sel_hi:[1,0,0] neg_lo:[1,0,0] neg_hi:[1,0,0]
	v_pk_mul_f32 v[158:159], v[142:143], s[36:37]
	v_pk_fma_f32 v[174:175], v[130:131], s[64:65], v[174:175] op_sel:[0,0,1] op_sel_hi:[1,0,0]
	s_waitcnt lgkmcnt(0)
	v_pk_mul_f32 v[190:191], v[160:161], s[10:11]
	v_pk_fma_f32 v[142:143], v[142:143], s[66:67], v[158:159] op_sel:[0,0,1] op_sel_hi:[1,0,0] neg_lo:[1,0,0] neg_hi:[1,0,0]
	v_pk_add_f32 v[158:159], v[130:131], v[160:161]
	v_pk_add_f32 v[130:131], v[130:131], v[160:161] neg_lo:[0,1] neg_hi:[0,1]
	v_xor_b32_e32 v177, 0x80000000, v144
	v_mov_b32_e32 v176, v145
	v_pk_fma_f32 v[190:191], v[160:161], s[8:9], v[190:191] op_sel:[0,0,1] op_sel_hi:[1,0,0] neg_lo:[1,0,0] neg_hi:[1,0,0]
	v_pk_mul_f32 v[160:161], v[130:131], s[18:19]
	v_pk_add_f32 v[192:193], v[128:129], v[144:145]
	v_pk_add_f32 v[144:145], v[128:129], v[144:145] neg_lo:[0,1] neg_hi:[0,1]
	v_pk_fma_f32 v[130:131], v[130:131], s[16:17], v[160:161] op_sel:[0,0,1] op_sel_hi:[1,0,0] neg_lo:[1,0,0] neg_hi:[1,0,0]
	v_pk_add_f32 v[160:161], v[128:129], v[176:177]
	v_pk_add_f32 v[128:129], v[128:129], v[176:177] neg_lo:[0,1] neg_hi:[0,1]
	v_pk_add_f32 v[176:177], v[162:163], v[178:179]
	v_pk_add_f32 v[162:163], v[162:163], v[178:179] neg_lo:[0,1] neg_hi:[0,1]
	v_cvt_f32_ubyte0_e32 v2, v2
	v_pk_mul_f32 v[178:179], v[162:163], s[18:19]
	v_mul_f32_e32 v2, 0x39000000, v2
	v_pk_fma_f32 v[162:163], v[162:163], s[16:17], v[178:179] op_sel:[0,0,1] op_sel_hi:[1,0,0]
	v_pk_add_f32 v[178:179], v[164:165], v[180:181]
	v_pk_add_f32 v[164:165], v[164:165], v[180:181] neg_lo:[0,1] neg_hi:[0,1]
	v_sin_f32_e32 v34, v2
	v_pk_mul_f32 v[180:181], v[164:165], s[36:37]
	v_cos_f32_e32 v30, v2
	v_pk_fma_f32 v[164:165], v[164:165], s[66:67], v[180:181] op_sel:[0,0,1] op_sel_hi:[1,0,0]
	v_pk_add_f32 v[180:181], v[166:167], v[182:183]
	v_pk_add_f32 v[166:167], v[166:167], v[182:183] neg_lo:[0,1] neg_hi:[0,1]
	v_xor_b32_e32 v31, 0x80000000, v34
	v_pk_mul_f32 v[182:183], v[166:167], s[40:41]
	v_mov_b32_e32 v35, v31
	v_pk_fma_f32 v[166:167], v[166:167], s[68:69], v[182:183] op_sel:[0,0,1] op_sel_hi:[1,0,0]
	v_pk_add_f32 v[182:183], v[168:169], v[184:185]
	v_pk_add_f32 v[184:185], v[168:169], v[184:185] neg_lo:[0,1] neg_hi:[0,1]
	v_pk_mul_f32 v[2:3], v[30:31], v[34:35] op_sel:[1,0] op_sel_hi:[0,1]
	v_pk_add_f32 v[168:169], v[170:171], v[186:187]
	v_pk_add_f32 v[170:171], v[170:171], v[186:187] neg_lo:[0,1] neg_hi:[0,1]
	v_pk_fma_f32 v[44:45], v[30:31], v[30:31], v[2:3] op_sel_hi:[1,0,1]
	v_pk_mul_f32 v[186:187], v[170:171], s[40:41]
	v_pk_mul_f32 v[2:3], v[34:35], v[44:45] op_sel:[0,1] op_sel_hi:[1,0]
	v_pk_fma_f32 v[170:171], v[170:171], s[68:69], v[186:187] op_sel:[0,0,1] op_sel_hi:[1,0,0] neg_lo:[1,0,0] neg_hi:[1,0,0]
	v_pk_add_f32 v[186:187], v[172:173], v[188:189]
	v_pk_add_f32 v[172:173], v[172:173], v[188:189] neg_lo:[0,1] neg_hi:[0,1]
	v_pk_mul_f32 v[188:189], v[172:173], s[36:37]
	v_pk_fma_f32 v[172:173], v[172:173], s[66:67], v[188:189] op_sel:[0,0,1] op_sel_hi:[1,0,0] neg_lo:[1,0,0] neg_hi:[1,0,0]
	v_pk_add_f32 v[188:189], v[174:175], v[190:191]
	v_pk_add_f32 v[174:175], v[174:175], v[190:191] neg_lo:[0,1] neg_hi:[0,1]
	v_pk_fma_f32 v[46:47], v[30:31], v[44:45], v[2:3] op_sel_hi:[0,1,1]
	v_pk_mul_f32 v[190:191], v[174:175], s[18:19]
	v_pk_mul_f32 v[2:3], v[44:45], v[44:45] op_sel:[1,1] op_sel_hi:[0,1] neg_lo:[0,1]
	v_pk_fma_f32 v[174:175], v[174:175], s[16:17], v[190:191] op_sel:[0,0,1] op_sel_hi:[1,0,0] neg_lo:[1,0,0] neg_hi:[1,0,0]
	v_pk_add_f32 v[190:191], v[192:193], v[152:153]
	v_pk_add_f32 v[152:153], v[192:193], v[152:153] neg_lo:[0,1] neg_hi:[0,1]
	v_pk_add_f32 v[192:193], v[194:195], v[138:139]
	v_pk_add_f32 v[138:139], v[194:195], v[138:139] neg_lo:[0,1] neg_hi:[0,1]
	v_pk_fma_f32 v[52:53], v[44:45], v[44:45], v[2:3] op_sel_hi:[1,0,1]
	v_pk_mul_f32 v[194:195], v[138:139], s[36:37]
	v_pk_fma_f32 v[138:139], v[138:139], s[66:67], v[194:195] op_sel:[0,0,1] op_sel_hi:[1,0,0]
	v_pk_add_f32 v[194:195], v[148:149], v[156:157]
	v_pk_add_f32 v[156:157], v[148:149], v[156:157] neg_lo:[0,1] neg_hi:[0,1]
	v_pk_add_f32 v[148:149], v[150:151], v[158:159]
	v_pk_add_f32 v[150:151], v[150:151], v[158:159] neg_lo:[0,1] neg_hi:[0,1]
	v_pk_mul_f32 v[2:3], v[52:53], v[52:53] op_sel:[1,1] op_sel_hi:[0,1] neg_lo:[0,1]
	v_pk_mul_f32 v[158:159], v[150:151], s[36:37]
	v_pk_fma_f32 v[48:49], v[52:53], v[52:53], v[2:3] op_sel_hi:[1,0,1]
	v_pk_fma_f32 v[150:151], v[150:151], s[66:67], v[158:159] op_sel:[0,0,1] op_sel_hi:[1,0,0] neg_lo:[1,0,0] neg_hi:[1,0,0]
	v_pk_add_f32 v[158:159], v[144:145], v[154:155]
	v_pk_add_f32 v[144:145], v[144:145], v[154:155] neg_lo:[0,1] neg_hi:[0,1]
	v_pk_add_f32 v[154:155], v[132:133], v[140:141]
	v_pk_add_f32 v[132:133], v[132:133], v[140:141] neg_lo:[0,1] neg_hi:[0,1]
	v_pk_mul_f32 v[2:3], v[52:53], v[48:49] op_sel:[1,1] op_sel_hi:[1,0] neg_lo:[1,0]
	v_pk_mul_f32 v[140:141], v[132:133], s[36:37]
	v_pk_fma_f32 v[36:37], v[52:53], v[48:49], v[2:3] op_sel_hi:[0,1,1]
	v_pk_fma_f32 v[132:133], v[132:133], s[66:67], v[140:141] op_sel:[0,0,1] op_sel_hi:[1,0,0]
	v_pk_add_f32 v[140:141], v[134:135], v[142:143]
	v_pk_add_f32 v[142:143], v[134:135], v[142:143] neg_lo:[0,1] neg_hi:[0,1]
	v_pk_mul_f32 v[2:3], v[52:53], v[36:37] op_sel:[1,1] op_sel_hi:[1,0] neg_lo:[1,0]
	v_pk_add_f32 v[134:135], v[136:137], v[130:131]
	v_pk_add_f32 v[130:131], v[136:137], v[130:131] neg_lo:[0,1] neg_hi:[0,1]
	v_pk_fma_f32 v[26:27], v[52:53], v[36:37], v[2:3] op_sel_hi:[0,1,1]
	v_pk_mul_f32 v[136:137], v[130:131], s[36:37]
	v_pk_mul_f32 v[2:3], v[52:53], v[26:27] op_sel:[1,1] op_sel_hi:[1,0] neg_lo:[1,0]
	v_pk_fma_f32 v[130:131], v[130:131], s[66:67], v[136:137] op_sel:[0,0,1] op_sel_hi:[1,0,0] neg_lo:[1,0,0] neg_hi:[1,0,0]
	v_pk_add_f32 v[136:137], v[160:161], v[182:183]
	v_pk_add_f32 v[160:161], v[160:161], v[182:183] neg_lo:[0,1] neg_hi:[0,1]
	v_pk_add_f32 v[182:183], v[176:177], v[168:169]
	v_pk_add_f32 v[168:169], v[176:177], v[168:169] neg_lo:[0,1] neg_hi:[0,1]
	v_pk_fma_f32 v[20:21], v[52:53], v[26:27], v[2:3] op_sel_hi:[0,1,1]
	v_pk_mul_f32 v[176:177], v[168:169], s[36:37]
	v_pk_mul_f32 v[2:3], v[52:53], v[20:21] op_sel:[1,1] op_sel_hi:[1,0] neg_lo:[1,0]
	v_pk_fma_f32 v[168:169], v[168:169], s[66:67], v[176:177] op_sel:[0,0,1] op_sel_hi:[1,0,0]
	v_pk_add_f32 v[176:177], v[178:179], v[186:187]
	v_pk_add_f32 v[186:187], v[178:179], v[186:187] neg_lo:[0,1] neg_hi:[0,1]
	v_pk_fma_f32 v[10:11], v[52:53], v[20:21], v[2:3] op_sel_hi:[0,1,1]
	v_pk_add_f32 v[178:179], v[180:181], v[188:189]
	v_pk_add_f32 v[180:181], v[180:181], v[188:189] neg_lo:[0,1] neg_hi:[0,1]
	v_pk_mul_f32 v[2:3], v[52:53], v[10:11] op_sel:[1,1] op_sel_hi:[1,0] neg_lo:[1,0]
	v_pk_mul_f32 v[188:189], v[180:181], s[36:37]
	v_pk_fma_f32 v[4:5], v[52:53], v[10:11], v[2:3] op_sel_hi:[0,1,1]
	v_pk_fma_f32 v[180:181], v[180:181], s[66:67], v[188:189] op_sel:[0,0,1] op_sel_hi:[1,0,0] neg_lo:[1,0,0] neg_hi:[1,0,0]
	v_pk_add_f32 v[188:189], v[128:129], v[184:185] op_sel:[0,1] op_sel_hi:[1,0] neg_hi:[0,1]
	v_pk_add_f32 v[128:129], v[128:129], v[184:185] op_sel:[0,1] op_sel_hi:[1,0] neg_lo:[0,1]
	v_pk_add_f32 v[184:185], v[162:163], v[170:171]
	v_pk_add_f32 v[162:163], v[162:163], v[170:171] neg_lo:[0,1] neg_hi:[0,1]
	v_pk_mul_f32 v[170:171], v[162:163], s[36:37]
	v_pk_fma_f32 v[162:163], v[162:163], s[66:67], v[170:171] op_sel:[0,0,1] op_sel_hi:[1,0,0]
	v_pk_add_f32 v[170:171], v[164:165], v[172:173]
	v_pk_add_f32 v[172:173], v[164:165], v[172:173] neg_lo:[0,1] neg_hi:[0,1]
	v_pk_mul_f32 v[2:3], v[46:47], v[4:5] op_sel:[1,1] op_sel_hi:[1,0] neg_lo:[1,0]
	v_pk_add_f32 v[164:165], v[166:167], v[174:175]
	v_pk_add_f32 v[166:167], v[166:167], v[174:175] neg_lo:[0,1] neg_hi:[0,1]
	v_pk_mul_f32 v[14:15], v[34:35], v[4:5] op_sel:[0,1] op_sel_hi:[1,0]
	v_pk_mul_f32 v[174:175], v[166:167], s[36:37]
	v_pk_mul_f32 v[40:41], v[34:35], v[10:11] op_sel:[0,1] op_sel_hi:[1,0]
	v_pk_fma_f32 v[166:167], v[166:167], s[66:67], v[174:175] op_sel:[0,0,1] op_sel_hi:[1,0,0] neg_lo:[1,0,0] neg_hi:[1,0,0]
	v_pk_add_f32 v[174:175], v[190:191], v[194:195]
	v_pk_add_f32 v[190:191], v[190:191], v[194:195] neg_lo:[0,1] neg_hi:[0,1]
	v_pk_add_f32 v[194:195], v[192:193], v[148:149]
	v_pk_add_f32 v[192:193], v[192:193], v[148:149] neg_lo:[0,1] neg_hi:[0,1]
	v_pk_mul_f32 v[66:67], v[34:35], v[20:21] op_sel:[0,1] op_sel_hi:[1,0]
	v_pk_add_f32 v[148:149], v[152:153], v[156:157] op_sel:[0,1] op_sel_hi:[1,0] neg_hi:[0,1]
	v_pk_add_f32 v[152:153], v[152:153], v[156:157] op_sel:[0,1] op_sel_hi:[1,0] neg_lo:[0,1]
	v_pk_add_f32 v[156:157], v[138:139], v[150:151]
	v_pk_add_f32 v[150:151], v[138:139], v[150:151] neg_lo:[0,1] neg_hi:[0,1]
	v_pk_mul_f32 v[82:83], v[34:35], v[26:27] op_sel:[0,1] op_sel_hi:[1,0]
	v_pk_add_f32 v[138:139], v[158:159], v[140:141]
	v_pk_add_f32 v[140:141], v[158:159], v[140:141] neg_lo:[0,1] neg_hi:[0,1]
	v_pk_add_f32 v[158:159], v[154:155], v[134:135]
	v_pk_add_f32 v[154:155], v[154:155], v[134:135] neg_lo:[0,1] neg_hi:[0,1]
	v_pk_mul_f32 v[96:97], v[34:35], v[36:37] op_sel:[0,1] op_sel_hi:[1,0]
	v_pk_add_f32 v[134:135], v[144:145], v[142:143] op_sel:[0,1] op_sel_hi:[1,0] neg_hi:[0,1]
	v_pk_add_f32 v[142:143], v[144:145], v[142:143] op_sel:[0,1] op_sel_hi:[1,0] neg_lo:[0,1]
	v_pk_add_f32 v[144:145], v[132:133], v[130:131]
	v_pk_add_f32 v[132:133], v[132:133], v[130:131] neg_lo:[0,1] neg_hi:[0,1]
	v_pk_mul_f32 v[110:111], v[34:35], v[48:49] op_sel:[0,1] op_sel_hi:[1,0]
	v_pk_add_f32 v[130:131], v[136:137], v[176:177]
	v_pk_add_f32 v[136:137], v[136:137], v[176:177] neg_lo:[0,1] neg_hi:[0,1]
	v_pk_add_f32 v[176:177], v[182:183], v[178:179]
	v_pk_add_f32 v[182:183], v[182:183], v[178:179] neg_lo:[0,1] neg_hi:[0,1]
	v_pk_mul_f32 v[124:125], v[34:35], v[52:53] op_sel:[0,1] op_sel_hi:[1,0]
	v_pk_add_f32 v[178:179], v[160:161], v[186:187] op_sel:[0,1] op_sel_hi:[1,0] neg_hi:[0,1]
	v_pk_add_f32 v[160:161], v[160:161], v[186:187] op_sel:[0,1] op_sel_hi:[1,0] neg_lo:[0,1]
	v_pk_add_f32 v[186:187], v[168:169], v[180:181]
	v_pk_add_f32 v[180:181], v[168:169], v[180:181] neg_lo:[0,1] neg_hi:[0,1]
	v_pk_fma_f32 v[2:3], v[46:47], v[4:5], v[2:3] op_sel_hi:[0,1,1]
	v_pk_add_f32 v[168:169], v[188:189], v[170:171]
	v_pk_add_f32 v[170:171], v[188:189], v[170:171] neg_lo:[0,1] neg_hi:[0,1]
	v_pk_add_f32 v[188:189], v[184:185], v[164:165]
	v_pk_add_f32 v[184:185], v[184:185], v[164:165] neg_lo:[0,1] neg_hi:[0,1]
	v_pk_mul_f32 v[8:9], v[44:45], v[4:5] op_sel:[1,1] op_sel_hi:[1,0] neg_lo:[1,0]
	v_pk_add_f32 v[164:165], v[128:129], v[172:173] op_sel:[0,1] op_sel_hi:[1,0] neg_hi:[0,1]
	v_pk_add_f32 v[128:129], v[128:129], v[172:173] op_sel:[0,1] op_sel_hi:[1,0] neg_lo:[0,1]
	v_pk_add_f32 v[172:173], v[162:163], v[166:167]
	v_pk_add_f32 v[166:167], v[162:163], v[166:167] neg_lo:[0,1] neg_hi:[0,1]
	v_pk_fma_f32 v[14:15], v[30:31], v[4:5], v[14:15] op_sel_hi:[0,1,1]
	v_pk_add_f32 v[162:163], v[174:175], v[194:195]
	v_pk_add_f32 v[174:175], v[174:175], v[194:195] neg_lo:[0,1] neg_hi:[0,1]
	v_pk_add_f32 v[194:195], v[190:191], v[192:193] op_sel:[0,1] op_sel_hi:[1,0] neg_hi:[0,1]
	v_pk_add_f32 v[190:191], v[190:191], v[192:193] op_sel:[0,1] op_sel_hi:[1,0] neg_lo:[0,1]
	v_pk_add_f32 v[192:193], v[148:149], v[156:157]
	v_pk_add_f32 v[148:149], v[148:149], v[156:157] neg_lo:[0,1] neg_hi:[0,1]
	v_pk_add_f32 v[156:157], v[152:153], v[150:151] op_sel:[0,1] op_sel_hi:[1,0] neg_hi:[0,1]
	v_pk_add_f32 v[150:151], v[152:153], v[150:151] op_sel:[0,1] op_sel_hi:[1,0] neg_lo:[0,1]
	v_pk_add_f32 v[152:153], v[138:139], v[158:159]
	v_pk_add_f32 v[138:139], v[138:139], v[158:159] neg_lo:[0,1] neg_hi:[0,1]
	v_pk_add_f32 v[158:159], v[140:141], v[154:155] op_sel:[0,1] op_sel_hi:[1,0] neg_hi:[0,1]
	v_pk_add_f32 v[140:141], v[140:141], v[154:155] op_sel:[0,1] op_sel_hi:[1,0] neg_lo:[0,1]
	v_pk_add_f32 v[154:155], v[134:135], v[144:145]
	v_pk_add_f32 v[134:135], v[134:135], v[144:145] neg_lo:[0,1] neg_hi:[0,1]
	v_pk_add_f32 v[144:145], v[142:143], v[132:133] op_sel:[0,1] op_sel_hi:[1,0] neg_hi:[0,1]
	v_pk_add_f32 v[132:133], v[142:143], v[132:133] op_sel:[0,1] op_sel_hi:[1,0] neg_lo:[0,1]
	v_pk_add_f32 v[142:143], v[130:131], v[176:177]
	v_pk_mul_f32 v[24:25], v[46:47], v[10:11] op_sel:[1,1] op_sel_hi:[1,0] neg_lo:[1,0]
	v_pk_mul_f32 v[34:35], v[34:35], v[142:143] op_sel:[0,1] op_sel_hi:[1,0]
	v_pk_mul_f32 v[32:33], v[44:45], v[10:11] op_sel:[1,1] op_sel_hi:[1,0] neg_lo:[1,0]
	v_pk_fma_f32 v[40:41], v[30:31], v[10:11], v[40:41] op_sel_hi:[0,1,1]
	v_pk_mul_f32 v[56:57], v[46:47], v[20:21] op_sel:[1,1] op_sel_hi:[1,0] neg_lo:[1,0]
	v_pk_mul_f32 v[62:63], v[44:45], v[20:21] op_sel:[1,1] op_sel_hi:[1,0] neg_lo:[1,0]
	v_pk_fma_f32 v[66:67], v[30:31], v[20:21], v[66:67] op_sel_hi:[0,1,1]
	v_pk_mul_f32 v[74:75], v[46:47], v[26:27] op_sel:[1,1] op_sel_hi:[1,0] neg_lo:[1,0]
	v_pk_mul_f32 v[78:79], v[44:45], v[26:27] op_sel:[1,1] op_sel_hi:[1,0] neg_lo:[1,0]
	v_pk_fma_f32 v[82:83], v[30:31], v[26:27], v[82:83] op_sel_hi:[0,1,1]
	v_pk_mul_f32 v[88:89], v[46:47], v[36:37] op_sel:[1,1] op_sel_hi:[1,0] neg_lo:[1,0]
	v_pk_mul_f32 v[92:93], v[44:45], v[36:37] op_sel:[1,1] op_sel_hi:[1,0] neg_lo:[1,0]
	v_pk_fma_f32 v[96:97], v[30:31], v[36:37], v[96:97] op_sel_hi:[0,1,1]
	v_pk_mul_f32 v[102:103], v[46:47], v[48:49] op_sel:[1,1] op_sel_hi:[1,0] neg_lo:[1,0]
	v_pk_mul_f32 v[106:107], v[44:45], v[48:49] op_sel:[1,1] op_sel_hi:[1,0] neg_lo:[1,0]
	v_pk_fma_f32 v[110:111], v[30:31], v[48:49], v[110:111] op_sel_hi:[0,1,1]
	v_pk_mul_f32 v[116:117], v[52:53], v[46:47] op_sel:[1,1] op_sel_hi:[0,1] neg_lo:[0,1]
	v_pk_mul_f32 v[120:121], v[44:45], v[52:53] op_sel:[1,1] op_sel_hi:[1,0] neg_lo:[1,0]
	v_pk_fma_f32 v[124:125], v[30:31], v[52:53], v[124:125] op_sel_hi:[0,1,1]
	v_pk_add_f32 v[130:131], v[130:131], v[176:177] neg_lo:[0,1] neg_hi:[0,1]
	v_pk_add_f32 v[176:177], v[136:137], v[182:183] op_sel:[0,1] op_sel_hi:[1,0] neg_hi:[0,1]
	v_pk_add_f32 v[136:137], v[136:137], v[182:183] op_sel:[0,1] op_sel_hi:[1,0] neg_lo:[0,1]
	v_pk_add_f32 v[182:183], v[178:179], v[186:187]
	v_pk_add_f32 v[178:179], v[178:179], v[186:187] neg_lo:[0,1] neg_hi:[0,1]
	v_pk_add_f32 v[186:187], v[160:161], v[180:181] op_sel:[0,1] op_sel_hi:[1,0] neg_hi:[0,1]
	v_pk_add_f32 v[160:161], v[160:161], v[180:181] op_sel:[0,1] op_sel_hi:[1,0] neg_lo:[0,1]
	v_pk_add_f32 v[180:181], v[168:169], v[188:189]
	v_pk_fma_f32 v[30:31], v[30:31], v[142:143], v[34:35] op_sel_hi:[0,1,1]
	v_pk_mul_f32 v[34:35], v[44:45], v[152:153] op_sel:[1,1] op_sel_hi:[1,0] neg_lo:[1,0]
	v_xor_b32_e32 v6, 0x80000000, v3
	v_pk_fma_f32 v[8:9], v[44:45], v[4:5], v[8:9] op_sel_hi:[0,1,1]
	v_pk_fma_f32 v[24:25], v[46:47], v[10:11], v[24:25] op_sel_hi:[0,1,1]
	v_pk_fma_f32 v[32:33], v[44:45], v[10:11], v[32:33] op_sel_hi:[0,1,1]
	v_pk_fma_f32 v[56:57], v[46:47], v[20:21], v[56:57] op_sel_hi:[0,1,1]
	v_pk_fma_f32 v[62:63], v[44:45], v[20:21], v[62:63] op_sel_hi:[0,1,1]
	v_pk_fma_f32 v[74:75], v[46:47], v[26:27], v[74:75] op_sel_hi:[0,1,1]
	v_pk_fma_f32 v[78:79], v[44:45], v[26:27], v[78:79] op_sel_hi:[0,1,1]
	v_pk_fma_f32 v[88:89], v[46:47], v[36:37], v[88:89] op_sel_hi:[0,1,1]
	v_pk_fma_f32 v[92:93], v[44:45], v[36:37], v[92:93] op_sel_hi:[0,1,1]
	v_pk_fma_f32 v[102:103], v[46:47], v[48:49], v[102:103] op_sel_hi:[0,1,1]
	v_pk_fma_f32 v[106:107], v[44:45], v[48:49], v[106:107] op_sel_hi:[0,1,1]
	v_pk_fma_f32 v[116:117], v[52:53], v[46:47], v[116:117] op_sel_hi:[1,0,1]
	v_pk_fma_f32 v[120:121], v[44:45], v[52:53], v[120:121] op_sel_hi:[0,1,1]
	v_mov_b32_e32 v7, v3
	v_pk_add_f32 v[168:169], v[168:169], v[188:189] neg_lo:[0,1] neg_hi:[0,1]
	v_pk_add_f32 v[188:189], v[170:171], v[184:185] op_sel:[0,1] op_sel_hi:[1,0] neg_hi:[0,1]
	v_pk_add_f32 v[170:171], v[170:171], v[184:185] op_sel:[0,1] op_sel_hi:[1,0] neg_lo:[0,1]
	v_pk_add_f32 v[184:185], v[164:165], v[172:173]
	v_pk_add_f32 v[164:165], v[164:165], v[172:173] neg_lo:[0,1] neg_hi:[0,1]
	v_pk_add_f32 v[172:173], v[128:129], v[166:167] op_sel:[0,1] op_sel_hi:[1,0] neg_hi:[0,1]
	v_pk_add_f32 v[128:129], v[128:129], v[166:167] op_sel:[0,1] op_sel_hi:[1,0] neg_lo:[0,1]
	v_pk_fma_f32 v[34:35], v[44:45], v[152:153], v[34:35] op_sel_hi:[0,1,1]
	v_pk_mul_f32 v[44:45], v[46:47], v[180:181] op_sel:[1,1] op_sel_hi:[1,0] neg_lo:[1,0]
	v_xor_b32_e32 v12, 0x80000000, v9
	v_xor_b32_e32 v16, 0x80000000, v15
	v_xor_b32_e32 v22, 0x80000000, v5
	v_xor_b32_e32 v28, 0x80000000, v25
	v_xor_b32_e32 v38, 0x80000000, v33
	v_xor_b32_e32 v42, 0x80000000, v41
	v_xor_b32_e32 v50, 0x80000000, v11
	v_xor_b32_e32 v60, 0x80000000, v57
	v_xor_b32_e32 v64, 0x80000000, v63
	v_xor_b32_e32 v68, 0x80000000, v67
	v_xor_b32_e32 v70, 0x80000000, v21
	v_xor_b32_e32 v76, 0x80000000, v75
	v_xor_b32_e32 v80, 0x80000000, v79
	v_xor_b32_e32 v84, 0x80000000, v83
	v_xor_b32_e32 v86, 0x80000000, v27
	v_xor_b32_e32 v90, 0x80000000, v89
	v_xor_b32_e32 v94, 0x80000000, v93
	v_xor_b32_e32 v98, 0x80000000, v97
	v_xor_b32_e32 v100, 0x80000000, v37
	v_xor_b32_e32 v104, 0x80000000, v103
	v_xor_b32_e32 v108, 0x80000000, v107
	v_mov_b32_e32 v109, v107
	v_mov_b32_e32 v105, v103
	v_mov_b32_e32 v101, v37
	v_mov_b32_e32 v99, v97
	v_mov_b32_e32 v95, v93
	v_mov_b32_e32 v91, v89
	v_mov_b32_e32 v87, v27
	v_mov_b32_e32 v85, v83
	v_mov_b32_e32 v81, v79
	v_mov_b32_e32 v77, v75
	v_mov_b32_e32 v71, v21
	v_mov_b32_e32 v69, v67
	v_mov_b32_e32 v65, v63
	v_mov_b32_e32 v61, v57
	v_mov_b32_e32 v51, v11
	v_mov_b32_e32 v43, v41
	v_mov_b32_e32 v39, v33
	v_mov_b32_e32 v29, v25
	v_mov_b32_e32 v23, v5
	v_mov_b32_e32 v17, v15
	v_mov_b32_e32 v13, v9
	v_pk_fma_f32 v[44:45], v[46:47], v[180:181], v[44:45] op_sel_hi:[0,1,1]
	v_pk_mul_f32 v[46:47], v[52:53], v[192:193] op_sel:[1,1] op_sel_hi:[1,0] neg_lo:[1,0]
	v_pk_mul_f32 v[72:73], v[48:49], v[194:195] op_sel:[1,1] op_sel_hi:[1,0] neg_lo:[1,0]
	v_pk_mul_f32 v[6:7], v[128:129], v[6:7] op_sel:[1,0] op_sel_hi:[0,1]
	v_pk_fma_f32 v[46:47], v[52:53], v[192:193], v[46:47] op_sel_hi:[0,1,1]
	v_pk_mul_f32 v[52:53], v[124:125], v[182:183] op_sel:[1,1] op_sel_hi:[1,0] neg_lo:[1,0]
	v_pk_mul_f32 v[54:55], v[120:121], v[154:155] op_sel:[1,1] op_sel_hi:[1,0] neg_lo:[1,0]
	v_pk_mul_f32 v[58:59], v[116:117], v[184:185] op_sel:[1,1] op_sel_hi:[1,0] neg_lo:[1,0]
	v_pk_fma_f32 v[48:49], v[48:49], v[194:195], v[72:73] op_sel_hi:[0,1,1]
	v_pk_mul_f32 v[72:73], v[110:111], v[176:177] op_sel:[1,1] op_sel_hi:[1,0] neg_lo:[1,0]
	v_pk_mul_f32 v[108:109], v[108:109], v[158:159] op_sel:[0,1] op_sel_hi:[1,0]
	v_pk_mul_f32 v[104:105], v[104:105], v[188:189] op_sel:[0,1] op_sel_hi:[1,0]
	v_pk_mul_f32 v[100:101], v[100:101], v[156:157] op_sel:[0,1] op_sel_hi:[1,0]
	v_pk_mul_f32 v[98:99], v[98:99], v[186:187] op_sel:[0,1] op_sel_hi:[1,0]
	v_pk_mul_f32 v[94:95], v[94:95], v[144:145] op_sel:[0,1] op_sel_hi:[1,0]
	v_pk_mul_f32 v[90:91], v[90:91], v[172:173] op_sel:[0,1] op_sel_hi:[1,0]
	v_pk_mul_f32 v[86:87], v[174:175], v[86:87] op_sel:[1,0] op_sel_hi:[0,1]
	v_pk_mul_f32 v[84:85], v[130:131], v[84:85] op_sel:[1,0] op_sel_hi:[0,1]
	v_pk_mul_f32 v[80:81], v[138:139], v[80:81] op_sel:[1,0] op_sel_hi:[0,1]
	v_pk_mul_f32 v[76:77], v[168:169], v[76:77] op_sel:[1,0] op_sel_hi:[0,1]
	v_pk_mul_f32 v[70:71], v[148:149], v[70:71] op_sel:[1,0] op_sel_hi:[0,1]
	v_pk_mul_f32 v[68:69], v[178:179], v[68:69] op_sel:[1,0] op_sel_hi:[0,1]
	v_pk_mul_f32 v[64:65], v[134:135], v[64:65] op_sel:[1,0] op_sel_hi:[0,1]
	v_pk_mul_f32 v[60:61], v[164:165], v[60:61] op_sel:[1,0] op_sel_hi:[0,1]
	v_pk_mul_f32 v[50:51], v[190:191], v[50:51] op_sel:[1,0] op_sel_hi:[0,1]
	v_pk_mul_f32 v[42:43], v[136:137], v[42:43] op_sel:[1,0] op_sel_hi:[0,1]
	v_pk_mul_f32 v[38:39], v[140:141], v[38:39] op_sel:[1,0] op_sel_hi:[0,1]
	v_pk_mul_f32 v[28:29], v[170:171], v[28:29] op_sel:[1,0] op_sel_hi:[0,1]
	v_pk_mul_f32 v[22:23], v[150:151], v[22:23] op_sel:[1,0] op_sel_hi:[0,1]
	v_pk_mul_f32 v[16:17], v[160:161], v[16:17] op_sel:[1,0] op_sel_hi:[0,1]
	v_pk_mul_f32 v[12:13], v[132:133], v[12:13] op_sel:[1,0] op_sel_hi:[0,1]
	v_pk_fma_f32 v[2:3], v[128:129], v[2:3], v[6:7] op_sel_hi:[1,0,1]
	v_pk_fma_f32 v[52:53], v[124:125], v[182:183], v[52:53] op_sel_hi:[0,1,1]
	v_pk_fma_f32 v[54:55], v[120:121], v[154:155], v[54:55] op_sel_hi:[0,1,1]
	v_pk_fma_f32 v[58:59], v[116:117], v[184:185], v[58:59] op_sel_hi:[0,1,1]
	v_pk_fma_f32 v[72:73], v[110:111], v[176:177], v[72:73] op_sel_hi:[0,1,1]
	v_pk_fma_f32 v[106:107], v[106:107], v[158:159], v[108:109] op_sel_hi:[0,1,1]
	v_pk_fma_f32 v[102:103], v[102:103], v[188:189], v[104:105] op_sel_hi:[0,1,1]
	v_pk_fma_f32 v[36:37], v[36:37], v[156:157], v[100:101] op_sel_hi:[0,1,1]
	v_pk_fma_f32 v[96:97], v[96:97], v[186:187], v[98:99] op_sel_hi:[0,1,1]
	v_pk_fma_f32 v[92:93], v[92:93], v[144:145], v[94:95] op_sel_hi:[0,1,1]
	v_pk_fma_f32 v[88:89], v[88:89], v[172:173], v[90:91] op_sel_hi:[0,1,1]
	v_pk_fma_f32 v[26:27], v[174:175], v[26:27], v[86:87] op_sel_hi:[1,0,1]
	v_pk_fma_f32 v[82:83], v[130:131], v[82:83], v[84:85] op_sel_hi:[1,0,1]
	v_pk_fma_f32 v[78:79], v[138:139], v[78:79], v[80:81] op_sel_hi:[1,0,1]
	v_pk_fma_f32 v[74:75], v[168:169], v[74:75], v[76:77] op_sel_hi:[1,0,1]
	v_pk_fma_f32 v[20:21], v[148:149], v[20:21], v[70:71] op_sel_hi:[1,0,1]
	v_pk_fma_f32 v[66:67], v[178:179], v[66:67], v[68:69] op_sel_hi:[1,0,1]
	v_pk_fma_f32 v[62:63], v[134:135], v[62:63], v[64:65] op_sel_hi:[1,0,1]
	v_pk_fma_f32 v[56:57], v[164:165], v[56:57], v[60:61] op_sel_hi:[1,0,1]
	v_pk_fma_f32 v[10:11], v[190:191], v[10:11], v[50:51] op_sel_hi:[1,0,1]
	v_pk_fma_f32 v[40:41], v[136:137], v[40:41], v[42:43] op_sel_hi:[1,0,1]
	v_pk_fma_f32 v[32:33], v[140:141], v[32:33], v[38:39] op_sel_hi:[1,0,1]
	v_pk_fma_f32 v[24:25], v[170:171], v[24:25], v[28:29] op_sel_hi:[1,0,1]
	v_pk_fma_f32 v[4:5], v[150:151], v[4:5], v[22:23] op_sel_hi:[1,0,1]
	v_pk_fma_f32 v[14:15], v[160:161], v[14:15], v[16:17] op_sel_hi:[1,0,1]
	v_pk_fma_f32 v[8:9], v[132:133], v[8:9], v[12:13] op_sel_hi:[1,0,1]
	ds_write_b64 v18, v[162:163]
	ds_write_b64 v18, v[26:27] offset:2112
	ds_write_b64 v18, v[48:49] offset:4224
	ds_write_b64 v18, v[10:11] offset:6336
	ds_write_b64 v18, v[46:47] offset:8448
	ds_write_b64 v18, v[20:21] offset:10560
	ds_write_b64 v18, v[36:37] offset:12672
	ds_write_b64 v18, v[4:5] offset:14784
	ds_write_b64 v18, v[34:35] offset:16896
	ds_write_b64 v18, v[78:79] offset:19008
	ds_write_b64 v18, v[106:107] offset:21120
	ds_write_b64 v18, v[32:33] offset:23232
	ds_write_b64 v18, v[54:55] offset:25344
	ds_write_b64 v18, v[62:63] offset:27456
	ds_write_b64 v18, v[92:93] offset:29568
	ds_write_b64 v18, v[8:9] offset:31680
	ds_write_b64 v18, v[30:31] offset:33792
	ds_write_b64 v18, v[82:83] offset:35904
	ds_write_b64 v18, v[72:73] offset:38016
	ds_write_b64 v18, v[40:41] offset:40128
	ds_write_b64 v18, v[52:53] offset:42240
	ds_write_b64 v18, v[66:67] offset:44352
	ds_write_b64 v18, v[96:97] offset:46464
	ds_write_b64 v18, v[14:15] offset:48576
	ds_write_b64 v18, v[44:45] offset:50688
	ds_write_b64 v18, v[74:75] offset:52800
	ds_write_b64 v18, v[102:103] offset:54912
	ds_write_b64 v18, v[24:25] offset:57024
	ds_write_b64 v18, v[58:59] offset:59136
	ds_write_b64 v18, v[56:57] offset:61248
	ds_write_b64 v18, v[88:89] offset:63360
	ds_write_b64 v18, v[2:3] offset:65472
	v_mov_b32_e32 v3, v210
	s_waitcnt lgkmcnt(0)
	s_barrier
	s_add_i32 s64, s62, s48
	v_and_b32_e32 v5, 15, v3
	v_cvt_f32_ubyte0_e32 v2, v5
	v_mul_f32_e32 v4, 0x3b800000, v2
	v_sin_f32_e32 v2, v4
	v_cos_f32_e32 v4, v4
	v_lshlrev_b32_e32 v64, 3, v5
	v_lshlrev_b32_e32 v18, 4, v3
	v_xor_b32_e32 v5, 0x80000000, v2
	v_mov_b32_e32 v3, v5
	v_pk_mul_f32 v[6:7], v[4:5], v[2:3] op_sel:[1,0] op_sel_hi:[0,1]
	v_pk_fma_f32 v[6:7], v[4:5], v[4:5], v[6:7] op_sel_hi:[1,0,1]
	s_ashr_i32 s65, s64, 31
	s_nop 0
	s_nop 0
	v_pk_mul_f32 v[10:11], v[6:7], v[6:7] op_sel:[1,1] op_sel_hi:[0,1] neg_lo:[0,1]
	v_pk_fma_f32 v[10:11], v[6:7], v[6:7], v[10:11] op_sel_hi:[1,0,1]
	v_pk_mul_f32 v[8:9], v[2:3], v[6:7] op_sel:[0,1] op_sel_hi:[1,0]
	v_pk_mul_f32 v[32:33], v[10:11], v[10:11] op_sel:[1,1] op_sel_hi:[0,1] neg_lo:[0,1]
	v_pk_fma_f32 v[32:33], v[10:11], v[10:11], v[32:33] op_sel_hi:[1,0,1]
	v_pk_mul_f32 v[16:17], v[2:3], v[10:11] op_sel:[0,1] op_sel_hi:[1,0]
	v_pk_mul_f32 v[48:49], v[10:11], v[32:33] op_sel:[1,1] op_sel_hi:[1,0] neg_lo:[1,0]
	v_pk_mul_f32 v[36:37], v[2:3], v[32:33] op_sel:[0,1] op_sel_hi:[1,0]
	v_pk_fma_f32 v[48:49], v[10:11], v[32:33], v[48:49] op_sel_hi:[0,1,1]
	v_pk_mul_f32 v[52:53], v[2:3], v[48:49] op_sel:[0,1] op_sel_hi:[1,0]
	v_pk_fma_f32 v[8:9], v[4:5], v[6:7], v[8:9] op_sel_hi:[0,1,1]
	v_pk_fma_f32 v[16:17], v[4:5], v[10:11], v[16:17] op_sel_hi:[0,1,1]
	v_pk_fma_f32 v[36:37], v[4:5], v[32:33], v[36:37] op_sel_hi:[0,1,1]
	v_pk_fma_f32 v[52:53], v[4:5], v[48:49], v[52:53] op_sel_hi:[0,1,1]
	v_and_b32_e32 v5, 0xffffff00, v18
	v_lshlrev_b32_e32 v18, 3, v5
	v_add3_u32 v18, 0, v64, v18
	v_ashrrev_i32_e32 v64, 2, v5
	v_add_u32_e32 v106, v18, v64
	ds_read2_b64 v[64:67], v106 offset1:16
	ds_read2_b64 v[68:71], v106 offset0:33 offset1:49
	ds_read2_b64 v[72:75], v106 offset0:66 offset1:82
	ds_read2_b64 v[76:79], v106 offset0:132 offset1:148
	ds_read2_b64 v[80:83], v106 offset0:99 offset1:115
	ds_read2_b64 v[84:87], v106 offset0:165 offset1:181
	ds_read2_b64 v[88:91], v106 offset0:198 offset1:214
	ds_read2_b64 v[92:95], v106 offset0:231 offset1:247
	s_waitcnt lgkmcnt(4)
	v_pk_add_f32 v[96:97], v[64:65], v[76:77]
	v_pk_add_f32 v[64:65], v[64:65], v[76:77] neg_lo:[0,1] neg_hi:[0,1]
	v_pk_add_f32 v[76:77], v[66:67], v[78:79]
	v_pk_add_f32 v[66:67], v[66:67], v[78:79] neg_lo:[0,1] neg_hi:[0,1]
	s_waitcnt lgkmcnt(1)
	v_pk_add_f32 v[98:99], v[74:75], v[90:91]
	v_pk_mul_f32 v[78:79], v[66:67], s[18:19]
	v_pk_add_f32 v[74:75], v[74:75], v[90:91] neg_lo:[0,1] neg_hi:[0,1]
	v_pk_fma_f32 v[66:67], v[66:67], s[16:17], v[78:79] op_sel:[0,0,1] op_sel_hi:[1,0,0]
	v_pk_add_f32 v[78:79], v[68:69], v[84:85]
	v_pk_add_f32 v[68:69], v[68:69], v[84:85] neg_lo:[0,1] neg_hi:[0,1]
	v_pk_mul_f32 v[90:91], v[74:75], s[40:41]
	v_pk_mul_f32 v[84:85], v[68:69], s[36:37]
	v_pk_fma_f32 v[74:75], v[74:75], s[68:69], v[90:91] op_sel:[0,0,1] op_sel_hi:[1,0,0] neg_lo:[1,0,0] neg_hi:[1,0,0]
	v_pk_fma_f32 v[68:69], v[68:69], s[66:67], v[84:85] op_sel:[0,0,1] op_sel_hi:[1,0,0]
	v_pk_add_f32 v[84:85], v[70:71], v[86:87]
	v_pk_add_f32 v[70:71], v[70:71], v[86:87] neg_lo:[0,1] neg_hi:[0,1]
	s_waitcnt lgkmcnt(0)
	v_pk_add_f32 v[90:91], v[80:81], v[92:93]
	v_pk_add_f32 v[80:81], v[80:81], v[92:93] neg_lo:[0,1] neg_hi:[0,1]
	v_pk_mul_f32 v[86:87], v[70:71], s[40:41]
	v_pk_mul_f32 v[92:93], v[80:81], s[36:37]
	v_pk_fma_f32 v[70:71], v[70:71], s[68:69], v[86:87] op_sel:[0,0,1] op_sel_hi:[1,0,0]
	v_pk_add_f32 v[86:87], v[72:73], v[88:89]
	v_pk_add_f32 v[88:89], v[72:73], v[88:89] neg_lo:[0,1] neg_hi:[0,1]
	v_pk_fma_f32 v[80:81], v[80:81], s[66:67], v[92:93] op_sel:[0,0,1] op_sel_hi:[1,0,0] neg_lo:[1,0,0] neg_hi:[1,0,0]
	v_pk_add_f32 v[92:93], v[82:83], v[94:95]
	v_pk_add_f32 v[82:83], v[82:83], v[94:95] neg_lo:[0,1] neg_hi:[0,1]
	v_pk_mul_f32 v[94:95], v[82:83], s[18:19]
	v_pk_fma_f32 v[82:83], v[82:83], s[16:17], v[94:95] op_sel:[0,0,1] op_sel_hi:[1,0,0] neg_lo:[1,0,0] neg_hi:[1,0,0]
	v_pk_add_f32 v[94:95], v[96:97], v[86:87]
	v_pk_add_f32 v[86:87], v[96:97], v[86:87] neg_lo:[0,1] neg_hi:[0,1]
	v_pk_add_f32 v[96:97], v[76:77], v[98:99]
	v_pk_add_f32 v[76:77], v[76:77], v[98:99] neg_lo:[0,1] neg_hi:[0,1]
	v_pk_add_f32 v[100:101], v[84:85], v[92:93]
	v_pk_add_f32 v[84:85], v[84:85], v[92:93] neg_lo:[0,1] neg_hi:[0,1]
	v_pk_add_f32 v[72:73], v[64:65], v[88:89] op_sel:[0,1] op_sel_hi:[1,0] neg_hi:[0,1]
	v_pk_add_f32 v[64:65], v[64:65], v[88:89] op_sel:[0,1] op_sel_hi:[1,0] neg_lo:[0,1]
	v_pk_add_f32 v[88:89], v[66:67], v[74:75]
	v_pk_add_f32 v[66:67], v[66:67], v[74:75] neg_lo:[0,1] neg_hi:[0,1]
	v_pk_mul_f32 v[98:99], v[76:77], s[36:37]
	v_pk_mul_f32 v[92:93], v[84:85], s[36:37]
	v_pk_mul_f32 v[74:75], v[66:67], s[36:37]
	v_pk_fma_f32 v[76:77], v[76:77], s[66:67], v[98:99] op_sel:[0,0,1] op_sel_hi:[1,0,0]
	v_pk_add_f32 v[98:99], v[78:79], v[90:91]
	v_pk_add_f32 v[90:91], v[78:79], v[90:91] neg_lo:[0,1] neg_hi:[0,1]
	v_pk_fma_f32 v[84:85], v[84:85], s[66:67], v[92:93] op_sel:[0,0,1] op_sel_hi:[1,0,0] neg_lo:[1,0,0] neg_hi:[1,0,0]
	v_pk_fma_f32 v[66:67], v[66:67], s[66:67], v[74:75] op_sel:[0,0,1] op_sel_hi:[1,0,0]
	v_pk_add_f32 v[74:75], v[68:69], v[80:81]
	v_pk_add_f32 v[92:93], v[70:71], v[82:83]
	v_pk_add_f32 v[70:71], v[70:71], v[82:83] neg_lo:[0,1] neg_hi:[0,1]
	v_pk_add_f32 v[68:69], v[68:69], v[80:81] neg_lo:[0,1] neg_hi:[0,1]
	v_pk_mul_f32 v[82:83], v[70:71], s[36:37]
	v_pk_add_f32 v[102:103], v[72:73], v[74:75]
	v_pk_add_f32 v[72:73], v[72:73], v[74:75] neg_lo:[0,1] neg_hi:[0,1]
	v_pk_add_f32 v[74:75], v[88:89], v[92:93]
	v_pk_add_f32 v[92:93], v[88:89], v[92:93] neg_lo:[0,1] neg_hi:[0,1]
	v_pk_mul_f32 v[24:25], v[6:7], v[10:11] op_sel:[1,1] op_sel_hi:[1,0] neg_lo:[1,0]
	v_xor_b32_e32 v81, 0x80000000, v68
	v_pk_fma_f32 v[70:71], v[70:71], s[66:67], v[82:83] op_sel:[0,0,1] op_sel_hi:[1,0,0] neg_lo:[1,0,0] neg_hi:[1,0,0]
	v_pk_add_f32 v[78:79], v[86:87], v[90:91] op_sel:[0,1] op_sel_hi:[1,0] neg_hi:[0,1]
	v_pk_add_f32 v[86:87], v[86:87], v[90:91] op_sel:[0,1] op_sel_hi:[1,0] neg_lo:[0,1]
	v_pk_add_f32 v[90:91], v[76:77], v[84:85]
	v_pk_add_f32 v[84:85], v[76:77], v[84:85] neg_lo:[0,1] neg_hi:[0,1]
	v_mov_b32_e32 v80, v69
	v_pk_fma_f32 v[24:25], v[6:7], v[10:11], v[24:25] op_sel_hi:[0,1,1]
	v_pk_mul_f32 v[28:29], v[10:11], v[8:9] op_sel:[1,1] op_sel_hi:[0,1] neg_lo:[0,1]
	v_pk_add_f32 v[68:69], v[64:65], v[80:81]
	v_pk_add_f32 v[64:65], v[64:65], v[80:81] neg_lo:[0,1] neg_hi:[0,1]
	v_pk_add_f32 v[80:81], v[66:67], v[70:71]
	v_pk_add_f32 v[70:71], v[66:67], v[70:71] neg_lo:[0,1] neg_hi:[0,1]
	v_pk_add_f32 v[88:89], v[72:73], v[92:93] op_sel:[0,1] op_sel_hi:[1,0] neg_hi:[0,1]
	v_pk_fma_f32 v[28:29], v[10:11], v[8:9], v[28:29] op_sel_hi:[1,0,1]
	v_pk_add_f32 v[76:77], v[86:87], v[84:85] op_sel:[0,1] op_sel_hi:[1,0] neg_hi:[0,1]
	v_pk_add_f32 v[72:73], v[72:73], v[92:93] op_sel:[0,1] op_sel_hi:[1,0] neg_lo:[0,1]
	v_pk_mul_f32 v[92:93], v[16:17], v[88:89] op_sel:[1,1] op_sel_hi:[1,0] neg_lo:[1,0]
	v_pk_add_f32 v[82:83], v[94:95], v[98:99]
	v_pk_add_f32 v[94:95], v[94:95], v[98:99] neg_lo:[0,1] neg_hi:[0,1]
	v_pk_add_f32 v[98:99], v[96:97], v[100:101]
	v_pk_add_f32 v[66:67], v[64:65], v[70:71] op_sel:[0,1] op_sel_hi:[1,0] neg_hi:[0,1]
	v_pk_fma_f32 v[88:89], v[16:17], v[88:89], v[92:93] op_sel_hi:[0,1,1]
	v_pk_mul_f32 v[92:93], v[24:25], v[76:77] op_sel:[1,1] op_sel_hi:[1,0] neg_lo:[1,0]
	v_pk_mul_f32 v[40:41], v[6:7], v[32:33] op_sel:[1,1] op_sel_hi:[1,0] neg_lo:[1,0]
	v_pk_add_f32 v[104:105], v[82:83], v[98:99]
	v_pk_add_f32 v[82:83], v[82:83], v[98:99] neg_lo:[0,1] neg_hi:[0,1]
	v_pk_fma_f32 v[76:77], v[24:25], v[76:77], v[92:93] op_sel_hi:[0,1,1]
	v_pk_mul_f32 v[92:93], v[28:29], v[66:67] op_sel:[1,1] op_sel_hi:[1,0] neg_lo:[1,0]
	v_pk_fma_f32 v[40:41], v[6:7], v[32:33], v[40:41] op_sel_hi:[0,1,1]
	v_pk_mul_f32 v[44:45], v[8:9], v[32:33] op_sel:[1,1] op_sel_hi:[1,0] neg_lo:[1,0]
	v_pk_add_f32 v[84:85], v[86:87], v[84:85] op_sel:[0,1] op_sel_hi:[1,0] neg_lo:[0,1]
	v_pk_add_f32 v[86:87], v[102:103], v[74:75]
	v_pk_add_f32 v[74:75], v[102:103], v[74:75] neg_lo:[0,1] neg_hi:[0,1]
	v_pk_fma_f32 v[66:67], v[28:29], v[66:67], v[92:93] op_sel_hi:[0,1,1]
	v_pk_mul_f32 v[92:93], v[32:33], v[82:83] op_sel:[1,1] op_sel_hi:[1,0] neg_lo:[1,0]
	v_pk_fma_f32 v[44:45], v[8:9], v[32:33], v[44:45] op_sel_hi:[0,1,1]
	v_pk_add_f32 v[100:101], v[96:97], v[100:101] neg_lo:[0,1] neg_hi:[0,1]
	v_pk_add_f32 v[98:99], v[78:79], v[90:91]
	v_pk_add_f32 v[78:79], v[78:79], v[90:91] neg_lo:[0,1] neg_hi:[0,1]
	v_pk_fma_f32 v[82:83], v[32:33], v[82:83], v[92:93] op_sel_hi:[0,1,1]
	v_pk_mul_f32 v[92:93], v[36:37], v[74:75] op_sel:[1,1] op_sel_hi:[1,0] neg_lo:[1,0]
	v_pk_add_f32 v[90:91], v[68:69], v[80:81]
	v_pk_add_f32 v[68:69], v[68:69], v[80:81] neg_lo:[0,1] neg_hi:[0,1]
	v_pk_fma_f32 v[74:75], v[36:37], v[74:75], v[92:93] op_sel_hi:[0,1,1]
	v_pk_mul_f32 v[92:93], v[40:41], v[78:79] op_sel:[1,1] op_sel_hi:[1,0] neg_lo:[1,0]
	v_pk_mul_f32 v[56:57], v[6:7], v[48:49] op_sel:[1,1] op_sel_hi:[1,0] neg_lo:[1,0]
	v_pk_add_f32 v[96:97], v[94:95], v[100:101] op_sel:[0,1] op_sel_hi:[1,0] neg_hi:[0,1]
	v_pk_add_f32 v[94:95], v[94:95], v[100:101] op_sel:[0,1] op_sel_hi:[1,0] neg_lo:[0,1]
	v_pk_fma_f32 v[78:79], v[40:41], v[78:79], v[92:93] op_sel_hi:[0,1,1]
	v_pk_mul_f32 v[92:93], v[44:45], v[68:69] op_sel:[1,1] op_sel_hi:[1,0] neg_lo:[1,0]
	v_pk_fma_f32 v[56:57], v[6:7], v[48:49], v[56:57] op_sel_hi:[0,1,1]
	v_pk_mul_f32 v[60:61], v[8:9], v[48:49] op_sel:[1,1] op_sel_hi:[1,0] neg_lo:[1,0]
	v_pk_fma_f32 v[68:69], v[44:45], v[68:69], v[92:93] op_sel_hi:[0,1,1]
	v_pk_mul_f32 v[92:93], v[48:49], v[94:95] op_sel:[1,1] op_sel_hi:[1,0] neg_lo:[1,0]
	v_pk_fma_f32 v[60:61], v[8:9], v[48:49], v[60:61] op_sel_hi:[0,1,1]
	v_pk_add_f32 v[64:65], v[64:65], v[70:71] op_sel:[0,1] op_sel_hi:[1,0] neg_lo:[0,1]
	v_pk_mul_f32 v[70:71], v[2:3], v[86:87] op_sel:[0,1] op_sel_hi:[1,0]
	v_pk_fma_f32 v[92:93], v[48:49], v[94:95], v[92:93] op_sel_hi:[0,1,1]
	v_pk_mul_f32 v[94:95], v[52:53], v[72:73] op_sel:[1,1] op_sel_hi:[1,0] neg_lo:[1,0]
	v_pk_fma_f32 v[70:71], v[4:5], v[86:87], v[70:71] op_sel_hi:[0,1,1]
	v_pk_mul_f32 v[86:87], v[8:9], v[90:91] op_sel:[1,1] op_sel_hi:[1,0] neg_lo:[1,0]
	v_pk_fma_f32 v[72:73], v[52:53], v[72:73], v[94:95] op_sel_hi:[0,1,1]
	v_pk_mul_f32 v[94:95], v[56:57], v[84:85] op_sel:[1,1] op_sel_hi:[1,0] neg_lo:[1,0]
	v_add_u32_e32 v5, 0x2000, v5
	v_pk_mul_f32 v[80:81], v[6:7], v[98:99] op_sel:[1,1] op_sel_hi:[1,0] neg_lo:[1,0]
	v_pk_fma_f32 v[86:87], v[8:9], v[90:91], v[86:87] op_sel_hi:[0,1,1]
	v_pk_mul_f32 v[90:91], v[10:11], v[96:97] op_sel:[1,1] op_sel_hi:[1,0] neg_lo:[1,0]
	v_pk_fma_f32 v[84:85], v[56:57], v[84:85], v[94:95] op_sel_hi:[0,1,1]
	v_pk_mul_f32 v[94:95], v[60:61], v[64:65] op_sel:[1,1] op_sel_hi:[1,0] neg_lo:[1,0]
	v_ashrrev_i32_e32 v5, 2, v5
	v_pk_fma_f32 v[80:81], v[6:7], v[98:99], v[80:81] op_sel_hi:[0,1,1]
	v_pk_fma_f32 v[90:91], v[10:11], v[96:97], v[90:91] op_sel_hi:[0,1,1]
	v_pk_fma_f32 v[64:65], v[60:61], v[64:65], v[94:95] op_sel_hi:[0,1,1]
	ds_write2_b64 v106, v[104:105], v[82:83] offset1:16
	ds_write2_b64 v106, v[90:91], v[92:93] offset0:33 offset1:49
	ds_write2_b64 v106, v[80:81], v[78:79] offset0:66 offset1:82
	ds_write2_b64 v106, v[76:77], v[84:85] offset0:99 offset1:115
	ds_write2_b64 v106, v[70:71], v[74:75] offset0:132 offset1:148
	ds_write2_b64 v106, v[88:89], v[72:73] offset0:165 offset1:181
	ds_write2_b64 v106, v[86:87], v[68:69] offset0:198 offset1:214
	ds_write2_b64 v106, v[66:67], v[64:65] offset0:231 offset1:247
	v_add3_u32 v18, v18, v5, s5
	ds_read2_b64 v[64:67], v18 offset1:16
	ds_read2_b64 v[68:71], v18 offset0:33 offset1:49
	ds_read2_b64 v[72:75], v18 offset0:66 offset1:82
	ds_read2_b64 v[76:79], v18 offset0:132 offset1:148
	ds_read2_b64 v[80:83], v18 offset0:99 offset1:115
	ds_read2_b64 v[84:87], v18 offset0:165 offset1:181
	ds_read2_b64 v[88:91], v18 offset0:198 offset1:214
	ds_read2_b64 v[92:95], v18 offset0:231 offset1:247
	s_waitcnt lgkmcnt(4)
	v_pk_add_f32 v[96:97], v[64:65], v[76:77]
	v_pk_add_f32 v[64:65], v[64:65], v[76:77] neg_lo:[0,1] neg_hi:[0,1]
	v_pk_add_f32 v[76:77], v[66:67], v[78:79]
	v_pk_add_f32 v[66:67], v[66:67], v[78:79] neg_lo:[0,1] neg_hi:[0,1]
	s_waitcnt lgkmcnt(1)
	v_pk_add_f32 v[98:99], v[74:75], v[90:91]
	v_pk_mul_f32 v[78:79], v[66:67], s[18:19]
	v_pk_add_f32 v[74:75], v[74:75], v[90:91] neg_lo:[0,1] neg_hi:[0,1]
	v_pk_fma_f32 v[66:67], v[66:67], s[16:17], v[78:79] op_sel:[0,0,1] op_sel_hi:[1,0,0]
	v_pk_add_f32 v[78:79], v[68:69], v[84:85]
	v_pk_add_f32 v[68:69], v[68:69], v[84:85] neg_lo:[0,1] neg_hi:[0,1]
	v_pk_mul_f32 v[90:91], v[74:75], s[40:41]
	v_pk_mul_f32 v[84:85], v[68:69], s[36:37]
	v_pk_fma_f32 v[74:75], v[74:75], s[68:69], v[90:91] op_sel:[0,0,1] op_sel_hi:[1,0,0] neg_lo:[1,0,0] neg_hi:[1,0,0]
	s_waitcnt lgkmcnt(0)
	v_pk_add_f32 v[90:91], v[80:81], v[92:93]
	v_pk_add_f32 v[80:81], v[80:81], v[92:93] neg_lo:[0,1] neg_hi:[0,1]
	v_pk_fma_f32 v[68:69], v[68:69], s[66:67], v[84:85] op_sel:[0,0,1] op_sel_hi:[1,0,0]
	v_pk_add_f32 v[84:85], v[70:71], v[86:87]
	v_pk_add_f32 v[70:71], v[70:71], v[86:87] neg_lo:[0,1] neg_hi:[0,1]
	v_pk_mul_f32 v[92:93], v[80:81], s[36:37]
	v_pk_mul_f32 v[86:87], v[70:71], s[40:41]
	v_pk_fma_f32 v[80:81], v[80:81], s[66:67], v[92:93] op_sel:[0,0,1] op_sel_hi:[1,0,0] neg_lo:[1,0,0] neg_hi:[1,0,0]
	v_pk_add_f32 v[92:93], v[82:83], v[94:95]
	v_pk_add_f32 v[82:83], v[82:83], v[94:95] neg_lo:[0,1] neg_hi:[0,1]
	v_pk_fma_f32 v[70:71], v[70:71], s[68:69], v[86:87] op_sel:[0,0,1] op_sel_hi:[1,0,0]
	v_pk_add_f32 v[86:87], v[72:73], v[88:89]
	v_pk_mul_f32 v[94:95], v[82:83], s[18:19]
	v_pk_add_f32 v[88:89], v[72:73], v[88:89] neg_lo:[0,1] neg_hi:[0,1]
	v_pk_fma_f32 v[82:83], v[82:83], s[16:17], v[94:95] op_sel:[0,0,1] op_sel_hi:[1,0,0] neg_lo:[1,0,0] neg_hi:[1,0,0]
	v_pk_add_f32 v[94:95], v[96:97], v[86:87]
	v_pk_add_f32 v[86:87], v[96:97], v[86:87] neg_lo:[0,1] neg_hi:[0,1]
	v_pk_add_f32 v[96:97], v[76:77], v[98:99]
	v_pk_add_f32 v[76:77], v[76:77], v[98:99] neg_lo:[0,1] neg_hi:[0,1]
	v_pk_mul_f32 v[98:99], v[76:77], s[36:37]
	v_pk_add_f32 v[100:101], v[84:85], v[92:93]
	v_pk_add_f32 v[84:85], v[84:85], v[92:93] neg_lo:[0,1] neg_hi:[0,1]
	v_pk_fma_f32 v[76:77], v[76:77], s[66:67], v[98:99] op_sel:[0,0,1] op_sel_hi:[1,0,0]
	v_pk_add_f32 v[98:99], v[78:79], v[90:91]
	v_pk_add_f32 v[90:91], v[78:79], v[90:91] neg_lo:[0,1] neg_hi:[0,1]
	v_pk_mul_f32 v[92:93], v[84:85], s[36:37]
	v_pk_add_f32 v[72:73], v[64:65], v[88:89] op_sel:[0,1] op_sel_hi:[1,0] neg_hi:[0,1]
	v_pk_add_f32 v[64:65], v[64:65], v[88:89] op_sel:[0,1] op_sel_hi:[1,0] neg_lo:[0,1]
	v_pk_add_f32 v[88:89], v[66:67], v[74:75]
	v_pk_add_f32 v[66:67], v[66:67], v[74:75] neg_lo:[0,1] neg_hi:[0,1]
	v_pk_fma_f32 v[84:85], v[84:85], s[66:67], v[92:93] op_sel:[0,0,1] op_sel_hi:[1,0,0] neg_lo:[1,0,0] neg_hi:[1,0,0]
	v_pk_mul_f32 v[74:75], v[66:67], s[36:37]
	v_pk_fma_f32 v[66:67], v[66:67], s[66:67], v[74:75] op_sel:[0,0,1] op_sel_hi:[1,0,0]
	v_pk_add_f32 v[74:75], v[68:69], v[80:81]
	v_pk_add_f32 v[92:93], v[70:71], v[82:83]
	v_pk_add_f32 v[70:71], v[70:71], v[82:83] neg_lo:[0,1] neg_hi:[0,1]
	v_pk_add_f32 v[78:79], v[86:87], v[90:91] op_sel:[0,1] op_sel_hi:[1,0] neg_hi:[0,1]
	v_pk_add_f32 v[86:87], v[86:87], v[90:91] op_sel:[0,1] op_sel_hi:[1,0] neg_lo:[0,1]
	v_pk_add_f32 v[90:91], v[76:77], v[84:85]
	v_pk_add_f32 v[84:85], v[76:77], v[84:85] neg_lo:[0,1] neg_hi:[0,1]
	v_pk_add_f32 v[80:81], v[68:69], v[80:81] neg_lo:[0,1] neg_hi:[0,1]
	v_pk_mul_f32 v[82:83], v[70:71], s[36:37]
	v_pk_add_f32 v[102:103], v[72:73], v[74:75]
	v_pk_add_f32 v[72:73], v[72:73], v[74:75] neg_lo:[0,1] neg_hi:[0,1]
	v_pk_add_f32 v[74:75], v[88:89], v[92:93]
	v_pk_fma_f32 v[70:71], v[70:71], s[66:67], v[82:83] op_sel:[0,0,1] op_sel_hi:[1,0,0] neg_lo:[1,0,0] neg_hi:[1,0,0]
	v_pk_add_f32 v[82:83], v[94:95], v[98:99]
	v_pk_add_f32 v[94:95], v[94:95], v[98:99] neg_lo:[0,1] neg_hi:[0,1]
	v_pk_add_f32 v[98:99], v[96:97], v[100:101]
	v_pk_add_f32 v[76:77], v[86:87], v[84:85] op_sel:[0,1] op_sel_hi:[1,0] neg_hi:[0,1]
	v_pk_add_f32 v[84:85], v[86:87], v[84:85] op_sel:[0,1] op_sel_hi:[1,0] neg_lo:[0,1]
	v_pk_add_f32 v[86:87], v[102:103], v[74:75]
	v_pk_add_f32 v[100:101], v[96:97], v[100:101] neg_lo:[0,1] neg_hi:[0,1]
	v_pk_add_f32 v[68:69], v[64:65], v[80:81] op_sel:[0,1] op_sel_hi:[1,0] neg_hi:[0,1]
	v_pk_add_f32 v[64:65], v[64:65], v[80:81] op_sel:[0,1] op_sel_hi:[1,0] neg_lo:[0,1]
	v_pk_add_f32 v[80:81], v[66:67], v[70:71]
	v_pk_add_f32 v[104:105], v[82:83], v[98:99]
	v_pk_add_f32 v[82:83], v[82:83], v[98:99] neg_lo:[0,1] neg_hi:[0,1]
	v_pk_add_f32 v[98:99], v[78:79], v[90:91]
	v_pk_mul_f32 v[2:3], v[2:3], v[86:87] op_sel:[0,1] op_sel_hi:[1,0]
	v_pk_add_f32 v[92:93], v[88:89], v[92:93] neg_lo:[0,1] neg_hi:[0,1]
	v_pk_add_f32 v[78:79], v[78:79], v[90:91] neg_lo:[0,1] neg_hi:[0,1]
	v_pk_add_f32 v[90:91], v[68:69], v[80:81]
	v_pk_fma_f32 v[2:3], v[4:5], v[86:87], v[2:3] op_sel_hi:[0,1,1]
	v_pk_mul_f32 v[4:5], v[6:7], v[98:99] op_sel:[1,1] op_sel_hi:[1,0] neg_lo:[1,0]
	v_pk_add_f32 v[70:71], v[66:67], v[70:71] neg_lo:[0,1] neg_hi:[0,1]
	v_pk_add_f32 v[96:97], v[94:95], v[100:101] op_sel:[0,1] op_sel_hi:[1,0] neg_hi:[0,1]
	v_pk_fma_f32 v[4:5], v[6:7], v[98:99], v[4:5] op_sel_hi:[0,1,1]
	v_pk_mul_f32 v[6:7], v[8:9], v[90:91] op_sel:[1,1] op_sel_hi:[1,0] neg_lo:[1,0]
	v_pk_add_f32 v[88:89], v[72:73], v[92:93] op_sel:[0,1] op_sel_hi:[1,0] neg_hi:[0,1]
	v_pk_fma_f32 v[6:7], v[8:9], v[90:91], v[6:7] op_sel_hi:[0,1,1]
	v_pk_mul_f32 v[8:9], v[10:11], v[96:97] op_sel:[1,1] op_sel_hi:[1,0] neg_lo:[1,0]
	v_pk_add_f32 v[66:67], v[64:65], v[70:71] op_sel:[0,1] op_sel_hi:[1,0] neg_hi:[0,1]
	v_pk_fma_f32 v[8:9], v[10:11], v[96:97], v[8:9] op_sel_hi:[0,1,1]
	v_pk_mul_f32 v[10:11], v[16:17], v[88:89] op_sel:[1,1] op_sel_hi:[1,0] neg_lo:[1,0]
	v_pk_add_f32 v[94:95], v[94:95], v[100:101] op_sel:[0,1] op_sel_hi:[1,0] neg_lo:[0,1]
	v_pk_add_f32 v[74:75], v[102:103], v[74:75] neg_lo:[0,1] neg_hi:[0,1]
	v_pk_add_f32 v[72:73], v[72:73], v[92:93] op_sel:[0,1] op_sel_hi:[1,0] neg_lo:[0,1]
	v_pk_add_f32 v[68:69], v[68:69], v[80:81] neg_lo:[0,1] neg_hi:[0,1]
	v_pk_add_f32 v[64:65], v[64:65], v[70:71] op_sel:[0,1] op_sel_hi:[1,0] neg_lo:[0,1]
	v_pk_fma_f32 v[10:11], v[16:17], v[88:89], v[10:11] op_sel_hi:[0,1,1]
	v_pk_mul_f32 v[12:13], v[24:25], v[76:77] op_sel:[1,1] op_sel_hi:[1,0] neg_lo:[1,0]
	v_pk_mul_f32 v[14:15], v[28:29], v[66:67] op_sel:[1,1] op_sel_hi:[1,0] neg_lo:[1,0]
	v_pk_mul_f32 v[16:17], v[32:33], v[82:83] op_sel:[1,1] op_sel_hi:[1,0] neg_lo:[1,0]
	v_pk_fma_f32 v[12:13], v[24:25], v[76:77], v[12:13] op_sel_hi:[0,1,1]
	v_pk_fma_f32 v[14:15], v[28:29], v[66:67], v[14:15] op_sel_hi:[0,1,1]
	v_pk_fma_f32 v[16:17], v[32:33], v[82:83], v[16:17] op_sel_hi:[0,1,1]
	v_pk_mul_f32 v[20:21], v[36:37], v[74:75] op_sel:[1,1] op_sel_hi:[1,0] neg_lo:[1,0]
	v_pk_mul_f32 v[22:23], v[40:41], v[78:79] op_sel:[1,1] op_sel_hi:[1,0] neg_lo:[1,0]
	v_pk_mul_f32 v[24:25], v[44:45], v[68:69] op_sel:[1,1] op_sel_hi:[1,0] neg_lo:[1,0]
	v_pk_mul_f32 v[26:27], v[48:49], v[94:95] op_sel:[1,1] op_sel_hi:[1,0] neg_lo:[1,0]
	v_pk_mul_f32 v[28:29], v[52:53], v[72:73] op_sel:[1,1] op_sel_hi:[1,0] neg_lo:[1,0]
	v_pk_mul_f32 v[30:31], v[56:57], v[84:85] op_sel:[1,1] op_sel_hi:[1,0] neg_lo:[1,0]
	v_pk_mul_f32 v[32:33], v[60:61], v[64:65] op_sel:[1,1] op_sel_hi:[1,0] neg_lo:[1,0]
	v_pk_fma_f32 v[20:21], v[36:37], v[74:75], v[20:21] op_sel_hi:[0,1,1]
	v_pk_fma_f32 v[22:23], v[40:41], v[78:79], v[22:23] op_sel_hi:[0,1,1]
	v_pk_fma_f32 v[24:25], v[44:45], v[68:69], v[24:25] op_sel_hi:[0,1,1]
	v_pk_fma_f32 v[26:27], v[48:49], v[94:95], v[26:27] op_sel_hi:[0,1,1]
	v_pk_fma_f32 v[28:29], v[52:53], v[72:73], v[28:29] op_sel_hi:[0,1,1]
	v_pk_fma_f32 v[30:31], v[56:57], v[84:85], v[30:31] op_sel_hi:[0,1,1]
	v_pk_fma_f32 v[32:33], v[60:61], v[64:65], v[32:33] op_sel_hi:[0,1,1]
	ds_write2_b64 v18, v[104:105], v[16:17] offset1:16
	ds_write2_b64 v18, v[8:9], v[26:27] offset0:33 offset1:49
	ds_write2_b64 v18, v[4:5], v[22:23] offset0:66 offset1:82
	ds_write2_b64 v18, v[12:13], v[30:31] offset0:99 offset1:115
	ds_write2_b64 v18, v[2:3], v[20:21] offset0:132 offset1:148
	ds_write2_b64 v18, v[10:11], v[28:29] offset0:165 offset1:181
	ds_write2_b64 v18, v[6:7], v[24:25] offset0:198 offset1:214
	ds_write2_b64 v18, v[14:15], v[32:33] offset0:231 offset1:247
	v_ashrrev_i32_e32 v2, 31, v210
	v_add_u32_sdwa v2, v210, v2 dst_sel:DWORD dst_unused:UNUSED_PAD src0_sel:DWORD src1_sel:BYTE_3
	s_lshl_b64 s[0:1], s[64:65], 15
	v_and_b32_e32 v2, 0xffffff00, v2
	s_add_u32 s0, s29, s0
	v_sub_u32_e32 v2, v210, v2
	s_addc_u32 s1, s85, s1
	v_ashrrev_i32_e32 v3, 31, v2
	v_lshl_add_u64 v[14:15], v[2:3], 3, s[0:1]
	s_movk_i32 s0, 0x1000
	v_add_co_u32_e32 v16, vcc, s0, v14
	s_movk_i32 s0, 0x3000
	s_nop 0
	v_addc_co_u32_e32 v17, vcc, 0, v15, vcc
	v_add_co_u32_e32 v2, vcc, s92, v14
	s_waitcnt lgkmcnt(0)
	s_nop 0
	v_addc_co_u32_e32 v3, vcc, 0, v15, vcc
	v_add_co_u32_e32 v22, vcc, s0, v14
	s_movk_i32 s0, 0x5000
	s_nop 0
	v_addc_co_u32_e32 v23, vcc, 0, v15, vcc
	v_add_co_u32_e32 v8, vcc, s95, v14
	s_barrier
	s_nop 0
	v_addc_co_u32_e32 v9, vcc, 0, v15, vcc
	v_add_co_u32_e32 v26, vcc, s0, v14
	s_nop 1
	v_addc_co_u32_e32 v27, vcc, 0, v15, vcc
	v_add_co_u32_e32 v10, vcc, s96, v14
	global_load_dwordx2 v[12:13], v[2:3], off nt
	global_load_dwordx2 v[6:7], v[2:3], off offset:2048 nt
	global_load_dwordx2 v[4:5], v[8:9], off offset:-4096 nt
	global_load_dwordx2 v[122:123], v[8:9], off nt
	v_addc_co_u32_e32 v11, vcc, 0, v15, vcc
	v_add_co_u32_e32 v28, vcc, s97, v14
	global_load_dwordx2 v[46:47], v[8:9], off offset:2048 nt
	global_load_dwordx2 v[38:39], v[10:11], off offset:-4096 nt
	global_load_dwordx2 v[20:21], v[10:11], off nt
	s_nop 0
	global_load_dwordx2 v[10:11], v[10:11], off offset:2048 nt
	v_addc_co_u32_e32 v29, vcc, 0, v15, vcc
	global_load_dwordx2 v[24:25], v[2:3], off offset:-4096 nt
	s_nop 0
	global_load_dwordx2 v[26:27], v[26:27], off offset:2048 nt
	s_nop 0
	global_load_dwordx2 v[8:9], v[28:29], off nt
	global_load_dwordx2 v[2:3], v[28:29], off offset:2048 nt
	global_load_dwordx2 v[30:31], v[14:15], off offset:2048 nt
	s_nop 0
	global_load_dwordx2 v[28:29], v[16:17], off offset:2048 nt
	s_nop 0
	global_load_dwordx2 v[16:17], v[22:23], off offset:2048 nt
	global_load_dwordx2 v[32:33], v[14:15], off nt
	v_mov_b32_e32 v14, v210
	s_waitcnt vmcnt(15)
	v_cvt_f32_f16_sdwa v164, v12 dst_sel:DWORD dst_unused:UNUSED_PAD src0_sel:WORD_1
	v_ashrrev_i32_e32 v15, 31, v14
	v_add_u32_sdwa v15, v14, v15 dst_sel:DWORD dst_unused:UNUSED_PAD src0_sel:DWORD src1_sel:BYTE_3
	v_ashrrev_i32_e32 v15, 8, v15
	v_mul_i32_i24_e32 v18, 0x100, v15
	v_sub_u32_e32 v18, v14, v18
	v_lshlrev_b32_e32 v14, 13, v15
	v_lshlrev_b32_e32 v15, 1, v18
	v_bfrev_b32_e32 v15, v15
	v_lshrrev_b32_e32 v15, 23, v15
	v_sub_u32_e32 v15, 0x200, v15
	v_bfrev_b32_e32 v15, v15
	v_lshrrev_b32_e32 v15, 19, v15
	v_and_b32_e32 v15, 0x1ff0, v15
	v_cmp_eq_u32_e64 s[0:1], 0, v18
	v_lshl_add_u32 v22, v18, 5, v14
	v_lshl_add_u32 v23, v22, 3, 0
	v_cndmask_b32_e64 v15, v15, 16, s[0:1]
	v_or_b32_e32 v14, v15, v14
	v_ashrrev_i32_e32 v22, 2, v22
	v_ashrrev_i32_e32 v15, 5, v14
	v_add_u32_e32 v211, v23, v22
	v_lshlrev_b32_e32 v14, 3, v14
	v_lshlrev_b32_e32 v15, 3, v15
	v_add3_u32 v212, 0, v14, v15
	ds_read2_b64 v[34:37], v211 offset1:1
	ds_read2_b64 v[40:43], v211 offset0:2 offset1:3
	ds_read2_b64 v[48:51], v212 offset1:1
	ds_read2_b64 v[52:55], v212 offset0:2 offset1:3
	ds_read2_b64 v[56:59], v211 offset0:4 offset1:5
	ds_read2_b64 v[60:63], v211 offset0:6 offset1:7
	ds_read2_b64 v[68:71], v212 offset0:4 offset1:5
	ds_read2_b64 v[72:75], v212 offset0:6 offset1:7
	ds_read2_b64 v[64:67], v211 offset0:8 offset1:9
	ds_read2_b64 v[76:79], v211 offset0:10 offset1:11
	ds_read2_b64 v[80:83], v212 offset0:8 offset1:9
	ds_read2_b64 v[98:101], v212 offset0:10 offset1:11
	ds_read2_b64 v[84:87], v211 offset0:12 offset1:13
	ds_read2_b64 v[88:91], v211 offset0:14 offset1:15
	ds_read2_b64 v[102:105], v212 offset0:12 offset1:13
	ds_read2_b64 v[106:109], v212 offset0:14 offset1:15
	s_waitcnt lgkmcnt(7)
	v_pk_add_f32 v[14:15], v[34:35], v[64:65]
	v_pk_add_f32 v[22:23], v[34:35], v[64:65] neg_lo:[0,1] neg_hi:[0,1]
	v_pk_add_f32 v[34:35], v[36:37], v[66:67]
	v_pk_add_f32 v[36:37], v[36:37], v[66:67] neg_lo:[0,1] neg_hi:[0,1]
	v_cmp_ne_u32_e32 vcc, 0, v18
	v_pk_mul_f32 v[44:45], v[36:37], s[18:19]
	v_bfrev_b32_e32 v18, v18
	v_pk_fma_f32 v[36:37], v[36:37], s[16:17], v[44:45] op_sel:[0,0,1] op_sel_hi:[1,0,0]
	s_waitcnt lgkmcnt(6)
	v_pk_add_f32 v[44:45], v[40:41], v[76:77]
	v_pk_add_f32 v[40:41], v[40:41], v[76:77] neg_lo:[0,1] neg_hi:[0,1]
	v_cvt_f32_ubyte3_e32 v18, v18
	v_pk_mul_f32 v[64:65], v[40:41], s[36:37]
	v_mul_f32_e32 v18, 0x38800000, v18
	v_pk_fma_f32 v[40:41], v[40:41], s[66:67], v[64:65] op_sel:[0,0,1] op_sel_hi:[1,0,0]
	v_pk_add_f32 v[64:65], v[42:43], v[78:79]
	v_pk_add_f32 v[42:43], v[42:43], v[78:79] neg_lo:[0,1] neg_hi:[0,1]
	s_waitcnt lgkmcnt(3)
	v_pk_add_f32 v[78:79], v[58:59], v[86:87]
	v_pk_mul_f32 v[66:67], v[42:43], s[40:41]
	v_pk_add_f32 v[58:59], v[58:59], v[86:87] neg_lo:[0,1] neg_hi:[0,1]
	v_pk_fma_f32 v[42:43], v[42:43], s[68:69], v[66:67] op_sel:[0,0,1] op_sel_hi:[1,0,0]
	v_pk_add_f32 v[66:67], v[56:57], v[84:85]
	v_pk_add_f32 v[76:77], v[56:57], v[84:85] neg_lo:[0,1] neg_hi:[0,1]
	v_pk_mul_f32 v[84:85], v[58:59], s[40:41]
	v_pk_fma_f32 v[58:59], v[58:59], s[68:69], v[84:85] op_sel:[0,0,1] op_sel_hi:[1,0,0] neg_lo:[1,0,0] neg_hi:[1,0,0]
	s_waitcnt lgkmcnt(2)
	v_pk_add_f32 v[84:85], v[60:61], v[88:89]
	v_pk_add_f32 v[60:61], v[60:61], v[88:89] neg_lo:[0,1] neg_hi:[0,1]
	v_pk_mul_f32 v[86:87], v[60:61], s[36:37]
	v_pk_add_f32 v[56:57], v[22:23], v[76:77] op_sel:[0,1] op_sel_hi:[1,0] neg_hi:[0,1]
	v_pk_fma_f32 v[60:61], v[60:61], s[66:67], v[86:87] op_sel:[0,0,1] op_sel_hi:[1,0,0] neg_lo:[1,0,0] neg_hi:[1,0,0]
	v_pk_add_f32 v[86:87], v[62:63], v[90:91]
	v_pk_add_f32 v[62:63], v[62:63], v[90:91] neg_lo:[0,1] neg_hi:[0,1]
	v_pk_add_f32 v[90:91], v[64:65], v[86:87]
	v_pk_mul_f32 v[88:89], v[62:63], s[18:19]
	v_pk_add_f32 v[64:65], v[64:65], v[86:87] neg_lo:[0,1] neg_hi:[0,1]
	v_pk_fma_f32 v[62:63], v[62:63], s[16:17], v[88:89] op_sel:[0,0,1] op_sel_hi:[1,0,0] neg_lo:[1,0,0] neg_hi:[1,0,0]
	v_pk_add_f32 v[88:89], v[14:15], v[66:67]
	v_pk_add_f32 v[14:15], v[14:15], v[66:67] neg_lo:[0,1] neg_hi:[0,1]
	v_pk_add_f32 v[66:67], v[34:35], v[78:79]
	v_pk_add_f32 v[34:35], v[34:35], v[78:79] neg_lo:[0,1] neg_hi:[0,1]
	v_pk_add_f32 v[22:23], v[22:23], v[76:77] op_sel:[0,1] op_sel_hi:[1,0] neg_lo:[0,1]
	v_pk_mul_f32 v[78:79], v[34:35], s[36:37]
	v_pk_add_f32 v[76:77], v[36:37], v[58:59]
	v_pk_add_f32 v[36:37], v[36:37], v[58:59] neg_lo:[0,1] neg_hi:[0,1]
	v_pk_fma_f32 v[34:35], v[34:35], s[66:67], v[78:79] op_sel:[0,0,1] op_sel_hi:[1,0,0]
	v_pk_add_f32 v[78:79], v[44:45], v[84:85]
	v_pk_add_f32 v[84:85], v[44:45], v[84:85] neg_lo:[0,1] neg_hi:[0,1]
	v_pk_mul_f32 v[86:87], v[64:65], s[36:37]
	v_pk_mul_f32 v[58:59], v[36:37], s[36:37]
	v_pk_fma_f32 v[64:65], v[64:65], s[66:67], v[86:87] op_sel:[0,0,1] op_sel_hi:[1,0,0] neg_lo:[1,0,0] neg_hi:[1,0,0]
	v_pk_fma_f32 v[36:37], v[36:37], s[66:67], v[58:59] op_sel:[0,0,1] op_sel_hi:[1,0,0]
	v_pk_add_f32 v[58:59], v[40:41], v[60:61]
	v_pk_add_f32 v[86:87], v[42:43], v[62:63]
	v_pk_add_f32 v[42:43], v[42:43], v[62:63] neg_lo:[0,1] neg_hi:[0,1]
	v_pk_mul_f32 v[62:63], v[42:43], s[36:37]
	v_pk_add_f32 v[44:45], v[14:15], v[84:85] op_sel:[0,1] op_sel_hi:[1,0] neg_hi:[0,1]
	v_pk_add_f32 v[14:15], v[14:15], v[84:85] op_sel:[0,1] op_sel_hi:[1,0] neg_lo:[0,1]
	v_pk_add_f32 v[84:85], v[34:35], v[64:65]
	v_pk_add_f32 v[64:65], v[34:35], v[64:65] neg_lo:[0,1] neg_hi:[0,1]
	v_pk_add_f32 v[94:95], v[56:57], v[58:59]
	v_pk_add_f32 v[56:57], v[56:57], v[58:59] neg_lo:[0,1] neg_hi:[0,1]
	v_pk_add_f32 v[58:59], v[76:77], v[86:87]
	v_pk_fma_f32 v[42:43], v[42:43], s[66:67], v[62:63] op_sel:[0,0,1] op_sel_hi:[1,0,0] neg_lo:[1,0,0] neg_hi:[1,0,0]
	v_pk_add_f32 v[62:63], v[88:89], v[78:79]
	v_pk_add_f32 v[78:79], v[88:89], v[78:79] neg_lo:[0,1] neg_hi:[0,1]
	v_pk_add_f32 v[88:89], v[66:67], v[90:91]
	v_pk_add_f32 v[110:111], v[76:77], v[86:87] neg_lo:[0,1] neg_hi:[0,1]
	v_pk_add_f32 v[86:87], v[94:95], v[58:59]
	v_pk_add_f32 v[34:35], v[94:95], v[58:59] neg_lo:[0,1] neg_hi:[0,1]
	v_pk_add_f32 v[58:59], v[50:51], v[82:83]
	v_pk_add_f32 v[50:51], v[50:51], v[82:83] neg_lo:[0,1] neg_hi:[0,1]
	v_pk_add_f32 v[60:61], v[40:41], v[60:61] neg_lo:[0,1] neg_hi:[0,1]
	v_pk_add_f32 v[148:149], v[62:63], v[88:89]
	v_pk_add_f32 v[138:139], v[62:63], v[88:89] neg_lo:[0,1] neg_hi:[0,1]
	v_pk_mul_f32 v[62:63], v[50:51], s[18:19]
	v_pk_add_f32 v[90:91], v[66:67], v[90:91] neg_lo:[0,1] neg_hi:[0,1]
	v_pk_fma_f32 v[50:51], v[50:51], s[16:17], v[62:63] op_sel:[0,0,1] op_sel_hi:[1,0,0]
	v_pk_add_f32 v[62:63], v[52:53], v[98:99]
	v_pk_add_f32 v[52:53], v[52:53], v[98:99] neg_lo:[0,1] neg_hi:[0,1]
	v_pk_add_f32 v[112:113], v[22:23], v[60:61] op_sel:[0,1] op_sel_hi:[1,0] neg_hi:[0,1]
	v_pk_add_f32 v[114:115], v[22:23], v[60:61] op_sel:[0,1] op_sel_hi:[1,0] neg_lo:[0,1]
	v_pk_add_f32 v[96:97], v[44:45], v[84:85]
	v_pk_add_f32 v[66:67], v[44:45], v[84:85] neg_lo:[0,1] neg_hi:[0,1]
	v_pk_add_f32 v[60:61], v[14:15], v[64:65] op_sel:[0,1] op_sel_hi:[1,0] neg_hi:[0,1]
	v_pk_add_f32 v[84:85], v[14:15], v[64:65] op_sel:[0,1] op_sel_hi:[1,0] neg_lo:[0,1]
	v_pk_mul_f32 v[64:65], v[52:53], s[36:37]
	v_pk_fma_f32 v[52:53], v[52:53], s[66:67], v[64:65] op_sel:[0,0,1] op_sel_hi:[1,0,0]
	v_pk_add_f32 v[64:65], v[54:55], v[100:101]
	v_pk_add_f32 v[54:55], v[54:55], v[100:101] neg_lo:[0,1] neg_hi:[0,1]
	v_pk_mul_f32 v[76:77], v[54:55], s[40:41]
	v_pk_add_f32 v[92:93], v[78:79], v[90:91] op_sel:[0,1] op_sel_hi:[1,0] neg_hi:[0,1]
	v_pk_fma_f32 v[54:55], v[54:55], s[68:69], v[76:77] op_sel:[0,0,1] op_sel_hi:[1,0,0]
	s_waitcnt lgkmcnt(1)
	v_pk_add_f32 v[76:77], v[68:69], v[102:103]
	v_pk_add_f32 v[68:69], v[68:69], v[102:103] neg_lo:[0,1] neg_hi:[0,1]
	v_pk_add_f32 v[88:89], v[78:79], v[90:91] op_sel:[0,1] op_sel_hi:[1,0] neg_lo:[0,1]
	v_xor_b32_e32 v79, 0x80000000, v68
	v_mov_b32_e32 v78, v69
	v_pk_add_f32 v[68:69], v[70:71], v[104:105]
	v_pk_add_f32 v[70:71], v[70:71], v[104:105] neg_lo:[0,1] neg_hi:[0,1]
	v_pk_add_f32 v[40:41], v[56:57], v[110:111] op_sel:[0,1] op_sel_hi:[1,0] neg_hi:[0,1]
	v_pk_add_f32 v[44:45], v[56:57], v[110:111] op_sel:[0,1] op_sel_hi:[1,0] neg_lo:[0,1]
	v_pk_add_f32 v[56:57], v[48:49], v[80:81]
	v_pk_add_f32 v[48:49], v[48:49], v[80:81] neg_lo:[0,1] neg_hi:[0,1]
	v_pk_mul_f32 v[80:81], v[70:71], s[40:41]
	v_cndmask_b32_e64 v18, v18, v208, s[0:1]
	v_pk_fma_f32 v[70:71], v[70:71], s[68:69], v[80:81] op_sel:[0,0,1] op_sel_hi:[1,0,0] neg_lo:[1,0,0] neg_hi:[1,0,0]
	s_waitcnt lgkmcnt(0)
	v_pk_add_f32 v[80:81], v[72:73], v[106:107]
	v_pk_add_f32 v[72:73], v[72:73], v[106:107] neg_lo:[0,1] neg_hi:[0,1]
	v_pk_add_f32 v[22:23], v[36:37], v[42:43]
	v_pk_mul_f32 v[82:83], v[72:73], s[36:37]
	v_pk_add_f32 v[116:117], v[36:37], v[42:43] neg_lo:[0,1] neg_hi:[0,1]
	v_pk_fma_f32 v[72:73], v[72:73], s[66:67], v[82:83] op_sel:[0,0,1] op_sel_hi:[1,0,0] neg_lo:[1,0,0] neg_hi:[1,0,0]
	v_pk_add_f32 v[82:83], v[74:75], v[108:109]
	v_pk_add_f32 v[74:75], v[74:75], v[108:109] neg_lo:[0,1] neg_hi:[0,1]
	v_pk_mul_f32 v[90:91], v[74:75], s[18:19]
	v_pk_fma_f32 v[74:75], v[74:75], s[16:17], v[90:91] op_sel:[0,0,1] op_sel_hi:[1,0,0] neg_lo:[1,0,0] neg_hi:[1,0,0]
	v_pk_add_f32 v[90:91], v[56:57], v[76:77]
	v_pk_add_f32 v[56:57], v[56:57], v[76:77] neg_lo:[0,1] neg_hi:[0,1]
	v_pk_add_f32 v[76:77], v[58:59], v[68:69]
	v_pk_add_f32 v[58:59], v[58:59], v[68:69] neg_lo:[0,1] neg_hi:[0,1]
	v_pk_add_f32 v[14:15], v[114:115], v[116:117] op_sel:[0,1] op_sel_hi:[1,0] neg_hi:[0,1]
	v_pk_mul_f32 v[68:69], v[58:59], s[36:37]
	v_pk_add_f32 v[36:37], v[114:115], v[116:117] op_sel:[0,1] op_sel_hi:[1,0] neg_lo:[0,1]
	v_pk_fma_f32 v[58:59], v[58:59], s[66:67], v[68:69] op_sel:[0,0,1] op_sel_hi:[1,0,0]
	v_pk_add_f32 v[68:69], v[62:63], v[80:81]
	v_pk_add_f32 v[80:81], v[62:63], v[80:81] neg_lo:[0,1] neg_hi:[0,1]
	s_waitcnt vmcnt(0)
	v_cvt_f32_f16_e32 v193, v33
	s_nop 0
	s_nop 0
	v_pk_add_f32 v[62:63], v[64:65], v[82:83]
	v_pk_add_f32 v[64:65], v[64:65], v[82:83] neg_lo:[0,1] neg_hi:[0,1]
	v_cvt_f32_f16_sdwa v192, v32 dst_sel:DWORD dst_unused:UNUSED_PAD src0_sel:WORD_1
	v_pk_mul_f32 v[82:83], v[64:65], s[36:37]
	v_cvt_f32_f16_e32 v194, v32
	v_pk_fma_f32 v[64:65], v[64:65], s[66:67], v[82:83] op_sel:[0,0,1] op_sel_hi:[1,0,0] neg_lo:[1,0,0] neg_hi:[1,0,0]
	v_pk_add_f32 v[82:83], v[48:49], v[78:79]
	v_pk_add_f32 v[48:49], v[48:49], v[78:79] neg_lo:[0,1] neg_hi:[0,1]
	v_pk_add_f32 v[78:79], v[50:51], v[70:71]
	v_pk_add_f32 v[50:51], v[50:51], v[70:71] neg_lo:[0,1] neg_hi:[0,1]
	v_cvt_f32_f16_sdwa v195, v33 dst_sel:DWORD dst_unused:UNUSED_PAD src0_sel:WORD_1
	v_pk_mul_f32 v[70:71], v[50:51], s[36:37]
	v_cvt_f32_f16_sdwa v170, v30 dst_sel:DWORD dst_unused:UNUSED_PAD src0_sel:WORD_1
	v_pk_fma_f32 v[50:51], v[50:51], s[66:67], v[70:71] op_sel:[0,0,1] op_sel_hi:[1,0,0]
	v_pk_add_f32 v[70:71], v[52:53], v[72:73]
	v_pk_add_f32 v[72:73], v[52:53], v[72:73] neg_lo:[0,1] neg_hi:[0,1]
	v_cvt_f32_f16_e32 v171, v31
	s_nop 0
	s_nop 0
	v_pk_add_f32 v[52:53], v[54:55], v[74:75]
	v_pk_add_f32 v[54:55], v[54:55], v[74:75] neg_lo:[0,1] neg_hi:[0,1]
	v_cvt_f32_f16_sdwa v185, v31 dst_sel:DWORD dst_unused:UNUSED_PAD src0_sel:WORD_1
	v_pk_mul_f32 v[74:75], v[54:55], s[36:37]
	v_cvt_f32_f16_e32 v184, v30
	v_pk_fma_f32 v[54:55], v[54:55], s[66:67], v[74:75] op_sel:[0,0,1] op_sel_hi:[1,0,0] neg_lo:[1,0,0] neg_hi:[1,0,0]
	v_pk_add_f32 v[74:75], v[90:91], v[68:69]
	v_pk_add_f32 v[68:69], v[90:91], v[68:69] neg_lo:[0,1] neg_hi:[0,1]
	v_pk_add_f32 v[90:91], v[76:77], v[62:63]
	v_pk_add_f32 v[62:63], v[76:77], v[62:63] neg_lo:[0,1] neg_hi:[0,1]
	v_cvt_f32_f16_sdwa v172, v24 dst_sel:DWORD dst_unused:UNUSED_PAD src0_sel:WORD_1
	v_xor_b32_e32 v77, 0x80000000, v62
	v_mov_b32_e32 v76, v63
	v_pk_add_f32 v[62:63], v[56:57], v[80:81] op_sel:[0,1] op_sel_hi:[1,0] neg_hi:[0,1]
	v_pk_add_f32 v[56:57], v[56:57], v[80:81] op_sel:[0,1] op_sel_hi:[1,0] neg_lo:[0,1]
	v_pk_add_f32 v[80:81], v[58:59], v[64:65]
	v_pk_add_f32 v[58:59], v[58:59], v[64:65] neg_lo:[0,1] neg_hi:[0,1]
	v_cvt_f32_f16_e32 v173, v25
	v_xor_b32_e32 v65, 0x80000000, v58
	v_mov_b32_e32 v64, v59
	v_pk_add_f32 v[58:59], v[82:83], v[70:71]
	v_pk_add_f32 v[70:71], v[82:83], v[70:71] neg_lo:[0,1] neg_hi:[0,1]
	v_pk_add_f32 v[82:83], v[78:79], v[52:53]
	v_pk_add_f32 v[52:53], v[78:79], v[52:53] neg_lo:[0,1] neg_hi:[0,1]
	v_pk_add_f32 v[118:119], v[58:59], v[82:83]
	v_pk_add_f32 v[134:135], v[58:59], v[82:83] neg_lo:[0,1] neg_hi:[0,1]
	v_cos_f32_e32 v83, v18
	v_sin_f32_e32 v82, v18
	v_cvt_f32_f16_sdwa v181, v25 dst_sel:DWORD dst_unused:UNUSED_PAD src0_sel:WORD_1
	v_cvt_f32_f16_e32 v180, v24
	v_cvt_f32_f16_sdwa v174, v28 dst_sel:DWORD dst_unused:UNUSED_PAD src0_sel:WORD_1
	v_cvt_f32_f16_e32 v175, v29
	v_cvt_f32_f16_sdwa v179, v29 dst_sel:DWORD dst_unused:UNUSED_PAD src0_sel:WORD_1
	v_cvt_f32_f16_e32 v178, v28
	v_cvt_f32_f16_e32 v165, v13
	v_cvt_f32_f16_sdwa v167, v13 dst_sel:DWORD dst_unused:UNUSED_PAD src0_sel:WORD_1
	v_cvt_f32_f16_e32 v166, v12
	v_cvt_f32_f16_e32 v154, v6
	v_cvt_f32_f16_e32 v155, v7
	v_cvt_f32_f16_sdwa v157, v7 dst_sel:DWORD dst_unused:UNUSED_PAD src0_sel:WORD_1
	v_cvt_f32_f16_sdwa v156, v6 dst_sel:DWORD dst_unused:UNUSED_PAD src0_sel:WORD_1
	v_cvt_f32_f16_sdwa v140, v4 dst_sel:DWORD dst_unused:UNUSED_PAD src0_sel:WORD_1
	v_cvt_f32_f16_e32 v141, v5
	v_cvt_f32_f16_sdwa v143, v5 dst_sel:DWORD dst_unused:UNUSED_PAD src0_sel:WORD_1
	v_cvt_f32_f16_e32 v142, v4
	v_cvt_f32_f16_e32 v124, v16
	v_cvt_f32_f16_e32 v125, v17
	v_cvt_f32_f16_sdwa v127, v17 dst_sel:DWORD dst_unused:UNUSED_PAD src0_sel:WORD_1
	v_cvt_f32_f16_sdwa v126, v16 dst_sel:DWORD dst_unused:UNUSED_PAD src0_sel:WORD_1
	v_cvt_f32_f16_sdwa v114, v122 dst_sel:DWORD dst_unused:UNUSED_PAD src0_sel:WORD_1
	v_cvt_f32_f16_e32 v115, v123
	v_cvt_f32_f16_sdwa v117, v123 dst_sel:DWORD dst_unused:UNUSED_PAD src0_sel:WORD_1
	v_cvt_f32_f16_e32 v116, v122
	v_xor_b32_e32 v79, 0x80000000, v52
	v_mov_b32_e32 v78, v53
	v_pk_add_f32 v[52:53], v[48:49], v[72:73] op_sel:[0,1] op_sel_hi:[1,0] neg_hi:[0,1]
	v_pk_add_f32 v[48:49], v[48:49], v[72:73] op_sel:[0,1] op_sel_hi:[1,0] neg_lo:[0,1]
	v_pk_add_f32 v[72:73], v[50:51], v[54:55]
	v_pk_add_f32 v[50:51], v[50:51], v[54:55] neg_lo:[0,1] neg_hi:[0,1]
	v_pk_fma_f32 v[160:161], v[82:83], 0, v[82:83] op_sel:[0,0,1] op_sel_hi:[1,0,0] neg_lo:[1,0,0] neg_hi:[1,0,0]
	v_xor_b32_e32 v55, 0x80000000, v50
	v_mov_b32_e32 v54, v51
	v_pk_fma_f32 v[198:199], v[82:83], 0, v[82:83] op_sel:[0,0,1] op_sel_hi:[1,0,0]
	v_pk_add_f32 v[42:43], v[112:113], v[22:23]
	v_pk_add_f32 v[22:23], v[112:113], v[22:23] neg_lo:[0,1] neg_hi:[0,1]
	v_pk_add_f32 v[98:99], v[74:75], v[90:91]
	v_pk_add_f32 v[100:101], v[74:75], v[90:91] neg_lo:[0,1] neg_hi:[0,1]
	v_pk_add_f32 v[102:103], v[68:69], v[76:77]
	v_pk_add_f32 v[106:107], v[68:69], v[76:77] neg_lo:[0,1] neg_hi:[0,1]
	v_pk_add_f32 v[104:105], v[62:63], v[80:81]
	v_pk_add_f32 v[108:109], v[62:63], v[80:81] neg_lo:[0,1] neg_hi:[0,1]
	v_pk_add_f32 v[110:111], v[56:57], v[64:65]
	v_pk_add_f32 v[112:113], v[56:57], v[64:65] neg_lo:[0,1] neg_hi:[0,1]
	v_pk_add_f32 v[152:153], v[70:71], v[78:79]
	v_pk_add_f32 v[162:163], v[70:71], v[78:79] neg_lo:[0,1] neg_hi:[0,1]
	v_pk_add_f32 v[176:177], v[52:53], v[72:73]
	v_pk_add_f32 v[182:183], v[52:53], v[72:73] neg_lo:[0,1] neg_hi:[0,1]
	v_pk_add_f32 v[188:189], v[48:49], v[54:55]
	v_pk_add_f32 v[196:197], v[48:49], v[54:55] neg_lo:[0,1] neg_hi:[0,1]
	v_pk_mul_f32 v[186:187], v[82:83], 0 op_sel_hi:[1,0]
	v_mov_b32_e32 v190, v160
	v_mov_b32_e32 v191, v199
	v_mul_f32_e32 v18, 0x3f3504f3, v83
	v_mul_f32_e32 v158, 0xbec3ef15, v83
	v_mul_f32_e32 v132, 0xbf6c835e, v83
	s_and_saveexec_b64 s[0:1], vcc
	s_xor_b64 s[0:1], exec, s[0:1]
	s_cbranch_execz .LBB0_536
	v_pk_add_f32 v[4:5], v[148:149], v[196:197]
	v_pk_add_f32 v[6:7], v[148:149], v[196:197] neg_lo:[0,1] neg_hi:[0,1]
	v_mul_f32_e32 v4, 0.5, v4
	v_mul_f32_e32 v12, 0.5, v7
	v_mov_b32_e32 v7, v5
	v_pk_mul_f32 v[6:7], v[6:7], s[44:45]
	v_pk_mov_b32 v[16:17], v[198:199], v[160:161] op_sel:[1,0]
	v_pk_mul_f32 v[24:25], v[190:191], v[6:7] op_sel:[0,1] op_sel_hi:[1,0]
	v_pk_mul_f32 v[6:7], v[190:191], v[6:7]
	v_pk_add_f32 v[24:25], v[24:25], v[24:25] op_sel:[0,1] op_sel_hi:[0,1]
	v_pk_add_f32 v[28:29], v[4:5], v[24:25] op_sel_hi:[0,1] neg_hi:[0,1]
	v_pk_add_f32 v[4:5], v[6:7], v[6:7] op_sel:[0,1] op_sel_hi:[0,1] neg_lo:[0,1] neg_hi:[0,1]
	v_pk_add_f32 v[6:7], v[12:13], v[4:5] op_sel_hi:[0,1] neg_hi:[0,1]
	v_pk_mul_f32 v[4:5], v[6:7], v[194:195]
	v_pk_mul_f32 v[6:7], v[6:7], v[192:193]
	v_pk_fma_f32 v[4:5], v[28:29], v[192:193], v[4:5]
	v_pk_fma_f32 v[6:7], v[28:29], v[194:195], v[6:7] neg_lo:[0,0,1] neg_hi:[0,0,1]
	s_mov_b32 s66, s19
	v_pk_add_f32 v[12:13], v[6:7], v[4:5] op_sel:[0,1] op_sel_hi:[1,0] neg_lo:[0,1]
	v_pk_add_f32 v[28:29], v[6:7], v[4:5] op_sel:[0,1] op_sel_hi:[1,0]
	v_pk_add_f32 v[4:5], v[4:5], v[6:7] op_sel:[1,0] op_sel_hi:[0,1] neg_lo:[0,1] neg_hi:[0,1]
	s_nop 0
	v_pk_mul_f32 v[12:13], v[12:13], 0.5 op_sel_hi:[1,0]
	v_mov_b32_e32 v29, v5
	v_mul_f32_e32 v24, v190, v12
	v_pk_fma_f32 v[30:31], v[190:191], v[12:13], v[24:25] op_sel_hi:[1,1,0] neg_lo:[1,0,0] neg_hi:[1,0,0]
	v_mul_f32_e32 v24, v160, v13
	v_pk_fma_f32 v[12:13], v[16:17], v[12:13], v[24:25] op_sel_hi:[1,1,0]
	v_mov_b32_e32 v16, v83
	v_mov_b32_e32 v30, v12
	v_pk_fma_f32 v[4:5], v[28:29], 0.5, v[12:13] op_sel_hi:[1,0,1] neg_lo:[0,0,1] neg_hi:[0,0,1]
	v_pk_fma_f32 v[122:123], v[28:29], 0.5, v[30:31] op_sel_hi:[1,0,1]
	v_pk_fma_f32 v[6:7], v[28:29], 0.5, v[30:31] op_sel_hi:[1,0,1] neg_lo:[1,0,0] neg_hi:[1,0,0]
	v_mov_b32_e32 v5, v123
	v_pk_mul_f32 v[24:25], v[4:5], s[46:47] op_sel_hi:[1,0]
	v_pk_add_f32 v[4:5], v[138:139], v[188:189]
	v_pk_add_f32 v[12:13], v[138:139], v[188:189] neg_lo:[0,1] neg_hi:[0,1]
	v_mov_b32_e32 v17, v82
	v_mul_f32_e32 v6, 0.5, v13
	v_pk_add_f32 v[28:29], v[186:187], v[16:17] neg_lo:[0,1] neg_hi:[0,1]
	v_pk_add_f32 v[30:31], v[186:187], v[16:17]
	v_mov_b32_e32 v13, v5
	v_pk_mov_b32 v[32:33], v[28:29], v[30:31] op_sel:[1,0]
	v_pk_mul_f32 v[12:13], v[12:13], s[44:45]
	v_mul_f32_e32 v4, 0.5, v4
	v_pk_mul_f32 v[48:49], v[32:33], v[12:13] op_sel:[0,1] op_sel_hi:[1,0]
	v_pk_mul_f32 v[12:13], v[32:33], v[12:13]
	v_pk_add_f32 v[48:49], v[48:49], v[48:49] op_sel:[0,1] op_sel_hi:[0,1]
	v_pk_add_f32 v[50:51], v[4:5], v[48:49] op_sel_hi:[0,1] neg_hi:[0,1]
	v_pk_add_f32 v[4:5], v[12:13], v[12:13] op_sel:[0,1] op_sel_hi:[0,1] neg_lo:[0,1] neg_hi:[0,1]
	v_pk_add_f32 v[12:13], v[6:7], v[4:5] op_sel_hi:[0,1] neg_hi:[0,1]
	v_pk_mul_f32 v[4:5], v[12:13], v[184:185]
	v_pk_mul_f32 v[12:13], v[12:13], v[170:171]
	v_pk_fma_f32 v[4:5], v[50:51], v[170:171], v[4:5]
	v_pk_fma_f32 v[12:13], v[50:51], v[184:185], v[12:13] neg_lo:[0,0,1] neg_hi:[0,0,1]
	v_mov_b32_e32 v31, v29
	v_pk_add_f32 v[48:49], v[12:13], v[4:5] op_sel:[0,1] op_sel_hi:[1,0] neg_lo:[0,1]
	v_pk_add_f32 v[50:51], v[12:13], v[4:5] op_sel:[0,1] op_sel_hi:[1,0]
	v_pk_add_f32 v[4:5], v[4:5], v[12:13] op_sel:[1,0] op_sel_hi:[0,1] neg_lo:[0,1] neg_hi:[0,1]
	v_pk_mul_f32 v[48:49], v[48:49], 0.5 op_sel_hi:[1,0]
	v_mov_b32_e32 v51, v5
	v_mul_f32_e32 v6, v29, v48
	v_pk_fma_f32 v[32:33], v[32:33], v[48:49], v[6:7] op_sel_hi:[1,1,0] neg_lo:[1,0,0] neg_hi:[1,0,0]
	v_mul_f32_e32 v6, v29, v49
	v_pk_fma_f32 v[28:29], v[30:31], v[48:49], v[6:7] op_sel_hi:[1,1,0]
	v_pk_mul_f32 v[12:13], v[16:17], s[36:37]
	v_mov_b32_e32 v32, v28
	v_pk_fma_f32 v[4:5], v[50:51], 0.5, v[28:29] op_sel_hi:[1,0,1] neg_lo:[0,0,1] neg_hi:[0,0,1]
	v_pk_fma_f32 v[138:139], v[50:51], 0.5, v[32:33] op_sel_hi:[1,0,1]
	v_pk_add_f32 v[16:17], v[92:93], v[182:183]
	v_mov_b32_e32 v5, v139
	v_pk_add_f32 v[28:29], v[92:93], v[182:183] neg_lo:[0,1] neg_hi:[0,1]
	v_pk_mul_f32 v[30:31], v[4:5], s[46:47] op_sel_hi:[1,0]
	v_pk_fma_f32 v[4:5], v[50:51], 0.5, v[32:33] op_sel_hi:[1,0,1] neg_lo:[1,0,0] neg_hi:[1,0,0]
	v_mul_f32_e32 v6, 0.5, v29
	v_pk_add_f32 v[32:33], v[18:19], v[12:13] op_sel:[0,1] op_sel_hi:[0,1] neg_lo:[0,1] neg_hi:[0,1]
	v_pk_add_f32 v[48:49], v[18:19], v[12:13] op_sel:[0,1] op_sel_hi:[0,1]
	v_mov_b32_e32 v29, v17
	v_mul_f32_e32 v4, 0.5, v16
	v_mov_b32_e32 v50, v32
	v_mov_b32_e32 v51, v49
	v_pk_mul_f32 v[16:17], v[28:29], s[44:45]
	v_pk_mov_b32 v[48:49], v[48:49], v[32:33] op_sel:[1,0]
	v_pk_mul_f32 v[28:29], v[50:51], v[16:17] op_sel:[0,1] op_sel_hi:[1,0]
	v_pk_mul_f32 v[16:17], v[50:51], v[16:17]
	v_pk_add_f32 v[28:29], v[28:29], v[28:29] op_sel:[0,1] op_sel_hi:[0,1]
	v_pk_add_f32 v[52:53], v[4:5], v[28:29] op_sel_hi:[0,1] neg_hi:[0,1]
	v_pk_add_f32 v[16:17], v[16:17], v[16:17] op_sel:[0,1] op_sel_hi:[0,1] neg_lo:[0,1] neg_hi:[0,1]
	v_pk_add_f32 v[28:29], v[6:7], v[16:17] op_sel_hi:[0,1] neg_hi:[0,1]
	v_pk_mul_f32 v[16:17], v[28:29], v[180:181]
	v_pk_mul_f32 v[28:29], v[28:29], v[172:173]
	v_pk_fma_f32 v[16:17], v[52:53], v[172:173], v[16:17]
	v_pk_fma_f32 v[28:29], v[52:53], v[180:181], v[28:29] neg_lo:[0,0,1] neg_hi:[0,0,1]
	v_sub_f32_e32 v6, v89, v177
	v_pk_add_f32 v[52:53], v[28:29], v[16:17] op_sel:[0,1] op_sel_hi:[1,0] neg_lo:[0,1]
	v_pk_add_f32 v[54:55], v[28:29], v[16:17] op_sel:[0,1] op_sel_hi:[1,0]
	v_pk_add_f32 v[16:17], v[16:17], v[28:29] op_sel:[1,0] op_sel_hi:[0,1] neg_lo:[0,1] neg_hi:[0,1]
	v_pk_mul_f32 v[52:53], v[52:53], 0.5 op_sel_hi:[1,0]
	v_mov_b32_e32 v55, v17
	v_mul_f32_e32 v4, v32, v52
	v_pk_fma_f32 v[56:57], v[50:51], v[52:53], v[4:5] op_sel_hi:[1,1,0] neg_lo:[1,0,0] neg_hi:[1,0,0]
	v_mul_f32_e32 v4, v32, v53
	v_pk_fma_f32 v[48:49], v[48:49], v[52:53], v[4:5] op_sel_hi:[1,1,0]
	v_pk_add_f32 v[28:29], v[88:89], v[176:177]
	v_mov_b32_e32 v56, v48
	v_pk_fma_f32 v[16:17], v[54:55], 0.5, v[48:49] op_sel_hi:[1,0,1] neg_lo:[0,0,1] neg_hi:[0,0,1]
	v_mov_b32_e32 v48, v12
	v_mov_b32_e32 v49, v88
	v_pk_mov_b32 v[12:13], v[12:13], v[176:177] op_sel:[1,0]
	v_mul_f32_e32 v18, 0.5, v29
	v_pk_add_f32 v[12:13], v[48:49], v[12:13] neg_lo:[0,1] neg_hi:[0,1]
	v_mul_f32_e32 v4, 0.5, v28
	v_pk_mul_f32 v[48:49], v[12:13], v[18:19]
	v_mov_b32_e32 v13, v32
	v_pk_fma_f32 v[50:51], v[50:51], v[48:49], v[48:49] op_sel:[0,1,0] op_sel_hi:[1,0,1]
	v_mov_b32_e32 v48, v49
	v_mov_b32_e32 v49, v18
	v_pk_mul_f32 v[48:49], v[12:13], v[48:49]
	v_pk_add_f32 v[52:53], v[4:5], v[50:51]
	v_mul_f32_e32 v6, 0.5, v6
	v_fma_f32 v53, v28, 0.5, -v50
	v_pk_add_f32 v[28:29], v[48:49], v[48:49] op_sel:[0,1] op_sel_hi:[0,1] neg_lo:[0,1] neg_hi:[0,1]
	v_pk_add_f32 v[48:49], v[6:7], v[28:29] op_sel_hi:[0,1] neg_hi:[0,1]
	v_pk_mul_f32 v[28:29], v[48:49], v[178:179]
	v_pk_mul_f32 v[48:49], v[48:49], v[174:175]
	v_pk_fma_f32 v[28:29], v[52:53], v[174:175], v[28:29]
	v_pk_fma_f32 v[48:49], v[52:53], v[178:179], v[48:49] neg_lo:[0,0,1] neg_hi:[0,0,1]
	v_pk_fma_f32 v[92:93], v[54:55], 0.5, v[56:57] op_sel_hi:[1,0,1]
	v_pk_add_f32 v[50:51], v[48:49], v[28:29] op_sel:[0,1] op_sel_hi:[1,0] neg_lo:[0,1]
	v_pk_add_f32 v[52:53], v[48:49], v[28:29] op_sel:[0,1] op_sel_hi:[1,0]
	v_mov_b32_e32 v17, v93
	v_pk_mul_f32 v[50:51], v[50:51], 0.5 op_sel_hi:[1,0]
	v_pk_mul_f32 v[64:65], v[16:17], s[46:47] op_sel_hi:[1,0]
	v_mul_f32_e32 v4, v12, v50
	v_pk_fma_f32 v[16:17], v[54:55], 0.5, v[56:57] op_sel_hi:[1,0,1] neg_lo:[1,0,0] neg_hi:[1,0,0]
	v_pk_fma_f32 v[54:55], v[12:13], v[50:51], v[4:5] op_sel_hi:[1,1,0] neg_lo:[1,0,0] neg_hi:[1,0,0]
	v_mov_b32_e32 v33, v12
	v_mul_f32_e32 v4, v12, v51
	v_pk_fma_f32 v[12:13], v[32:33], v[50:51], v[4:5] op_sel_hi:[1,1,0]
	v_pk_add_f32 v[28:29], v[28:29], v[48:49] op_sel:[1,0] op_sel_hi:[0,1] neg_lo:[0,1] neg_hi:[0,1]
	v_mov_b32_e32 v53, v29
	v_mov_b32_e32 v54, v12
	v_pk_fma_f32 v[12:13], v[52:53], 0.5, v[12:13] op_sel_hi:[1,0,1] neg_lo:[0,0,1] neg_hi:[0,0,1]
	v_pk_fma_f32 v[88:89], v[52:53], 0.5, v[54:55] op_sel_hi:[1,0,1]
	s_mov_b32 s67, s16
	v_mov_b32_e32 v13, v89
	v_pk_mul_f32 v[68:69], v[12:13], s[46:47] op_sel_hi:[1,0]
	v_pk_fma_f32 v[12:13], v[52:53], 0.5, v[54:55] op_sel_hi:[1,0,1] neg_lo:[1,0,0] neg_hi:[1,0,0]
	v_mov_b32_e32 v4, v83
	s_mov_b32 s17, s19
	v_pk_mul_f32 v[48:49], v[82:83], s[66:67] op_sel_hi:[0,1]
	v_pk_add_f32 v[28:29], v[96:97], v[162:163]
	v_pk_add_f32 v[32:33], v[96:97], v[162:163] neg_lo:[0,1] neg_hi:[0,1]
	v_pk_fma_f32 v[52:53], v[4:5], s[16:17], v[48:49] op_sel_hi:[0,1,1] neg_lo:[0,0,1] neg_hi:[0,0,1]
	v_mul_f32_e32 v12, 0.5, v33
	v_pk_fma_f32 v[50:51], v[4:5], s[16:17], v[48:49] op_sel_hi:[0,1,1]
	v_mov_b32_e32 v33, v29
	v_mul_f32_e32 v6, 0.5, v28
	v_mov_b32_e32 v54, v52
	v_mov_b32_e32 v55, v51
	v_pk_mul_f32 v[28:29], v[32:33], s[44:45]
	v_pk_mov_b32 v[56:57], v[50:51], v[52:53] op_sel:[1,0]
	v_pk_mul_f32 v[32:33], v[54:55], v[28:29] op_sel:[0,1] op_sel_hi:[1,0]
	v_pk_mul_f32 v[28:29], v[54:55], v[28:29]
	v_pk_add_f32 v[32:33], v[32:33], v[32:33] op_sel:[0,1] op_sel_hi:[0,1]
	v_pk_add_f32 v[58:59], v[6:7], v[32:33] op_sel_hi:[0,1] neg_hi:[0,1]
	v_pk_add_f32 v[28:29], v[28:29], v[28:29] op_sel:[0,1] op_sel_hi:[0,1] neg_lo:[0,1] neg_hi:[0,1]
	v_pk_add_f32 v[32:33], v[12:13], v[28:29] op_sel_hi:[0,1] neg_hi:[0,1]
	v_pk_mul_f32 v[28:29], v[32:33], v[166:167]
	v_pk_mul_f32 v[32:33], v[32:33], v[164:165]
	v_pk_fma_f32 v[28:29], v[58:59], v[164:165], v[28:29]
	v_pk_fma_f32 v[32:33], v[58:59], v[166:167], v[32:33] neg_lo:[0,0,1] neg_hi:[0,0,1]
	v_mov_b32_e32 v159, v66
	v_pk_add_f32 v[58:59], v[32:33], v[28:29] op_sel:[0,1] op_sel_hi:[1,0] neg_lo:[0,1]
	v_pk_add_f32 v[70:71], v[32:33], v[28:29] op_sel:[0,1] op_sel_hi:[1,0]
	v_pk_add_f32 v[28:29], v[28:29], v[32:33] op_sel:[1,0] op_sel_hi:[0,1] neg_lo:[0,1] neg_hi:[0,1]
	v_pk_mul_f32 v[58:59], v[58:59], 0.5 op_sel_hi:[1,0]
	v_mov_b32_e32 v71, v29
	v_mul_f32_e32 v6, v52, v58
	v_pk_fma_f32 v[72:73], v[54:55], v[58:59], v[6:7] op_sel_hi:[1,1,0] neg_lo:[1,0,0] neg_hi:[1,0,0]
	v_mul_f32_e32 v6, v52, v59
	v_pk_fma_f32 v[56:57], v[56:57], v[58:59], v[6:7] op_sel_hi:[1,1,0]
	v_sub_f32_e32 v12, v67, v153
	v_mov_b32_e32 v72, v56
	v_pk_fma_f32 v[28:29], v[70:71], 0.5, v[56:57] op_sel_hi:[1,0,1] neg_lo:[0,0,1] neg_hi:[0,0,1]
	v_pk_fma_f32 v[96:97], v[70:71], 0.5, v[72:73] op_sel_hi:[1,0,1]
	v_pk_mov_b32 v[56:57], v[48:49], v[152:153] op_sel:[1,0]
	v_mov_b32_e32 v29, v97
	v_pk_mul_f32 v[62:63], v[28:29], s[46:47] op_sel_hi:[1,0]
	v_pk_add_f32 v[28:29], v[66:67], v[152:153]
	v_pk_add_f32 v[56:57], v[158:159], v[56:57] neg_lo:[0,1] neg_hi:[0,1]
	v_mul_f32_e32 v18, 0.5, v29
	v_pk_mul_f32 v[58:59], v[56:57], v[18:19]
	v_mul_f32_e32 v6, 0.5, v28
	v_pk_fma_f32 v[54:55], v[54:55], v[58:59], v[58:59] op_sel:[0,1,0] op_sel_hi:[1,0,1]
	v_mov_b32_e32 v66, v56
	v_mov_b32_e32 v67, v52
	v_mov_b32_e32 v58, v59
	v_mov_b32_e32 v59, v18
	v_pk_mul_f32 v[58:59], v[66:67], v[58:59]
	v_pk_add_f32 v[66:67], v[6:7], v[54:55]
	v_mul_f32_e32 v12, 0.5, v12
	v_fma_f32 v67, v28, 0.5, -v54
	v_pk_add_f32 v[28:29], v[58:59], v[58:59] op_sel:[0,1] op_sel_hi:[0,1] neg_lo:[0,1] neg_hi:[0,1]
	v_pk_add_f32 v[54:55], v[12:13], v[28:29] op_sel_hi:[0,1] neg_hi:[0,1]
	v_pk_mul_f32 v[28:29], v[54:55], v[156:157]
	v_pk_mul_f32 v[54:55], v[54:55], v[154:155]
	v_pk_fma_f32 v[32:33], v[70:71], 0.5, v[72:73] op_sel_hi:[1,0,1] neg_lo:[1,0,0] neg_hi:[1,0,0]
	v_pk_fma_f32 v[58:59], v[66:67], v[154:155], v[28:29] neg_lo:[0,0,1] neg_hi:[0,0,1]
	v_pk_fma_f32 v[28:29], v[66:67], v[154:155], v[28:29]
	v_pk_fma_f32 v[70:71], v[66:67], v[156:157], v[54:55]
	v_pk_fma_f32 v[54:55], v[66:67], v[156:157], v[54:55] neg_lo:[0,0,1] neg_hi:[0,0,1]
	v_pk_add_f32 v[72:73], v[58:59], v[28:29] op_sel:[0,1] op_sel_hi:[1,0]
	v_pk_add_f32 v[66:67], v[70:71], v[54:55] op_sel_hi:[0,1] neg_lo:[0,1] neg_hi:[0,1]
	v_pk_add_f32 v[28:29], v[58:59], v[28:29] op_sel_hi:[0,1] neg_lo:[0,1] neg_hi:[0,1]
	v_pk_add_f32 v[54:55], v[70:71], v[54:55] op_sel:[0,1] op_sel_hi:[1,0]
	v_mov_b32_e32 v73, v67
	v_mov_b32_e32 v55, v29
	v_pk_mul_f32 v[28:29], v[54:55], 0.5 op_sel_hi:[1,0]
	v_mov_b32_e32 v133, v84
	v_pk_mul_f32 v[54:55], v[52:53], v[28:29] op_sel:[0,1] op_sel_hi:[0,0]
	v_pk_fma_f32 v[58:59], v[56:57], v[28:29], v[54:55] op_sel_hi:[0,1,1]
	v_pk_fma_f32 v[28:29], v[56:57], v[28:29], v[54:55] op_sel_hi:[0,1,1] neg_hi:[0,0,1]
	v_pk_fma_f32 v[54:55], v[72:73], 0.5, v[58:59] op_sel_hi:[1,0,1] neg_lo:[0,0,1] neg_hi:[0,0,1]
	v_pk_fma_f32 v[66:67], v[72:73], 0.5, v[28:29] op_sel_hi:[1,0,1]
	v_pk_add_f32 v[56:57], v[60:61], v[134:135] neg_lo:[0,1] neg_hi:[0,1]
	v_mov_b32_e32 v55, v67
	v_pk_mul_f32 v[90:91], v[54:55], s[46:47] op_sel_hi:[1,0]
	v_pk_add_f32 v[54:55], v[134:135], v[60:61]
	v_mul_f32_e32 v12, 0.5, v57
	v_mov_b32_e32 v57, v55
	v_mul_f32_e32 v6, 0.5, v54
	v_pk_mov_b32 v[58:59], v[52:53], v[50:51] op_sel:[1,0]
	v_pk_mul_f32 v[54:55], v[56:57], s[44:45]
	v_pk_fma_f32 v[28:29], v[72:73], 0.5, v[28:29] op_sel_hi:[1,0,1] neg_lo:[1,0,0] neg_hi:[1,0,0]
	v_pk_mul_f32 v[56:57], v[58:59], v[54:55] op_sel:[0,1] op_sel_hi:[1,0]
	v_pk_mul_f32 v[54:55], v[58:59], v[54:55]
	v_pk_add_f32 v[56:57], v[56:57], v[56:57] op_sel:[0,1] op_sel_hi:[0,1]
	v_pk_add_f32 v[60:61], v[6:7], v[56:57] op_sel_hi:[0,1] neg_hi:[0,1]
	v_pk_add_f32 v[54:55], v[54:55], v[54:55] op_sel:[0,1] op_sel_hi:[0,1] neg_lo:[0,1] neg_hi:[0,1]
	v_pk_add_f32 v[56:57], v[12:13], v[54:55] op_sel_hi:[0,1] neg_hi:[0,1]
	v_pk_mul_f32 v[54:55], v[56:57], v[142:143]
	v_pk_mul_f32 v[56:57], v[56:57], v[140:141]
	v_pk_fma_f32 v[54:55], v[60:61], v[140:141], v[54:55]
	v_pk_fma_f32 v[56:57], v[60:61], v[142:143], v[56:57] neg_lo:[0,0,1] neg_hi:[0,0,1]
	v_mov_b32_e32 v51, v53
	v_pk_add_f32 v[60:61], v[56:57], v[54:55] op_sel:[0,1] op_sel_hi:[1,0] neg_lo:[0,1]
	v_pk_add_f32 v[70:71], v[56:57], v[54:55] op_sel:[0,1] op_sel_hi:[1,0]
	v_pk_add_f32 v[54:55], v[54:55], v[56:57] op_sel:[1,0] op_sel_hi:[0,1] neg_lo:[0,1] neg_hi:[0,1]
	v_pk_mul_f32 v[60:61], v[60:61], 0.5 op_sel_hi:[1,0]
	v_mov_b32_e32 v71, v55
	v_mul_f32_e32 v6, v53, v60
	v_pk_fma_f32 v[72:73], v[58:59], v[60:61], v[6:7] op_sel_hi:[1,1,0] neg_lo:[1,0,0] neg_hi:[1,0,0]
	v_mul_f32_e32 v6, v53, v61
	v_pk_fma_f32 v[50:51], v[50:51], v[60:61], v[6:7] op_sel_hi:[1,1,0]
	v_pk_add_f32 v[54:55], v[118:119], v[84:85]
	v_mov_b32_e32 v72, v50
	v_mov_b32_e32 v49, v118
	v_pk_fma_f32 v[50:51], v[70:71], 0.5, v[50:51] op_sel_hi:[1,0,1] neg_lo:[0,0,1] neg_hi:[0,0,1]
	v_pk_fma_f32 v[60:61], v[70:71], 0.5, v[72:73] op_sel_hi:[1,0,1]
	v_mul_f32_e32 v18, 0.5, v55
	v_pk_add_f32 v[48:49], v[132:133], v[48:49] neg_lo:[0,1] neg_hi:[0,1]
	v_mov_b32_e32 v51, v61
	v_pk_mul_f32 v[56:57], v[48:49], v[18:19]
	v_pk_mul_f32 v[94:95], v[50:51], s[46:47] op_sel_hi:[1,0]
	v_pk_fma_f32 v[50:51], v[70:71], 0.5, v[72:73] op_sel_hi:[1,0,1] neg_lo:[1,0,0] neg_hi:[1,0,0]
	v_mul_f32_e32 v6, 0.5, v54
	v_pk_fma_f32 v[58:59], v[58:59], v[56:57], v[56:57] op_sel:[0,1,0] op_sel_hi:[1,0,1]
	v_mov_b32_e32 v70, v48
	v_mov_b32_e32 v71, v53
	v_mov_b32_e32 v56, v57
	v_mov_b32_e32 v57, v18
	v_sub_f32_e32 v12, v85, v119
	v_pk_mul_f32 v[56:57], v[70:71], v[56:57]
	v_pk_add_f32 v[70:71], v[6:7], v[58:59]
	v_mul_f32_e32 v12, 0.5, v12
	v_fma_f32 v71, v54, 0.5, -v58
	v_pk_add_f32 v[54:55], v[56:57], v[56:57] op_sel:[0,1] op_sel_hi:[0,1] neg_lo:[0,1] neg_hi:[0,1]
	v_pk_add_f32 v[56:57], v[12:13], v[54:55] op_sel_hi:[0,1] neg_hi:[0,1]
	v_pk_mul_f32 v[54:55], v[56:57], v[126:127]
	v_pk_mul_f32 v[56:57], v[56:57], v[124:125]
	v_pk_fma_f32 v[58:59], v[70:71], v[124:125], v[54:55] neg_lo:[0,0,1] neg_hi:[0,0,1]
	v_pk_fma_f32 v[54:55], v[70:71], v[124:125], v[54:55]
	v_pk_fma_f32 v[72:73], v[70:71], v[126:127], v[56:57]
	v_pk_fma_f32 v[56:57], v[70:71], v[126:127], v[56:57] neg_lo:[0,0,1] neg_hi:[0,0,1]
	v_pk_add_f32 v[70:71], v[58:59], v[54:55] op_sel:[0,1] op_sel_hi:[1,0]
	v_pk_add_f32 v[74:75], v[72:73], v[56:57] op_sel_hi:[0,1] neg_lo:[0,1] neg_hi:[0,1]
	v_pk_add_f32 v[54:55], v[58:59], v[54:55] op_sel_hi:[0,1] neg_lo:[0,1] neg_hi:[0,1]
	v_pk_add_f32 v[56:57], v[72:73], v[56:57] op_sel:[0,1] op_sel_hi:[1,0]
	v_mov_b32_e32 v71, v75
	v_mov_b32_e32 v57, v55
	v_pk_mul_f32 v[54:55], v[56:57], 0.5 op_sel_hi:[1,0]
	s_mov_b32 s66, s11
	v_pk_mul_f32 v[52:53], v[52:53], v[54:55] op_sel:[1,1] op_sel_hi:[1,0]
	s_mov_b32 s67, s8
	v_pk_fma_f32 v[56:57], v[48:49], v[54:55], v[52:53] op_sel_hi:[0,1,1]
	v_pk_fma_f32 v[48:49], v[48:49], v[54:55], v[52:53] op_sel_hi:[0,1,1] neg_hi:[0,0,1]
	s_nop 0
	v_pk_fma_f32 v[52:53], v[70:71], 0.5, v[56:57] op_sel_hi:[1,0,1] neg_lo:[0,0,1] neg_hi:[0,0,1]
	v_pk_fma_f32 v[84:85], v[70:71], 0.5, v[48:49] op_sel_hi:[1,0,1]
	s_mov_b32 s9, s11
	v_mov_b32_e32 v53, v85
	v_pk_mul_f32 v[80:81], v[52:53], s[46:47] op_sel_hi:[1,0]
	v_pk_mul_f32 v[118:119], v[82:83], s[66:67] op_sel_hi:[0,1]
	v_pk_add_f32 v[52:53], v[86:87], v[112:113]
	v_pk_add_f32 v[54:55], v[86:87], v[112:113] neg_lo:[0,1] neg_hi:[0,1]
	v_pk_fma_f32 v[58:59], v[4:5], s[8:9], v[118:119] op_sel_hi:[0,1,1] neg_lo:[0,0,1] neg_hi:[0,0,1]
	v_mul_f32_e32 v12, 0.5, v55
	v_pk_fma_f32 v[72:73], v[4:5], s[8:9], v[118:119] op_sel_hi:[0,1,1]
	v_mov_b32_e32 v55, v53
	v_mul_f32_e32 v6, 0.5, v52
	v_mov_b32_e32 v56, v58
	v_mov_b32_e32 v57, v73
	v_pk_mul_f32 v[52:53], v[54:55], s[44:45]
	v_pk_fma_f32 v[48:49], v[70:71], 0.5, v[48:49] op_sel_hi:[1,0,1] neg_lo:[1,0,0] neg_hi:[1,0,0]
	v_pk_mul_f32 v[54:55], v[56:57], v[52:53] op_sel:[0,1] op_sel_hi:[1,0]
	v_pk_mul_f32 v[52:53], v[56:57], v[52:53]
	v_pk_add_f32 v[54:55], v[54:55], v[54:55] op_sel:[0,1] op_sel_hi:[0,1]
	v_pk_add_f32 v[74:75], v[6:7], v[54:55] op_sel_hi:[0,1] neg_hi:[0,1]
	v_pk_add_f32 v[52:53], v[52:53], v[52:53] op_sel:[0,1] op_sel_hi:[0,1] neg_lo:[0,1] neg_hi:[0,1]
	v_pk_add_f32 v[54:55], v[12:13], v[52:53] op_sel_hi:[0,1] neg_hi:[0,1]
	v_pk_mul_f32 v[52:53], v[54:55], v[116:117]
	v_pk_mul_f32 v[54:55], v[54:55], v[114:115]
	v_pk_fma_f32 v[52:53], v[74:75], v[114:115], v[52:53]
	v_pk_fma_f32 v[54:55], v[74:75], v[116:117], v[54:55] neg_lo:[0,0,1] neg_hi:[0,0,1]
	v_pk_mov_b32 v[70:71], v[72:73], v[58:59] op_sel:[1,0]
	v_pk_add_f32 v[74:75], v[54:55], v[52:53] op_sel:[0,1] op_sel_hi:[1,0] neg_lo:[0,1]
	v_pk_add_f32 v[76:77], v[54:55], v[52:53] op_sel:[0,1] op_sel_hi:[1,0]
	v_pk_add_f32 v[52:53], v[52:53], v[54:55] op_sel:[1,0] op_sel_hi:[0,1] neg_lo:[0,1] neg_hi:[0,1]
	v_pk_mul_f32 v[74:75], v[74:75], 0.5 op_sel_hi:[1,0]
	v_mov_b32_e32 v77, v53
	v_mul_f32_e32 v6, v58, v74
	v_pk_fma_f32 v[112:113], v[56:57], v[74:75], v[6:7] op_sel_hi:[1,1,0] neg_lo:[1,0,0] neg_hi:[1,0,0]
	v_mul_f32_e32 v6, v58, v75
	v_pk_fma_f32 v[70:71], v[70:71], v[74:75], v[6:7] op_sel_hi:[1,1,0]
	v_pk_add_f32 v[54:55], v[34:35], v[110:111]
	v_mov_b32_e32 v112, v70
	v_pk_fma_f32 v[52:53], v[76:77], 0.5, v[70:71] op_sel_hi:[1,0,1] neg_lo:[0,0,1] neg_hi:[0,0,1]
	v_pk_fma_f32 v[86:87], v[76:77], 0.5, v[112:113] op_sel_hi:[1,0,1]
	v_sub_f32_e32 v12, v35, v111
	v_mov_b32_e32 v53, v87
	v_pk_mul_f32 v[78:79], v[52:53], s[46:47] op_sel_hi:[1,0]
	v_mul_f32_e32 v52, 0xbe47c5c2, v83
	v_mov_b32_e32 v53, v34
	v_pk_mov_b32 v[34:35], v[118:119], v[110:111] op_sel:[1,0]
	v_mul_f32_e32 v18, 0.5, v55
	v_pk_add_f32 v[34:35], v[52:53], v[34:35] neg_lo:[0,1] neg_hi:[0,1]
	v_mov_b32_e32 v71, v58
	v_pk_mul_f32 v[52:53], v[34:35], v[18:19]
	v_mov_b32_e32 v70, v34
	v_pk_fma_f32 v[56:57], v[56:57], v[52:53], v[52:53] op_sel:[0,1,0] op_sel_hi:[1,0,1]
	v_mov_b32_e32 v52, v53
	v_mov_b32_e32 v53, v18
	v_mul_f32_e32 v6, 0.5, v54
	v_pk_mul_f32 v[52:53], v[70:71], v[52:53]
	v_cvt_f32_f16_e32 v70, v46
	v_cvt_f32_f16_e32 v71, v47
	v_cvt_f32_f16_sdwa v47, v47 dst_sel:DWORD dst_unused:UNUSED_PAD src0_sel:WORD_1
	v_cvt_f32_f16_sdwa v46, v46 dst_sel:DWORD dst_unused:UNUSED_PAD src0_sel:WORD_1
	v_pk_fma_f32 v[74:75], v[76:77], 0.5, v[112:113] op_sel_hi:[1,0,1] neg_lo:[1,0,0] neg_hi:[1,0,0]
	v_mul_f32_e32 v12, 0.5, v12
	v_pk_add_f32 v[76:77], v[6:7], v[56:57]
	v_pk_add_f32 v[52:53], v[52:53], v[52:53] op_sel:[0,1] op_sel_hi:[0,1] neg_lo:[0,1] neg_hi:[0,1]
	v_fma_f32 v77, v54, 0.5, -v56
	v_pk_add_f32 v[54:55], v[12:13], v[52:53] op_sel_hi:[0,1] neg_hi:[0,1]
	v_pk_mul_f32 v[52:53], v[54:55], v[46:47]
	v_pk_mul_f32 v[54:55], v[54:55], v[70:71]
	v_pk_fma_f32 v[56:57], v[76:77], v[70:71], v[52:53] neg_lo:[0,0,1] neg_hi:[0,0,1]
	v_pk_fma_f32 v[52:53], v[76:77], v[70:71], v[52:53]
	v_pk_fma_f32 v[70:71], v[76:77], v[46:47], v[54:55]
	v_pk_fma_f32 v[46:47], v[76:77], v[46:47], v[54:55] neg_lo:[0,0,1] neg_hi:[0,0,1]
	v_pk_add_f32 v[54:55], v[56:57], v[52:53] op_sel:[0,1] op_sel_hi:[1,0]
	v_pk_add_f32 v[76:77], v[70:71], v[46:47] op_sel_hi:[0,1] neg_lo:[0,1] neg_hi:[0,1]
	v_pk_add_f32 v[52:53], v[56:57], v[52:53] op_sel_hi:[0,1] neg_lo:[0,1] neg_hi:[0,1]
	v_pk_add_f32 v[46:47], v[70:71], v[46:47] op_sel:[0,1] op_sel_hi:[1,0]
	v_mov_b32_e32 v55, v77
	v_mov_b32_e32 v47, v53
	v_pk_mul_f32 v[46:47], v[46:47], 0.5 op_sel_hi:[1,0]
	s_mov_b32 s25, s27
	v_pk_mul_f32 v[52:53], v[58:59], v[46:47] op_sel:[0,1] op_sel_hi:[0,0]
	v_pk_fma_f32 v[56:57], v[34:35], v[46:47], v[52:53] op_sel_hi:[0,1,1]
	v_pk_fma_f32 v[46:47], v[34:35], v[46:47], v[52:53] op_sel_hi:[0,1,1] neg_hi:[0,0,1]
	s_nop 0
	v_pk_fma_f32 v[52:53], v[54:55], 0.5, v[56:57] op_sel_hi:[1,0,1] neg_lo:[0,0,1] neg_hi:[0,0,1]
	v_pk_fma_f32 v[34:35], v[54:55], 0.5, v[46:47] op_sel_hi:[1,0,1]
	s_mov_b32 s66, s27
	v_mov_b32_e32 v53, v35
	v_pk_mul_f32 v[136:137], v[52:53], s[46:47] op_sel_hi:[1,0]
	v_pk_fma_f32 v[52:53], v[54:55], 0.5, v[46:47] op_sel_hi:[1,0,1] neg_lo:[1,0,0] neg_hi:[1,0,0]
	s_mov_b32 s67, s24
	v_pk_mul_f32 v[46:47], v[82:83], s[24:25] op_sel_hi:[0,1]
	v_pk_add_f32 v[54:55], v[108:109], v[40:41]
	v_pk_add_f32 v[40:41], v[40:41], v[108:109] neg_lo:[0,1] neg_hi:[0,1]
	v_pk_fma_f32 v[108:109], v[4:5], s[66:67], v[46:47] op_sel_hi:[0,1,1] neg_lo:[0,0,1] neg_hi:[0,0,1]
	v_mul_f32_e32 v12, 0.5, v41
	v_pk_fma_f32 v[70:71], v[4:5], s[66:67], v[46:47] op_sel_hi:[0,1,1]
	v_mov_b32_e32 v41, v55
	v_mov_b32_e32 v56, v108
	v_mov_b32_e32 v57, v71
	v_pk_mul_f32 v[40:41], v[40:41], s[44:45]
	v_mul_f32_e32 v6, 0.5, v54
	v_pk_mul_f32 v[54:55], v[56:57], v[40:41] op_sel:[0,1] op_sel_hi:[1,0]
	v_cvt_f32_f16_sdwa v76, v38 dst_sel:DWORD dst_unused:UNUSED_PAD src0_sel:WORD_1
	v_cvt_f32_f16_e32 v77, v39
	v_cvt_f32_f16_sdwa v39, v39 dst_sel:DWORD dst_unused:UNUSED_PAD src0_sel:WORD_1
	v_cvt_f32_f16_e32 v38, v38
	v_pk_mul_f32 v[40:41], v[56:57], v[40:41]
	v_pk_add_f32 v[54:55], v[54:55], v[54:55] op_sel:[0,1] op_sel_hi:[0,1]
	v_pk_add_f32 v[112:113], v[6:7], v[54:55] op_sel_hi:[0,1] neg_hi:[0,1]
	s_nop 0
	v_pk_add_f32 v[40:41], v[40:41], v[40:41] op_sel:[0,1] op_sel_hi:[0,1] neg_lo:[0,1] neg_hi:[0,1]
	v_pk_add_f32 v[54:55], v[12:13], v[40:41] op_sel_hi:[0,1] neg_hi:[0,1]
	v_pk_mul_f32 v[40:41], v[54:55], v[38:39]
	v_pk_mul_f32 v[54:55], v[54:55], v[76:77]
	v_pk_fma_f32 v[40:41], v[112:113], v[76:77], v[40:41]
	v_pk_fma_f32 v[38:39], v[112:113], v[38:39], v[54:55] neg_lo:[0,0,1] neg_hi:[0,0,1]
	v_pk_mov_b32 v[110:111], v[70:71], v[108:109] op_sel:[1,0]
	v_pk_add_f32 v[54:55], v[38:39], v[40:41] op_sel:[0,1] op_sel_hi:[1,0] neg_lo:[0,1]
	v_pk_add_f32 v[76:77], v[38:39], v[40:41] op_sel:[0,1] op_sel_hi:[1,0]
	v_pk_add_f32 v[38:39], v[40:41], v[38:39] op_sel:[1,0] op_sel_hi:[0,1] neg_lo:[0,1] neg_hi:[0,1]
	v_pk_mul_f32 v[54:55], v[54:55], 0.5 op_sel_hi:[1,0]
	v_mov_b32_e32 v77, v39
	v_mul_f32_e32 v4, v108, v54
	v_pk_fma_f32 v[112:113], v[56:57], v[54:55], v[4:5] op_sel_hi:[1,1,0] neg_lo:[1,0,0] neg_hi:[1,0,0]
	v_mul_f32_e32 v4, v108, v55
	v_pk_fma_f32 v[54:55], v[110:111], v[54:55], v[4:5] op_sel_hi:[1,1,0]
	v_sub_f32_e32 v6, v45, v105
	v_mov_b32_e32 v112, v54
	v_pk_fma_f32 v[40:41], v[76:77], 0.5, v[54:55] op_sel_hi:[1,0,1] neg_lo:[0,0,1] neg_hi:[0,0,1]
	v_pk_fma_f32 v[38:39], v[76:77], 0.5, v[112:113] op_sel_hi:[1,0,1]
	v_pk_add_f32 v[54:55], v[104:105], v[44:45]
	v_mov_b32_e32 v41, v39
	v_pk_mul_f32 v[130:131], v[40:41], s[46:47] op_sel_hi:[1,0]
	v_mul_f32_e32 v40, 0xbf54db31, v83
	v_mov_b32_e32 v41, v44
	v_pk_mov_b32 v[44:45], v[46:47], v[104:105] op_sel:[1,0]
	v_mul_f32_e32 v18, 0.5, v55
	v_pk_add_f32 v[40:41], v[40:41], v[44:45] neg_lo:[0,1] neg_hi:[0,1]
	v_mov_b32_e32 v105, v108
	v_pk_mul_f32 v[44:45], v[40:41], v[18:19]
	v_mov_b32_e32 v104, v40
	v_pk_fma_f32 v[56:57], v[56:57], v[44:45], v[44:45] op_sel:[0,1,0] op_sel_hi:[1,0,1]
	v_mov_b32_e32 v44, v45
	v_mov_b32_e32 v45, v18
	v_mul_f32_e32 v4, 0.5, v54
	v_pk_mul_f32 v[44:45], v[104:105], v[44:45]
	v_cvt_f32_f16_e32 v104, v26
	v_cvt_f32_f16_e32 v105, v27
	v_cvt_f32_f16_sdwa v27, v27 dst_sel:DWORD dst_unused:UNUSED_PAD src0_sel:WORD_1
	v_cvt_f32_f16_sdwa v26, v26 dst_sel:DWORD dst_unused:UNUSED_PAD src0_sel:WORD_1
	v_mul_f32_e32 v6, 0.5, v6
	v_pk_add_f32 v[110:111], v[4:5], v[56:57]
	v_pk_add_f32 v[44:45], v[44:45], v[44:45] op_sel:[0,1] op_sel_hi:[0,1] neg_lo:[0,1] neg_hi:[0,1]
	v_fma_f32 v111, v54, 0.5, -v56
	v_pk_add_f32 v[54:55], v[6:7], v[44:45] op_sel_hi:[0,1] neg_hi:[0,1]
	v_pk_mul_f32 v[44:45], v[54:55], v[26:27]
	v_pk_mul_f32 v[54:55], v[54:55], v[104:105]
	v_pk_fma_f32 v[56:57], v[110:111], v[104:105], v[44:45] neg_lo:[0,0,1] neg_hi:[0,0,1]
	v_pk_fma_f32 v[44:45], v[110:111], v[104:105], v[44:45]
	v_pk_fma_f32 v[104:105], v[110:111], v[26:27], v[54:55]
	v_pk_fma_f32 v[26:27], v[110:111], v[26:27], v[54:55] neg_lo:[0,0,1] neg_hi:[0,0,1]
	v_pk_add_f32 v[54:55], v[56:57], v[44:45] op_sel:[0,1] op_sel_hi:[1,0]
	v_pk_add_f32 v[110:111], v[104:105], v[26:27] op_sel_hi:[0,1] neg_lo:[0,1] neg_hi:[0,1]
	v_pk_add_f32 v[44:45], v[56:57], v[44:45] op_sel_hi:[0,1] neg_lo:[0,1] neg_hi:[0,1]
	v_pk_add_f32 v[26:27], v[104:105], v[26:27] op_sel:[0,1] op_sel_hi:[1,0]
	v_mov_b32_e32 v55, v111
	v_mov_b32_e32 v27, v45
	v_pk_mul_f32 v[26:27], v[26:27], 0.5 op_sel_hi:[1,0]
	v_mov_b32_e32 v47, v102
	v_pk_mul_f32 v[44:45], v[108:109], v[26:27] op_sel:[0,1] op_sel_hi:[0,0]
	v_pk_fma_f32 v[56:57], v[40:41], v[26:27], v[44:45] op_sel_hi:[0,1,1]
	v_pk_fma_f32 v[40:41], v[40:41], v[26:27], v[44:45] op_sel_hi:[0,1,1] neg_hi:[0,0,1]
	v_pk_fma_f32 v[44:45], v[54:55], 0.5, v[56:57] op_sel_hi:[1,0,1] neg_lo:[0,0,1] neg_hi:[0,0,1]
	v_pk_fma_f32 v[26:27], v[54:55], 0.5, v[40:41] op_sel_hi:[1,0,1]
	v_pk_fma_f32 v[56:57], v[54:55], 0.5, v[40:41] op_sel_hi:[1,0,1] neg_lo:[1,0,0] neg_hi:[1,0,0]
	v_pk_add_f32 v[40:41], v[106:107], v[42:43]
	v_pk_add_f32 v[42:43], v[42:43], v[106:107] neg_lo:[0,1] neg_hi:[0,1]
	v_mov_b32_e32 v45, v27
	v_mul_f32_e32 v6, 0.5, v43
	v_mov_b32_e32 v43, v41
	v_pk_mul_f32 v[120:121], v[44:45], s[46:47] op_sel_hi:[1,0]
	v_mul_f32_e32 v4, 0.5, v40
	v_pk_mov_b32 v[44:45], v[108:109], v[70:71] op_sel:[1,0]
	v_pk_mul_f32 v[40:41], v[42:43], s[44:45]
	v_cvt_f32_f16_sdwa v54, v20 dst_sel:DWORD dst_unused:UNUSED_PAD src0_sel:WORD_1
	v_pk_mul_f32 v[42:43], v[44:45], v[40:41] op_sel:[0,1] op_sel_hi:[1,0]
	v_cvt_f32_f16_e32 v55, v21
	v_cvt_f32_f16_sdwa v21, v21 dst_sel:DWORD dst_unused:UNUSED_PAD src0_sel:WORD_1
	v_cvt_f32_f16_e32 v20, v20
	v_pk_mul_f32 v[40:41], v[44:45], v[40:41]
	v_pk_add_f32 v[42:43], v[42:43], v[42:43] op_sel:[0,1] op_sel_hi:[0,1]
	v_pk_add_f32 v[104:105], v[4:5], v[42:43] op_sel_hi:[0,1] neg_hi:[0,1]
	s_nop 0
	v_pk_add_f32 v[40:41], v[40:41], v[40:41] op_sel:[0,1] op_sel_hi:[0,1] neg_lo:[0,1] neg_hi:[0,1]
	v_pk_add_f32 v[42:43], v[6:7], v[40:41] op_sel_hi:[0,1] neg_hi:[0,1]
	v_pk_mul_f32 v[40:41], v[42:43], v[20:21]
	v_pk_mul_f32 v[42:43], v[42:43], v[54:55]
	v_pk_fma_f32 v[40:41], v[104:105], v[54:55], v[40:41]
	v_pk_fma_f32 v[20:21], v[104:105], v[20:21], v[42:43] neg_lo:[0,0,1] neg_hi:[0,0,1]
	v_mov_b32_e32 v71, v109
	v_pk_add_f32 v[42:43], v[20:21], v[40:41] op_sel:[0,1] op_sel_hi:[1,0] neg_lo:[0,1]
	v_pk_add_f32 v[54:55], v[20:21], v[40:41] op_sel:[0,1] op_sel_hi:[1,0]
	v_pk_add_f32 v[20:21], v[40:41], v[20:21] op_sel:[1,0] op_sel_hi:[0,1] neg_lo:[0,1] neg_hi:[0,1]
	v_pk_mul_f32 v[42:43], v[42:43], 0.5 op_sel_hi:[1,0]
	v_mov_b32_e32 v55, v21
	v_mul_f32_e32 v4, v109, v42
	v_pk_fma_f32 v[104:105], v[44:45], v[42:43], v[4:5] op_sel_hi:[1,1,0] neg_lo:[1,0,0] neg_hi:[1,0,0]
	v_mul_f32_e32 v4, v109, v43
	v_pk_fma_f32 v[42:43], v[70:71], v[42:43], v[4:5] op_sel_hi:[1,1,0]
	v_sub_f32_e32 v6, v23, v103
	v_mov_b32_e32 v104, v42
	v_pk_fma_f32 v[40:41], v[54:55], 0.5, v[42:43] op_sel_hi:[1,0,1] neg_lo:[0,0,1] neg_hi:[0,0,1]
	v_pk_fma_f32 v[20:21], v[54:55], 0.5, v[104:105] op_sel_hi:[1,0,1]
	v_pk_add_f32 v[42:43], v[102:103], v[22:23]
	v_mov_b32_e32 v41, v21
	v_pk_mul_f32 v[128:129], v[40:41], s[46:47] op_sel_hi:[1,0]
	v_mul_f32_e32 v40, 0xbf0e39da, v83
	v_mov_b32_e32 v41, v22
	v_mul_f32_e32 v18, 0.5, v43
	v_pk_add_f32 v[22:23], v[40:41], v[46:47] neg_lo:[0,1] neg_hi:[0,1]
	v_mov_b32_e32 v47, v109
	v_pk_mul_f32 v[40:41], v[22:23], v[18:19]
	v_mov_b32_e32 v46, v22
	v_pk_fma_f32 v[44:45], v[44:45], v[40:41], v[40:41] op_sel:[0,1,0] op_sel_hi:[1,0,1]
	v_mov_b32_e32 v40, v41
	v_mov_b32_e32 v41, v18
	v_mul_f32_e32 v4, 0.5, v42
	v_pk_mul_f32 v[40:41], v[46:47], v[40:41]
	v_cvt_f32_f16_e32 v46, v10
	v_cvt_f32_f16_e32 v47, v11
	v_cvt_f32_f16_sdwa v11, v11 dst_sel:DWORD dst_unused:UNUSED_PAD src0_sel:WORD_1
	v_cvt_f32_f16_sdwa v10, v10 dst_sel:DWORD dst_unused:UNUSED_PAD src0_sel:WORD_1
	v_pk_fma_f32 v[70:71], v[54:55], 0.5, v[104:105] op_sel_hi:[1,0,1] neg_lo:[1,0,0] neg_hi:[1,0,0]
	v_mul_f32_e32 v6, 0.5, v6
	v_pk_add_f32 v[54:55], v[4:5], v[44:45]
	v_pk_add_f32 v[40:41], v[40:41], v[40:41] op_sel:[0,1] op_sel_hi:[0,1] neg_lo:[0,1] neg_hi:[0,1]
	v_fma_f32 v55, v42, 0.5, -v44
	v_pk_add_f32 v[42:43], v[6:7], v[40:41] op_sel_hi:[0,1] neg_hi:[0,1]
	v_pk_mul_f32 v[40:41], v[42:43], v[10:11]
	v_pk_mul_f32 v[42:43], v[42:43], v[46:47]
	v_pk_fma_f32 v[44:45], v[54:55], v[46:47], v[40:41] neg_lo:[0,0,1] neg_hi:[0,0,1]
	v_pk_fma_f32 v[40:41], v[54:55], v[46:47], v[40:41]
	v_pk_fma_f32 v[46:47], v[54:55], v[10:11], v[42:43]
	v_pk_fma_f32 v[10:11], v[54:55], v[10:11], v[42:43] neg_lo:[0,0,1] neg_hi:[0,0,1]
	v_pk_add_f32 v[42:43], v[44:45], v[40:41] op_sel:[0,1] op_sel_hi:[1,0]
	v_pk_add_f32 v[54:55], v[46:47], v[10:11] op_sel_hi:[0,1] neg_lo:[0,1] neg_hi:[0,1]
	v_pk_add_f32 v[40:41], v[44:45], v[40:41] op_sel_hi:[0,1] neg_lo:[0,1] neg_hi:[0,1]
	v_pk_add_f32 v[10:11], v[46:47], v[10:11] op_sel:[0,1] op_sel_hi:[1,0]
	v_mov_b32_e32 v43, v55
	v_mov_b32_e32 v11, v41
	v_pk_mul_f32 v[10:11], v[10:11], 0.5 op_sel_hi:[1,0]
	v_mov_b32_e32 v119, v98
	v_pk_mul_f32 v[40:41], v[108:109], v[10:11] op_sel:[1,1] op_sel_hi:[1,0]
	v_pk_fma_f32 v[76:77], v[76:77], 0.5, v[112:113] op_sel_hi:[1,0,1] neg_lo:[1,0,0] neg_hi:[1,0,0]
	v_pk_fma_f32 v[44:45], v[22:23], v[10:11], v[40:41] op_sel_hi:[0,1,1]
	v_pk_fma_f32 v[10:11], v[22:23], v[10:11], v[40:41] op_sel_hi:[0,1,1] neg_hi:[0,0,1]
	v_pk_fma_f32 v[22:23], v[42:43], 0.5, v[44:45] op_sel_hi:[1,0,1] neg_lo:[0,0,1] neg_hi:[0,0,1]
	v_pk_fma_f32 v[40:41], v[42:43], 0.5, v[10:11] op_sel_hi:[1,0,1]
	v_pk_fma_f32 v[54:55], v[42:43], 0.5, v[10:11] op_sel_hi:[1,0,1] neg_lo:[1,0,0] neg_hi:[1,0,0]
	v_pk_add_f32 v[10:11], v[100:101], v[14:15]
	v_pk_add_f32 v[14:15], v[14:15], v[100:101] neg_lo:[0,1] neg_hi:[0,1]
	v_mov_b32_e32 v23, v41
	v_mul_f32_e32 v6, 0.5, v15
	v_mov_b32_e32 v15, v11
	v_pk_mul_f32 v[150:151], v[22:23], s[46:47] op_sel_hi:[1,0]
	v_mul_f32_e32 v4, 0.5, v10
	v_pk_mov_b32 v[22:23], v[58:59], v[72:73] op_sel:[1,0]
	v_pk_mul_f32 v[10:11], v[14:15], s[44:45]
	v_cvt_f32_f16_sdwa v42, v8 dst_sel:DWORD dst_unused:UNUSED_PAD src0_sel:WORD_1
	v_pk_mul_f32 v[14:15], v[22:23], v[10:11] op_sel:[0,1] op_sel_hi:[1,0]
	v_cvt_f32_f16_e32 v43, v9
	v_cvt_f32_f16_sdwa v9, v9 dst_sel:DWORD dst_unused:UNUSED_PAD src0_sel:WORD_1
	v_cvt_f32_f16_e32 v8, v8
	v_pk_mul_f32 v[10:11], v[22:23], v[10:11]
	v_pk_add_f32 v[14:15], v[14:15], v[14:15] op_sel:[0,1] op_sel_hi:[0,1]
	v_pk_add_f32 v[44:45], v[4:5], v[14:15] op_sel_hi:[0,1] neg_hi:[0,1]
	s_nop 0
	v_pk_add_f32 v[10:11], v[10:11], v[10:11] op_sel:[0,1] op_sel_hi:[0,1] neg_lo:[0,1] neg_hi:[0,1]
	v_pk_add_f32 v[14:15], v[6:7], v[10:11] op_sel_hi:[0,1] neg_hi:[0,1]
	v_pk_mul_f32 v[10:11], v[14:15], v[8:9]
	v_pk_mul_f32 v[14:15], v[14:15], v[42:43]
	v_pk_fma_f32 v[10:11], v[44:45], v[42:43], v[10:11]
	v_pk_fma_f32 v[8:9], v[44:45], v[8:9], v[14:15] neg_lo:[0,0,1] neg_hi:[0,0,1]
	v_mov_b32_e32 v73, v59
	v_pk_add_f32 v[14:15], v[8:9], v[10:11] op_sel:[0,1] op_sel_hi:[1,0] neg_lo:[0,1]
	v_pk_add_f32 v[42:43], v[8:9], v[10:11] op_sel:[0,1] op_sel_hi:[1,0]
	v_pk_add_f32 v[8:9], v[10:11], v[8:9] op_sel:[1,0] op_sel_hi:[0,1] neg_lo:[0,1] neg_hi:[0,1]
	v_pk_mul_f32 v[14:15], v[14:15], 0.5 op_sel_hi:[1,0]
	v_mov_b32_e32 v43, v9
	v_mul_f32_e32 v4, v59, v14
	v_pk_fma_f32 v[44:45], v[22:23], v[14:15], v[4:5] op_sel_hi:[1,1,0] neg_lo:[1,0,0] neg_hi:[1,0,0]
	v_mul_f32_e32 v4, v59, v15
	v_pk_fma_f32 v[14:15], v[72:73], v[14:15], v[4:5] op_sel_hi:[1,1,0]
	v_sub_f32_e32 v6, v37, v99
	v_mov_b32_e32 v44, v14
	v_pk_fma_f32 v[8:9], v[42:43], 0.5, v[14:15] op_sel_hi:[1,0,1] neg_lo:[0,0,1] neg_hi:[0,0,1]
	v_pk_fma_f32 v[10:11], v[42:43], 0.5, v[44:45] op_sel_hi:[1,0,1]
	v_pk_add_f32 v[14:15], v[98:99], v[36:37]
	v_mov_b32_e32 v9, v11
	v_pk_mul_f32 v[168:169], v[8:9], s[46:47] op_sel_hi:[1,0]
	v_mul_f32_e32 v8, 0xbf7b14be, v83
	v_mov_b32_e32 v9, v36
	v_mul_f32_e32 v18, 0.5, v15
	v_pk_add_f32 v[8:9], v[8:9], v[118:119] neg_lo:[0,1] neg_hi:[0,1]
	v_pk_fma_f32 v[72:73], v[42:43], 0.5, v[44:45] op_sel_hi:[1,0,1] neg_lo:[1,0,0] neg_hi:[1,0,0]
	v_pk_mul_f32 v[36:37], v[8:9], v[18:19]
	v_mov_b32_e32 v42, v8
	v_pk_fma_f32 v[22:23], v[22:23], v[36:37], v[36:37] op_sel:[0,1,0] op_sel_hi:[1,0,1]
	v_mov_b32_e32 v43, v59
	v_mov_b32_e32 v36, v37
	v_mov_b32_e32 v37, v18
	v_mul_f32_e32 v4, 0.5, v14
	v_pk_mul_f32 v[36:37], v[42:43], v[36:37]
	v_cvt_f32_f16_e32 v44, v2
	v_cvt_f32_f16_e32 v45, v3
	v_cvt_f32_f16_sdwa v3, v3 dst_sel:DWORD dst_unused:UNUSED_PAD src0_sel:WORD_1
	v_cvt_f32_f16_sdwa v2, v2 dst_sel:DWORD dst_unused:UNUSED_PAD src0_sel:WORD_1
	v_mul_f32_e32 v6, 0.5, v6
	v_pk_add_f32 v[46:47], v[4:5], v[22:23]
	v_fma_f32 v4, v14, 0.5, -v22
	v_pk_add_f32 v[22:23], v[36:37], v[36:37] op_sel:[0,1] op_sel_hi:[0,1] neg_lo:[0,1] neg_hi:[0,1]
	v_pk_add_f32 v[36:37], v[6:7], v[22:23] op_sel_hi:[0,1] neg_hi:[0,1]
	v_mov_b32_e32 v14, v46
	v_mov_b32_e32 v15, v4
	v_pk_mul_f32 v[22:23], v[4:5], v[44:45] op_sel_hi:[0,1]
	v_pk_mul_f32 v[82:83], v[36:37], v[2:3]
	v_pk_mul_f32 v[46:47], v[46:47], v[2:3]
	v_pk_mul_f32 v[36:37], v[36:37], v[44:45]
	v_pk_fma_f32 v[98:99], v[14:15], v[44:45], v[82:83] neg_lo:[0,0,1] neg_hi:[0,0,1]
	v_pk_fma_f32 v[2:3], v[14:15], v[2:3], v[36:37] neg_lo:[0,0,1] neg_hi:[0,0,1]
	v_add_f32_e32 v4, v23, v83
	v_add_f32_e32 v6, v46, v36
	v_pk_add_f32 v[22:23], v[6:7], v[2:3] op_sel_hi:[0,1] neg_lo:[0,1] neg_hi:[0,1]
	v_pk_add_f32 v[36:37], v[98:99], v[4:5] op_sel_hi:[1,0] neg_lo:[0,1] neg_hi:[0,1]
	v_pk_add_f32 v[2:3], v[6:7], v[2:3] op_sel_hi:[0,1]
	v_mov_b32_e32 v37, v3
	v_pk_mul_f32 v[2:3], v[36:37], 0.5 op_sel_hi:[1,0]
	v_pk_add_f32 v[14:15], v[98:99], v[4:5] op_sel_hi:[1,0]
	v_mul_f32_e32 v4, v59, v3
	v_pk_fma_f32 v[36:37], v[42:43], v[2:3], v[4:5] op_sel_hi:[1,1,0] neg_lo:[0,0,1] neg_hi:[0,0,1]
	v_pk_mov_b32 v[42:43], v[58:59], v[8:9] op_sel:[1,0]
	v_mul_f32_e32 v4, v8, v3
	v_pk_fma_f32 v[2:3], v[42:43], v[2:3], v[4:5] op_sel_hi:[1,1,0]
	v_mov_b32_e32 v15, v23
	v_pk_fma_f32 v[8:9], v[14:15], 0.5, v[2:3] op_sel_hi:[1,0,1] neg_lo:[0,0,1] neg_hi:[0,0,1]
	v_pk_fma_f32 v[42:43], v[14:15], 0.5, v[36:37] op_sel_hi:[1,0,0]
	v_pk_fma_f32 v[2:3], v[14:15], 0.5, v[2:3] op_sel_hi:[1,0,1]
	v_mov_b32_e32 v9, v43
	v_pk_fma_f32 v[58:59], v[22:23], 0.5, v[36:37] op_sel_hi:[1,0,0] neg_lo:[1,0,0] neg_hi:[1,0,0]
	v_pk_mul_f32 v[144:145], v[8:9], s[46:47] op_sel_hi:[1,0]
	v_mov_b32_e32 v58, v2
	v_mov_b32_e32 v72, v10
	v_mov_b32_e32 v54, v40
	v_mov_b32_e32 v70, v20
	v_mov_b32_e32 v56, v26
	v_mov_b32_e32 v76, v38
	v_mov_b32_e32 v52, v34
	v_mov_b32_e32 v74, v86
	v_mov_b32_e32 v48, v84
	v_mov_b32_e32 v50, v60
	v_mov_b32_e32 v28, v66
	v_mov_b32_e32 v32, v96
	v_mov_b32_e32 v12, v88
	v_mov_b32_e32 v16, v92
	v_mov_b32_e32 v4, v138
	v_mov_b32_e32 v6, v122
